# pipelined gemm<4,8>: per-write vmcnt(7) waits instead of one vmcnt(0) per K tile
# baseline (speedup 1.0000x reference)
; DI int lbid() { int b = blockIdx.x; asm volatile("" : "+s"(b)); return b; }
; DI int lgdim() { int b = gridDim.x; asm volatile("" : "+s"(b)); return b; }
; DI int ltid() { int t = threadIdx.x; asm volatile("" : "+v"(t)); return t; }
; #define GLOAD(kt) { GL1(0, kt) GL1(1, kt) GL1(2, kt) GL1(3, kt) }
; #define SSTORE(buf)                              \
;   {                                              \
;     char* as_ = smem + (buf) * BUF;              \
;     char* bs_ = as_ + ASZ;                       \
;     SS1(0) SS1(1) SS1(2) SS1(3)                  \
;   }
; template <int MT, int NT>
; DI void gemm_core(const u16* __restrict__ A, int lda, const u16* __restrict__ B, int ldb, int K,
;                   f32x4 (&acc)[MT][NT], char* smem) {
;     ...
;   const int tid = ltid(), l = tid & 63, w = tid >> 6, wm = w >> 1, wn = w & 1;
;   const int fr = l & 15, fq = l >> 4;
;   uint4 ra0, ra1, ra2, ra3, rb0, rb1, rb2, rb3;
;   const int nk = K >> 6;
;   const int srow = tid >> 3, sch = tid & 7;
;   const int ssw = sch ^ ((srow >> 1) & 7);
;   const int fsw = (fr >> 1) & 7;
;     ...
;   GLOAD(0);
;   SSTORE(0);
;   GLOAD(((1 < nk) ? 1 : 0));
; DI bool next_tile(int it, int RT, int CT, int PR, int PCc, int& rt, int& ct) {
;   const int bid = lbid(), x = bid & 7, j = bid >> 3, J = lgdim() >> 3;
;   const int u = j + it * J;
;   const int pcols = CT / PCc, npatch = (RT / PR) * pcols;
;   const int pid = (u >> 6) * 8 + x;
;   if (pid >= npatch) return false;
;   const int w = u & 63, pr = pid / pcols, pc = pid - pr * pcols;
;   rt = pr * PR + w / PCc;
;   ct = pc * PCc + w % PCc;
;   return true;
.LBB0_129:
	s_mov_b32 s0, s56
	s_load_dword s1, s[36:37], 0x0
	s_waitcnt lgkmcnt(0)
	s_ashr_i32 s1, s1, 3
	s_and_b32 s3, s0, 7
	s_ashr_i32 s0, s0, 3
	s_mul_i32 s2, s1, s18
	s_add_i32 s2, s2, s0
	s_ashr_i32 s0, s2, 3
	s_and_b32 s0, s0, -8
	s_or_b32 s3, s0, s3
	s_cmp_gt_i32 s3, 31
	s_mov_b64 s[0:1], -1
	s_cbranch_scc1 .LBB0_128
	s_lshr_b32 s0, s3, 31
	s_add_i32 s0, s3, s0
	s_ashr_i32 s0, s0, 1
	s_lshl_b32 s1, s0, 4
	s_lshl_b32 s3, s3, 3
	s_sub_i32 s1, s3, s1
	s_and_b32 s3, s2, 7
	s_lshl_b32 s2, s2, 5
	s_lshl_b32 s0, s0, 11
	s_and_b32 s2, s2, 0x700
	s_or_b32 s1, s1, s3
	s_or_b32 s0, s0, s2
	s_lshl_b32 s19, s1, 8
	s_mul_i32 s2, s0, 0x880
	s_mul_hi_i32 s3, s0, 0x880
	s_add_u32 s2, s60, s2
	s_addc_u32 s3, s61, s3
	s_mul_i32 s1, s1, 0x88000
	s_mul_hi_i32 s5, s19, 0x880
	s_add_u32 s4, s52, s1
	v_mov_b32_e32 v34, v171
	s_addc_u32 s5, s33, s5
	v_mov_b64_e32 v[26:27], s[2:3]
	v_ashrrev_i32_e32 v35, 3, v34
	v_lshlrev_b32_e32 v36, 4, v34
	v_mov_b64_e32 v[30:31], s[4:5]
	v_add_u32_e32 v37, 64, v35
	v_add_u32_e32 v38, 0x80, v35
	v_add_u32_e32 v39, 0xc0, v35
	v_mad_i64_i32 v[2:3], s[2:3], v35, s59, v[26:27]
	v_and_b32_e32 v0, 0x70, v36
	v_mad_i64_i32 v[6:7], s[2:3], v35, s59, v[30:31]
	v_mad_i64_i32 v[10:11], s[2:3], v37, s59, v[26:27]
	v_mad_i64_i32 v[14:15], s[2:3], v37, s59, v[30:31]
	v_mad_i64_i32 v[18:19], s[2:3], v38, s59, v[26:27]
	v_mad_i64_i32 v[22:23], s[2:3], v38, s59, v[30:31]
	v_mad_i64_i32 v[26:27], s[2:3], v39, s59, v[26:27]
	v_mad_i64_i32 v[30:31], s[2:3], v39, s59, v[30:31]
	s_waitcnt vmcnt(16)
	v_lshl_add_u64 v[162:163], v[2:3], 0, v[0:1]
	v_lshl_add_u64 v[164:165], v[6:7], 0, v[0:1]
	v_lshl_add_u64 v[166:167], v[10:11], 0, v[0:1]
	v_lshl_add_u64 v[168:169], v[14:15], 0, v[0:1]
	v_lshl_add_u64 v[176:177], v[18:19], 0, v[0:1]
	v_lshl_add_u64 v[178:179], v[22:23], 0, v[0:1]
	v_lshl_add_u64 v[180:181], v[26:27], 0, v[0:1]
	s_waitcnt vmcnt(0)
	v_lshl_add_u64 v[182:183], v[30:31], 0, v[0:1]
	global_load_dwordx4 v[2:5], v[162:163], off
	global_load_dwordx4 v[6:9], v[164:165], off
	global_load_dwordx4 v[10:13], v[166:167], off
	global_load_dwordx4 v[14:17], v[168:169], off
	global_load_dwordx4 v[18:21], v[176:177], off
	global_load_dwordx4 v[22:25], v[178:179], off
	global_load_dwordx4 v[26:29], v[180:181], off
	global_load_dwordx4 v[30:33], v[182:183], off
	global_load_dwordx4 v[134:137], v[180:181], off offset:128
	global_load_dwordx4 v[126:129], v[176:177], off offset:128
	global_load_dwordx4 v[114:117], v[166:167], off offset:128
	global_load_dwordx4 v[110:113], v[162:163], off offset:128
	global_load_dwordx4 v[150:153], v[182:183], off offset:128
	global_load_dwordx4 v[138:141], v[178:179], off offset:128
	global_load_dwordx4 v[130:133], v[168:169], off offset:128
	global_load_dwordx4 v[118:121], v[164:165], off offset:128
	v_lshlrev_b32_e32 v0, 7, v35
	v_bitop3_b32 v173, v36, s75, v34 bitop3:0x48
	v_and_b32_e32 v44, 15, v34
	v_lshlrev_b32_e32 v45, 1, v34
	v_or_b32_e32 v35, v0, v173
	v_lshlrev_b32_e32 v175, 7, v37
	v_lshlrev_b32_e32 v184, 7, v38
	v_lshlrev_b32_e32 v185, 7, v39
	v_bfe_u32 v41, v34, 4, 2
	v_bfe_u32 v43, v34, 1, 3
	v_or_b32_e32 v36, v175, v173
	v_or_b32_e32 v37, v184, v173
	v_or_b32_e32 v38, v185, v173
	v_lshrrev_b32_e32 v40, 4, v34
	v_lshrrev_b32_e32 v42, 1, v34
	v_and_or_b32 v34, v42, s90, v44
	v_lshlrev_b32_e32 v187, 7, v34
	s_mov_b32 s1, 0
	s_mov_b32 s2, 0
	s_waitcnt vmcnt(15)
	ds_write_b128 v35, v[2:5]
	s_waitcnt vmcnt(13)
	ds_write_b128 v36, v[10:13]
	s_waitcnt vmcnt(11)
	ds_write_b128 v37, v[18:21]
	s_waitcnt vmcnt(9)
	ds_write_b128 v38, v[26:29]
	ds_write_b128 v35, v[6:9] offset:32768
	ds_write_b128 v36, v[14:17] offset:32768
	ds_write_b128 v37, v[22:25] offset:32768
	s_waitcnt vmcnt(8)
	ds_write_b128 v38, v[30:33] offset:32768
	v_and_or_b32 v2, v45, s57, v44
	v_lshlrev_b32_e32 v188, 7, v2
	v_bitop3_b32 v2, v41, v43, 4 bitop3:0x36
	v_bitop3_b32 v3, v40, v43, 3 bitop3:0x6c
	v_lshlrev_b32_e32 v189, 4, v2
	v_mov_b32_e32 v2, 0
	v_lshlrev_b32_e32 v186, 4, v3
	v_mov_b32_e32 v3, v2
	v_mov_b32_e32 v4, v2
	v_mov_b32_e32 v5, v2
	v_mov_b32_e32 v6, v2
	v_mov_b32_e32 v7, v2
	v_mov_b32_e32 v8, v2
	v_mov_b32_e32 v9, v2
	v_mov_b32_e32 v10, v2
	v_mov_b32_e32 v11, v2
	v_mov_b32_e32 v12, v2
	v_mov_b32_e32 v13, v2
	v_mov_b32_e32 v14, v2
	v_mov_b32_e32 v15, v2
	v_mov_b32_e32 v16, v2
	v_mov_b32_e32 v17, v2
	v_mov_b32_e32 v18, v2
	v_mov_b32_e32 v19, v2
	v_mov_b32_e32 v20, v2
	v_mov_b32_e32 v21, v2
	v_mov_b32_e32 v22, v2
	v_mov_b32_e32 v23, v2
	v_mov_b32_e32 v24, v2
	v_mov_b32_e32 v25, v2
	v_mov_b32_e32 v26, v2
	v_mov_b32_e32 v27, v2
	v_mov_b32_e32 v28, v2
	v_mov_b32_e32 v29, v2
	v_mov_b32_e32 v30, v2
	v_mov_b32_e32 v31, v2
	v_mov_b32_e32 v32, v2
	v_mov_b32_e32 v33, v2
	v_mov_b32_e32 v34, v2
	v_mov_b32_e32 v35, v2
	v_mov_b32_e32 v36, v2
	v_mov_b32_e32 v37, v2
	v_mov_b32_e32 v38, v2
	v_mov_b32_e32 v39, v2
	v_mov_b32_e32 v40, v2
	v_mov_b32_e32 v41, v2
	v_mov_b32_e32 v42, v2
	v_mov_b32_e32 v43, v2
	v_mov_b32_e32 v44, v2
	v_mov_b32_e32 v45, v2
	v_mov_b32_e32 v46, v2
	v_mov_b32_e32 v47, v2
	v_mov_b32_e32 v48, v2
	v_mov_b32_e32 v49, v2
	v_mov_b32_e32 v50, v2
	v_mov_b32_e32 v51, v2
	v_mov_b32_e32 v52, v2
	v_mov_b32_e32 v53, v2
	v_mov_b32_e32 v54, v2
	v_mov_b32_e32 v55, v2
	v_mov_b32_e32 v56, v2
	v_mov_b32_e32 v57, v2
	v_mov_b32_e32 v58, v2
	v_mov_b32_e32 v59, v2
	v_mov_b32_e32 v60, v2
	v_mov_b32_e32 v61, v2
	v_mov_b32_e32 v62, v2
	v_mov_b32_e32 v63, v2
	v_mov_b32_e32 v64, v2
	v_mov_b32_e32 v65, v2
	v_mov_b32_e32 v66, v2
	v_mov_b32_e32 v67, v2
	v_mov_b32_e32 v68, v2
	v_mov_b32_e32 v69, v2
	v_mov_b32_e32 v70, v2
	v_mov_b32_e32 v71, v2
	v_mov_b32_e32 v72, v2
	v_mov_b32_e32 v73, v2
	v_mov_b32_e32 v74, v2
	v_mov_b32_e32 v75, v2
	v_mov_b32_e32 v76, v2
	v_mov_b32_e32 v77, v2
	v_mov_b32_e32 v78, v2
	v_mov_b32_e32 v79, v2
	v_mov_b32_e32 v80, v2
	v_mov_b32_e32 v81, v2
	v_mov_b32_e32 v82, v2
	v_mov_b32_e32 v83, v2
	v_mov_b32_e32 v84, v2
	v_mov_b32_e32 v85, v2
	v_mov_b32_e32 v86, v2
	v_mov_b32_e32 v87, v2
	v_mov_b32_e32 v88, v2
	v_mov_b32_e32 v89, v2
	v_mov_b32_e32 v90, v2
	v_mov_b32_e32 v91, v2
	v_mov_b32_e32 v92, v2
	v_mov_b32_e32 v93, v2
	v_mov_b32_e32 v94, v2
	v_mov_b32_e32 v95, v2
	v_mov_b32_e32 v96, v2
	v_mov_b32_e32 v97, v2
	v_mov_b32_e32 v98, v2
	v_mov_b32_e32 v99, v2
	v_mov_b32_e32 v100, v2
	v_mov_b32_e32 v101, v2
	v_mov_b32_e32 v102, v2
	v_mov_b32_e32 v103, v2
	v_mov_b32_e32 v104, v2
	v_mov_b32_e32 v105, v2
	v_mov_b32_e32 v106, v2
	v_mov_b32_e32 v107, v2
	v_mov_b32_e32 v108, v2
	v_mov_b32_e32 v109, v2
	v_mov_b32_e32 v122, v2
	v_mov_b32_e32 v123, v2
	v_mov_b32_e32 v124, v2
	v_mov_b32_e32 v125, v2
	v_mov_b32_e32 v142, v2
	v_mov_b32_e32 v143, v2
	v_mov_b32_e32 v144, v2
	v_mov_b32_e32 v145, v2
	v_mov_b32_e32 v146, v2
	v_mov_b32_e32 v147, v2
	v_mov_b32_e32 v148, v2
	v_mov_b32_e32 v149, v2
	v_mov_b32_e32 v154, v2
	v_mov_b32_e32 v155, v2
	v_mov_b32_e32 v156, v2
	v_mov_b32_e32 v157, v2
	v_mov_b32_e32 v158, v2
	v_mov_b32_e32 v159, v2
	v_mov_b32_e32 v160, v2
	v_mov_b32_e32 v161, v2
	s_waitcnt vmcnt(0) lgkmcnt(0)
	s_barrier
; DI f32x4 mfma16(bf16x8 a, bf16x8 b, f32x4 c) { return __builtin_amdgcn_mfma_f32_16x16x32_bf16(a, b, c, 0, 0, 0); }
; #define GLOAD(kt) { GL1(0, kt) GL1(1, kt) GL1(2, kt) GL1(3, kt) }
; #define SSTORE(buf)                              \
;   {                                              \
;     char* as_ = smem + (buf) * BUF;              \
;     char* bs_ = as_ + ASZ;                       \
;     SS1(0) SS1(1) SS1(2) SS1(3)                  \
;   }
; template <int MT, int NT>
; DI void gemm_core(const u16* __restrict__ A, int lda, const u16* __restrict__ B, int ldb, int K,
;                   f32x4 (&acc)[MT][NT], char* smem) {
;     ...
;   for (int kt = 0; kt < nk; ++kt) {
;     __syncthreads();
;     SSTORE((kt + 1) & 1);
;     { const int kn_ = (kt + 2 < nk) ? kt + 2 : nk - 1; GLOAD(kn_); }
;     const char* as = smem + (kt & 1) * BUF;
;     const char* bs = as + ASZ;
; #pragma unroll
;     for (int kk = 0; kk < 2; ++kk) {
;       bf16x8 xf[MT], wf[NT];
; #pragma unroll
;       for (int mi = 0; mi < MT; ++mi)
;         xf[mi] = *(const bf16x8*)(as + (wm * (MT * 16) + mi * 16 + fr) * 128 + (((kk * 4 + fq) ^ fsw) * 16));
; #pragma unroll
;       for (int ni = 0; ni < NT; ++ni)
;         wf[ni] = *(const bf16x8*)(bs + (wn * (NT * 16) + ni * 16 + fr) * 128 + (((kk * 4 + fq) ^ fsw) * 16));
;       __builtin_amdgcn_s_setprio(1);
; #pragma unroll
;       for (int mi = 0; mi < MT; ++mi)
; #pragma unroll
;         for (int ni = 0; ni < NT; ++ni) acc[mi][ni] = mfma16(wf[ni], xf[mi], acc[mi][ni]);
;       __builtin_amdgcn_s_setprio(0);
;     }
	v_add_u32_e32 v207, v186, v188
	v_add_u32_e32 v206, v186, v187
	ds_read_b128 v[190:193], v206
	ds_read_b128 v[208:211], v206 offset:2048
	ds_read_b128 v[212:215], v206 offset:4096
	ds_read_b128 v[216:219], v206 offset:6144
	ds_read_b128 v[220:223], v207 offset:32768
	ds_read_b128 v[224:227], v207 offset:34816
	ds_read_b128 v[228:231], v207 offset:36864
	ds_read_b128 v[232:235], v207 offset:38912
	ds_read_b128 v[236:239], v207 offset:40960
	ds_read_b128 v[240:243], v207 offset:43008
	ds_read_b128 v[244:247], v207 offset:45056
	ds_read_b128 v[248:251], v207 offset:47104
	s_waitcnt lgkmcnt(0)
.LBB0_131:
	s_add_i32 s4, s1, 0x10000
	s_and_b32 s5, s4, 0x10000
	s_add_i32 s3, s2, 1
	s_min_u32 s2, s2, 13
	s_lshl_b32 s54, s2, 7
	s_and_b32 s1, s1, 0x10000
	v_or_b32_e32 v206, s1, v189
	v_add_u32_e32 v207, v206, v188
	v_add_u32_e32 v206, v206, v187
	v_add3_u32 v170, s5, v0, v173
	s_waitcnt lgkmcnt(10)
	v_mfma_f32_16x16x32_bf16 v[158:161], v[220:223], v[190:193], v[158:161]
	s_waitcnt vmcnt(7)
	ds_write_b128 v170, v[110:113]
	s_waitcnt lgkmcnt(10)
	v_mfma_f32_16x16x32_bf16 v[94:97], v[220:223], v[208:211], v[94:97]
	v_lshl_add_u64 v[110:111], v[162:163], 0, s[54:55]
	global_load_dwordx4 v[110:113], v[110:111], off offset:256
	s_waitcnt lgkmcnt(8)
	v_mfma_f32_16x16x32_bf16 v[62:65], v[220:223], v[212:215], v[62:65]
	s_waitcnt vmcnt(7)
	ds_write_b128 v170, v[118:121] offset:32768
	s_waitcnt lgkmcnt(3)
	v_mfma_f32_16x16x32_bf16 v[30:33], v[220:223], v[216:219], v[30:33]
	v_lshl_add_u64 v[118:119], v[164:165], 0, s[54:55]
	global_load_dwordx4 v[118:121], v[118:119], off offset:256
	ds_read_b128 v[194:197], v206
	v_mfma_f32_16x16x32_bf16 v[154:157], v[224:227], v[190:193], v[154:157]
	ds_read_b128 v[220:223], v207 offset:32768
	s_waitcnt vmcnt(7)
	ds_write_b128 v170, v[114:117] offset:8192
	v_mfma_f32_16x16x32_bf16 v[90:93], v[224:227], v[208:211], v[90:93]
	v_lshl_add_u64 v[114:115], v[166:167], 0, s[54:55]
	global_load_dwordx4 v[114:117], v[114:115], off offset:256
	v_mfma_f32_16x16x32_bf16 v[58:61], v[224:227], v[212:215], v[58:61]
	v_mfma_f32_16x16x32_bf16 v[26:29], v[224:227], v[216:219], v[26:29]
	ds_read_b128 v[198:201], v206 offset:2048
	v_mfma_f32_16x16x32_bf16 v[146:149], v[228:231], v[190:193], v[146:149]
	ds_read_b128 v[224:227], v207 offset:34816
	s_waitcnt vmcnt(7)
	ds_write_b128 v170, v[130:133] offset:40960
	v_mfma_f32_16x16x32_bf16 v[86:89], v[228:231], v[208:211], v[86:89]
	v_lshl_add_u64 v[130:131], v[168:169], 0, s[54:55]
	global_load_dwordx4 v[130:133], v[130:131], off offset:256
	v_mfma_f32_16x16x32_bf16 v[54:57], v[228:231], v[212:215], v[54:57]
	v_mfma_f32_16x16x32_bf16 v[22:25], v[228:231], v[216:219], v[22:25]
	ds_read_b128 v[202:205], v206 offset:4096
	v_mfma_f32_16x16x32_bf16 v[142:145], v[232:235], v[190:193], v[142:145]
	ds_read_b128 v[228:231], v207 offset:36864
	s_waitcnt vmcnt(7)
	ds_write_b128 v170, v[126:129] offset:16384
	v_mfma_f32_16x16x32_bf16 v[82:85], v[232:235], v[208:211], v[82:85]
	v_lshl_add_u64 v[126:127], v[176:177], 0, s[54:55]
	global_load_dwordx4 v[126:129], v[126:127], off offset:256
	v_mfma_f32_16x16x32_bf16 v[50:53], v[232:235], v[212:215], v[50:53]
	v_mfma_f32_16x16x32_bf16 v[18:21], v[232:235], v[216:219], v[18:21]
	v_mfma_f32_16x16x32_bf16 v[122:125], v[236:239], v[190:193], v[122:125]
	ds_read_b128 v[232:235], v207 offset:38912
	s_waitcnt vmcnt(7)
	ds_write_b128 v170, v[138:141] offset:49152
	v_mfma_f32_16x16x32_bf16 v[78:81], v[236:239], v[208:211], v[78:81]
	v_lshl_add_u64 v[138:139], v[178:179], 0, s[54:55]
	global_load_dwordx4 v[138:141], v[138:139], off offset:256
	v_mfma_f32_16x16x32_bf16 v[46:49], v[236:239], v[212:215], v[46:49]
	v_mfma_f32_16x16x32_bf16 v[14:17], v[236:239], v[216:219], v[14:17]
	v_mfma_f32_16x16x32_bf16 v[106:109], v[240:243], v[190:193], v[106:109]
	ds_read_b128 v[236:239], v207 offset:40960
	s_waitcnt vmcnt(7)
	ds_write_b128 v170, v[134:137] offset:24576
	v_mfma_f32_16x16x32_bf16 v[74:77], v[240:243], v[208:211], v[74:77]
	v_lshl_add_u64 v[134:135], v[180:181], 0, s[54:55]
	global_load_dwordx4 v[134:137], v[134:135], off offset:256
	v_mfma_f32_16x16x32_bf16 v[42:45], v[240:243], v[212:215], v[42:45]
	v_mfma_f32_16x16x32_bf16 v[10:13], v[240:243], v[216:219], v[10:13]
	v_mfma_f32_16x16x32_bf16 v[102:105], v[244:247], v[190:193], v[102:105]
	ds_read_b128 v[240:243], v207 offset:43008
	s_waitcnt vmcnt(7)
	ds_write_b128 v170, v[150:153] offset:57344
	v_mfma_f32_16x16x32_bf16 v[70:73], v[244:247], v[208:211], v[70:73]
	v_lshl_add_u64 v[150:151], v[182:183], 0, s[54:55]
	global_load_dwordx4 v[150:153], v[150:151], off offset:256
	v_mfma_f32_16x16x32_bf16 v[38:41], v[244:247], v[212:215], v[38:41]
	v_mfma_f32_16x16x32_bf16 v[6:9], v[244:247], v[216:219], v[6:9]
	s_waitcnt lgkmcnt(15)
	v_mfma_f32_16x16x32_bf16 v[2:5], v[248:251], v[216:219], v[2:5]
	ds_read_b128 v[244:247], v207 offset:45056
	ds_read_b128 v[216:219], v206 offset:6144
	v_mfma_f32_16x16x32_bf16 v[98:101], v[248:251], v[190:193], v[98:101]
	v_mfma_f32_16x16x32_bf16 v[66:69], v[248:251], v[208:211], v[66:69]
	v_mfma_f32_16x16x32_bf16 v[34:37], v[248:251], v[212:215], v[34:37]
	ds_read_b128 v[248:251], v207 offset:47104
	s_waitcnt lgkmcnt(3)
	s_barrier
;   __device__ __forceinline__ u16* P() const { return (u16*)(ws + O_P); }
; DI f32x4 mfma16(bf16x8 a, bf16x8 b, f32x4 c) { return __builtin_amdgcn_mfma_f32_16x16x32_bf16(a, b, c, 0, 0, 0); }
; #define EPI_LOOP(MT_, NT_)                                                \
;   const int l_ = ltid() & 63, w_ = ltid() >> 6;                           \
;   const int wm_ = w_ >> 1, wn_ = w_ & 1, fr_ = l_ & 15, fq_ = l_ >> 4;    \
;   _Pragma("unroll") for (int mi = 0; mi < MT_; ++mi)                      \
;   _Pragma("unroll") for (int ni = 0; ni < NT_; ++ni)
; template <int MT, int NT>
; DI void gemm_core(const u16* __restrict__ A, int lda, const u16* __restrict__ B, int ldb, int K,
;                   f32x4 (&acc)[MT][NT], char* smem) {
;     ...
;     for (int kk = 0; kk < 2; ++kk) {
;       bf16x8 xf[MT], wf[NT];
; #pragma unroll
;       for (int mi = 0; mi < MT; ++mi)
;         xf[mi] = *(const bf16x8*)(as + (wm * (MT * 16) + mi * 16 + fr) * 128 + (((kk * 4 + fq) ^ fsw) * 16));
; #pragma unroll
;       for (int ni = 0; ni < NT; ++ni)
;         wf[ni] = *(const bf16x8*)(bs + (wn * (NT * 16) + ni * 16 + fr) * 128 + (((kk * 4 + fq) ^ fsw) * 16));
;       __builtin_amdgcn_s_setprio(1);
; #pragma unroll
;       for (int mi = 0; mi < MT; ++mi)
; #pragma unroll
;         for (int ni = 0; ni < NT; ++ni) acc[mi][ni] = mfma16(wf[ni], xf[mi], acc[mi][ni]);
;       __builtin_amdgcn_s_setprio(0);
;     }
;   }
; DI void phase_inproj(const Params& p, int l, char* smem) {
;     ...
;     EPI_LOOP(4, 8) {
;       const int row = r0 + wm_ * 64 + mi * 16 + fr_, col = c0 + wn_ * 128 + ni * 16 + fq_ * 4;
;       if (col < PC) {
;         uint2 o;
;         o.x = pack2(acc[mi][ni][0], acc[mi][ni][1]); o.y = pack2(acc[mi][ni][2], acc[mi][ni][3]);
;         *(uint2*)(p.P() + (size_t)row * PC + col) = o;
	v_or_b32_e32 v206, s5, v186
	v_add_u32_e32 v207, v206, v188
	v_add_u32_e32 v206, v206, v187
	v_mfma_f32_16x16x32_bf16 v[158:161], v[220:223], v[194:197], v[158:161]
	v_mfma_f32_16x16x32_bf16 v[94:97], v[220:223], v[198:201], v[94:97]
	v_mfma_f32_16x16x32_bf16 v[62:65], v[220:223], v[202:205], v[62:65]
	s_waitcnt lgkmcnt(1)
	v_mfma_f32_16x16x32_bf16 v[30:33], v[220:223], v[216:219], v[30:33]
	ds_read_b128 v[190:193], v206
	v_mfma_f32_16x16x32_bf16 v[154:157], v[224:227], v[194:197], v[154:157]
	ds_read_b128 v[220:223], v207 offset:32768
	v_mfma_f32_16x16x32_bf16 v[90:93], v[224:227], v[198:201], v[90:93]
	v_mfma_f32_16x16x32_bf16 v[58:61], v[224:227], v[202:205], v[58:61]
	v_mfma_f32_16x16x32_bf16 v[26:29], v[224:227], v[216:219], v[26:29]
	ds_read_b128 v[208:211], v206 offset:2048
	v_mfma_f32_16x16x32_bf16 v[146:149], v[228:231], v[194:197], v[146:149]
	ds_read_b128 v[224:227], v207 offset:34816
	v_mfma_f32_16x16x32_bf16 v[86:89], v[228:231], v[198:201], v[86:89]
	v_mfma_f32_16x16x32_bf16 v[54:57], v[228:231], v[202:205], v[54:57]
	v_mfma_f32_16x16x32_bf16 v[22:25], v[228:231], v[216:219], v[22:25]
	ds_read_b128 v[212:215], v206 offset:4096
	v_mfma_f32_16x16x32_bf16 v[142:145], v[232:235], v[194:197], v[142:145]
	ds_read_b128 v[228:231], v207 offset:36864
	v_mfma_f32_16x16x32_bf16 v[82:85], v[232:235], v[198:201], v[82:85]
	v_mfma_f32_16x16x32_bf16 v[50:53], v[232:235], v[202:205], v[50:53]
	v_mfma_f32_16x16x32_bf16 v[18:21], v[232:235], v[216:219], v[18:21]
	v_mfma_f32_16x16x32_bf16 v[122:125], v[236:239], v[194:197], v[122:125]
	ds_read_b128 v[232:235], v207 offset:38912
	v_mfma_f32_16x16x32_bf16 v[78:81], v[236:239], v[198:201], v[78:81]
	v_mfma_f32_16x16x32_bf16 v[46:49], v[236:239], v[202:205], v[46:49]
	v_mfma_f32_16x16x32_bf16 v[14:17], v[236:239], v[216:219], v[14:17]
	v_mfma_f32_16x16x32_bf16 v[106:109], v[240:243], v[194:197], v[106:109]
	ds_read_b128 v[236:239], v207 offset:40960
	v_mfma_f32_16x16x32_bf16 v[74:77], v[240:243], v[198:201], v[74:77]
	v_mfma_f32_16x16x32_bf16 v[42:45], v[240:243], v[202:205], v[42:45]
	v_mfma_f32_16x16x32_bf16 v[10:13], v[240:243], v[216:219], v[10:13]
	v_mfma_f32_16x16x32_bf16 v[102:105], v[244:247], v[194:197], v[102:105]
	ds_read_b128 v[240:243], v207 offset:43008
	v_mfma_f32_16x16x32_bf16 v[70:73], v[244:247], v[198:201], v[70:73]
	v_mfma_f32_16x16x32_bf16 v[38:41], v[244:247], v[202:205], v[38:41]
	v_mfma_f32_16x16x32_bf16 v[6:9], v[244:247], v[216:219], v[6:9]
	s_waitcnt lgkmcnt(9)
	v_mfma_f32_16x16x32_bf16 v[2:5], v[248:251], v[216:219], v[2:5]
	ds_read_b128 v[244:247], v207 offset:45056
	ds_read_b128 v[216:219], v206 offset:6144
	v_mfma_f32_16x16x32_bf16 v[98:101], v[248:251], v[194:197], v[98:101]
	v_mfma_f32_16x16x32_bf16 v[66:69], v[248:251], v[198:201], v[66:69]
	v_mfma_f32_16x16x32_bf16 v[34:37], v[248:251], v[202:205], v[34:37]
	ds_read_b128 v[248:251], v207 offset:47104
	s_cmp_lg_u32 s3, 16
	s_mov_b32 s1, s4
	s_mov_b32 s2, s3
	s_cbranch_scc1 .LBB0_131
	s_waitcnt vmcnt(0) lgkmcnt(0)
	v_mov_b32_e32 v170, 0x358637bd
	v_mov_b32_e32 v194, 0x25a08
	v_mbcnt_lo_u32_b32 v195, -1, 0
	v_mbcnt_hi_u32_b32 v196, -1, v195
	v_mov_b32_e32 v197, 0x24000
	v_mov_b32_e32 v198, 0x1fa0
	v_mov_b32_e32 v199, 0x41b17218
	v_mov_b32_e32 v200, 0x7e800
	v_mov_b32_e32 v201, 0xfd0
	v_mov_b32_e32 v202, 0x100
	v_mov_b32_e32 v203, 0x200
	v_mov_b32_e32 v204, 0x7f61b1e6
	v_mov_b32_e32 v205, 0xff800000
	v_mov_b32_e32 v206, 0x3f80
	v_mov_b32_e32 v207, 0x1d400
	s_waitcnt vmcnt(7)
	v_mov_b32_e32 v110, v171
	v_mov_b32_e32 v111, v171
	s_barrier
	s_nop 0
	v_ashrrev_i32_e32 v112, 1, v111
	v_and_b32_e32 v112, 0xffffffc0, v112
	v_and_b32_e32 v0, 15, v110
	s_waitcnt vmcnt(5)
	v_add_u32_e32 v114, s0, v112
	v_lshlrev_b32_e32 v111, 1, v111
	v_lshrrev_b32_e32 v110, 2, v110
	v_and_b32_e32 v111, 0x80, v111
	v_and_b32_e32 v110, 12, v110
	v_or_b32_e32 v115, v114, v0
	v_or3_b32 v110, v110, v111, s19
	v_mad_i64_i32 v[112:113], s[0:1], v115, s91, 0
	v_cmp_gt_i32_e64 s[12:13], s69, v110
	v_lshl_add_u64 v[112:113], s[78:79], 0, v[112:113]
	v_ashrrev_i32_e32 v111, 31, v110
	s_and_saveexec_b64 s[0:1], s[12:13]
	s_cbranch_execz .LBB0_134
	v_lshl_add_u64 v[116:117], v[110:111], 1, v[112:113]
	v_cvt_pk_bf16_f32 v119, v160, v161
	v_cvt_pk_bf16_f32 v118, v158, v159
	global_store_dwordx2 v[116:117], v[118:119], off

;   __device__ __forceinline__ u16* wqx(int l) const { return (u16*)(ws + l * LAYER_W + O_WQX); }
;   __device__ __forceinline__ u16* P() const { return (u16*)(ws + O_P); }
; DI int ltid() { int t = threadIdx.x; asm volatile("" : "+v"(t)); return t; }
; #define GLOAD(kt) { GL1(0, kt) GL1(1, kt) GL1(2, kt) GL1(3, kt) }
; #define SSTORE(buf)                              \
;   {                                              \
;     char* as_ = smem + (buf) * BUF;              \
;     char* bs_ = as_ + ASZ;                       \
;     SS1(0) SS1(1) SS1(2) SS1(3)                  \
;   }
; template <int MT, int NT>
; DI void gemm_core(const u16* __restrict__ A, int lda, const u16* __restrict__ B, int ldb, int K,
;                   f32x4 (&acc)[MT][NT], char* smem) {
;   constexpr int BM = 64 * MT, BN = 32 * NT;
;   constexpr int ASZ = BM * 128, BSZ = BN * 128, BUF = ASZ + BSZ;
;   constexpr int NA = BM / 64, NB = BN / 64;
;   const int tid = ltid(), l = tid & 63, w = tid >> 6, wm = w >> 1, wn = w & 1;
;   const int fr = l & 15, fq = l >> 4;
;   uint4 ra0, ra1, ra2, ra3, rb0, rb1, rb2, rb3;
;   const int nk = K >> 6;
;   const int srow = tid >> 3, sch = tid & 7;
;   const int ssw = sch ^ ((srow >> 1) & 7);
;   const int fsw = (fr >> 1) & 7;
;     ...
;   GLOAD(0);
;   SSTORE(0);
;   GLOAD(((1 < nk) ? 1 : 0));
; DI void qx_tile(const Params& p, int l, int rt, int ct, char* smem) {
;     ...
;   f32x4 acc[4][8];
;   zero_acc<4, 8>(acc);
;   gemm_core<4, 8>(p.P() + (size_t)r0 * PC + CQ, PC, p.wqx(l) + (size_t)c0 * KP256, KP256, 256, acc, smem);
.LBB0_234:
	s_or_b64 exec, exec, s[0:1]
	s_mul_i32 s0, s8, 0x7ffffd
	s_add_i32 s0, s0, s7
	s_lshl_b32 s1, s6, 8
	s_lshl_b32 s0, s0, 9
	s_and_b32 s1, s1, 0x100
	s_or_b32 s0, s0, s1
	s_mul_i32 s6, s5, 0x1fa0
	s_mul_hi_i32 s1, s5, 0x1fa0
	s_add_u32 s6, s78, s6
	s_addc_u32 s1, s79, s1
	s_add_u32 s6, s6, 0x1c10
	s_addc_u32 s7, s1, 0
	s_mul_i32 s8, s0, 0x280
	s_mul_hi_i32 s1, s0, 0x280
	s_add_u32 s8, s2, s8
	v_mov_b32_e32 v34, v171
	s_addc_u32 s9, s3, s1
	v_mov_b64_e32 v[26:27], s[6:7]
	v_ashrrev_i32_e32 v35, 3, v34
	v_lshlrev_b32_e32 v36, 4, v34
	v_mov_b64_e32 v[30:31], s[8:9]
	v_add_u32_e32 v37, 64, v35
	v_add_u32_e32 v38, 0x80, v35
	v_add_u32_e32 v39, 0xc0, v35
	s_waitcnt lgkmcnt(0)
	v_mad_i64_i32 v[2:3], s[6:7], v35, s91, v[26:27]
	v_and_b32_e32 v0, 0x70, v36
	v_mad_i64_i32 v[6:7], s[6:7], v35, s12, v[30:31]
	v_mad_i64_i32 v[10:11], s[6:7], v37, s91, v[26:27]
	v_mad_i64_i32 v[14:15], s[6:7], v37, s12, v[30:31]
	v_mad_i64_i32 v[18:19], s[6:7], v38, s91, v[26:27]
	v_mad_i64_i32 v[22:23], s[6:7], v38, s12, v[30:31]
	v_mad_i64_i32 v[26:27], s[6:7], v39, s91, v[26:27]
	v_mad_i64_i32 v[30:31], s[6:7], v39, s12, v[30:31]
	v_lshl_add_u64 v[162:163], v[2:3], 0, v[0:1]
	v_lshl_add_u64 v[164:165], v[6:7], 0, v[0:1]
	v_lshl_add_u64 v[166:167], v[10:11], 0, v[0:1]
	v_lshl_add_u64 v[168:169], v[14:15], 0, v[0:1]
	v_lshl_add_u64 v[176:177], v[18:19], 0, v[0:1]
	v_lshl_add_u64 v[178:179], v[22:23], 0, v[0:1]
	v_lshl_add_u64 v[180:181], v[26:27], 0, v[0:1]
	v_lshl_add_u64 v[182:183], v[30:31], 0, v[0:1]
	global_load_dwordx4 v[2:5], v[162:163], off
	global_load_dwordx4 v[6:9], v[164:165], off
	global_load_dwordx4 v[10:13], v[166:167], off
	global_load_dwordx4 v[14:17], v[168:169], off
	global_load_dwordx4 v[18:21], v[176:177], off
	global_load_dwordx4 v[22:25], v[178:179], off
	global_load_dwordx4 v[26:29], v[180:181], off
	global_load_dwordx4 v[30:33], v[182:183], off
	global_load_dwordx4 v[98:101], v[180:181], off offset:128
	global_load_dwordx4 v[102:105], v[176:177], off offset:128
	global_load_dwordx4 v[106:109], v[166:167], off offset:128
	global_load_dwordx4 v[110:113], v[162:163], off offset:128
	global_load_dwordx4 v[114:117], v[182:183], off offset:128
	global_load_dwordx4 v[118:121], v[178:179], off offset:128
	global_load_dwordx4 v[122:125], v[168:169], off offset:128
	global_load_dwordx4 v[126:129], v[164:165], off offset:128
	v_lshrrev_b32_e32 v40, 4, v34
	v_lshrrev_b32_e32 v42, 1, v34
	v_bfe_u32 v43, v34, 1, 3
	v_and_b32_e32 v44, 15, v34
	v_lshlrev_b32_e32 v0, 7, v35
	v_bitop3_b32 v173, v36, s75, v34 bitop3:0x48
	v_bfe_u32 v41, v34, 4, 2
	v_lshlrev_b32_e32 v45, 1, v34
	v_and_or_b32 v34, v42, s90, v44
	v_bitop3_b32 v36, v40, v43, 3 bitop3:0x6c
	v_or_b32_e32 v40, v0, v173
	v_lshlrev_b32_e32 v175, 7, v37
	v_lshlrev_b32_e32 v184, 7, v38
	v_lshlrev_b32_e32 v185, 7, v39
	v_lshlrev_b32_e32 v186, 4, v36
	v_lshlrev_b32_e32 v187, 7, v34
	v_or_b32_e32 v34, v175, v173
	v_or_b32_e32 v36, v184, v173
	v_or_b32_e32 v37, v185, v173
	v_and_or_b32 v35, v45, s57, v44
	v_lshlrev_b32_e32 v188, 7, v35
	s_mov_b32 s1, 0
	s_waitcnt vmcnt(15)
	ds_write_b128 v40, v[2:5]
	s_waitcnt vmcnt(13)
	ds_write_b128 v34, v[10:13]
	s_waitcnt vmcnt(11)
	ds_write_b128 v36, v[18:21]
	s_waitcnt vmcnt(9)
	ds_write_b128 v37, v[26:29]
	ds_write_b128 v40, v[6:9] offset:32768
	ds_write_b128 v34, v[14:17] offset:32768
	ds_write_b128 v36, v[22:25] offset:32768
	s_waitcnt vmcnt(8)
	ds_write_b128 v37, v[30:33] offset:32768
	v_bitop3_b32 v2, v41, v43, 4 bitop3:0x36
	v_lshlrev_b32_e32 v189, 4, v2
	v_mov_b32_e32 v2, 0
	v_mov_b32_e32 v3, v2
	v_mov_b32_e32 v4, v2
	v_mov_b32_e32 v5, v2
	v_mov_b32_e32 v6, v2
	v_mov_b32_e32 v7, v2
	v_mov_b32_e32 v8, v2
	v_mov_b32_e32 v9, v2
	v_mov_b32_e32 v10, v2
	v_mov_b32_e32 v11, v2
	v_mov_b32_e32 v12, v2
	v_mov_b32_e32 v13, v2
	v_mov_b32_e32 v14, v2
	v_mov_b32_e32 v15, v2
	v_mov_b32_e32 v16, v2
	v_mov_b32_e32 v17, v2
	v_mov_b32_e32 v18, v2
	v_mov_b32_e32 v19, v2
	v_mov_b32_e32 v20, v2
	v_mov_b32_e32 v21, v2
	v_mov_b32_e32 v22, v2
	v_mov_b32_e32 v23, v2
	v_mov_b32_e32 v24, v2
	v_mov_b32_e32 v25, v2
	v_mov_b32_e32 v26, v2
	v_mov_b32_e32 v27, v2
	v_mov_b32_e32 v28, v2
	v_mov_b32_e32 v29, v2
	v_mov_b32_e32 v30, v2
	v_mov_b32_e32 v31, v2
	v_mov_b32_e32 v32, v2
	v_mov_b32_e32 v33, v2
	v_mov_b32_e32 v34, v2
	v_mov_b32_e32 v35, v2
	v_mov_b32_e32 v36, v2
	v_mov_b32_e32 v37, v2
	v_mov_b32_e32 v38, v2
	v_mov_b32_e32 v39, v2
	v_mov_b32_e32 v40, v2
	v_mov_b32_e32 v41, v2
	v_mov_b32_e32 v42, v2
	v_mov_b32_e32 v43, v2
	v_mov_b32_e32 v44, v2
	v_mov_b32_e32 v45, v2
	v_mov_b32_e32 v46, v2
	v_mov_b32_e32 v47, v2
	v_mov_b32_e32 v48, v2
	v_mov_b32_e32 v49, v2
	v_mov_b32_e32 v50, v2
	v_mov_b32_e32 v51, v2
	v_mov_b32_e32 v52, v2
	v_mov_b32_e32 v53, v2
	v_mov_b32_e32 v54, v2
	v_mov_b32_e32 v55, v2
	v_mov_b32_e32 v56, v2
	v_mov_b32_e32 v57, v2
	v_mov_b32_e32 v58, v2
	v_mov_b32_e32 v59, v2
	v_mov_b32_e32 v60, v2
	v_mov_b32_e32 v61, v2
	v_mov_b32_e32 v62, v2
	v_mov_b32_e32 v63, v2
	v_mov_b32_e32 v64, v2
	v_mov_b32_e32 v65, v2
	v_mov_b32_e32 v66, v2
	v_mov_b32_e32 v67, v2
	v_mov_b32_e32 v68, v2
	v_mov_b32_e32 v69, v2
	v_mov_b32_e32 v70, v2
	v_mov_b32_e32 v71, v2
	v_mov_b32_e32 v72, v2
	v_mov_b32_e32 v73, v2
	v_mov_b32_e32 v74, v2
	v_mov_b32_e32 v75, v2
	v_mov_b32_e32 v76, v2
	v_mov_b32_e32 v77, v2
	v_mov_b32_e32 v78, v2
	v_mov_b32_e32 v79, v2
	v_mov_b32_e32 v80, v2
	v_mov_b32_e32 v81, v2
	v_mov_b32_e32 v82, v2
	v_mov_b32_e32 v83, v2
	v_mov_b32_e32 v84, v2
	v_mov_b32_e32 v85, v2
	v_mov_b32_e32 v86, v2
	v_mov_b32_e32 v87, v2
	v_mov_b32_e32 v88, v2
	v_mov_b32_e32 v89, v2
	v_mov_b32_e32 v90, v2
	v_mov_b32_e32 v91, v2
	v_mov_b32_e32 v92, v2
	v_mov_b32_e32 v93, v2
	v_mov_b32_e32 v94, v2
	v_mov_b32_e32 v95, v2
	v_mov_b32_e32 v96, v2
	v_mov_b32_e32 v97, v2
	v_mov_b32_e32 v130, v2
	v_mov_b32_e32 v131, v2
	v_mov_b32_e32 v132, v2
	v_mov_b32_e32 v133, v2
	v_mov_b32_e32 v134, v2
	v_mov_b32_e32 v135, v2
	v_mov_b32_e32 v136, v2
	v_mov_b32_e32 v137, v2
	v_mov_b32_e32 v138, v2
	v_mov_b32_e32 v139, v2
	v_mov_b32_e32 v140, v2
	v_mov_b32_e32 v141, v2
	v_mov_b32_e32 v142, v2
	v_mov_b32_e32 v143, v2
	v_mov_b32_e32 v144, v2
	v_mov_b32_e32 v145, v2
	v_mov_b32_e32 v146, v2
	v_mov_b32_e32 v147, v2
	v_mov_b32_e32 v148, v2
	v_mov_b32_e32 v149, v2
	v_mov_b32_e32 v150, v2
	v_mov_b32_e32 v151, v2
	v_mov_b32_e32 v152, v2
	v_mov_b32_e32 v153, v2
	v_mov_b32_e32 v154, v2
	v_mov_b32_e32 v155, v2
	v_mov_b32_e32 v156, v2
	v_mov_b32_e32 v157, v2
	v_mov_b32_e32 v158, v2
	v_mov_b32_e32 v159, v2
	v_mov_b32_e32 v160, v2
	v_mov_b32_e32 v161, v2
	s_waitcnt vmcnt(0) lgkmcnt(0)
	s_barrier
; DI f32x4 mfma16(bf16x8 a, bf16x8 b, f32x4 c) { return __builtin_amdgcn_mfma_f32_16x16x32_bf16(a, b, c, 0, 0, 0); }
; #define GLOAD(kt) { GL1(0, kt) GL1(1, kt) GL1(2, kt) GL1(3, kt) }
; #define SSTORE(buf)                              \
;   {                                              \
;     char* as_ = smem + (buf) * BUF;              \
;     char* bs_ = as_ + ASZ;                       \
;     SS1(0) SS1(1) SS1(2) SS1(3)                  \
;   }
; template <int MT, int NT>
; DI void gemm_core(const u16* __restrict__ A, int lda, const u16* __restrict__ B, int ldb, int K,
;                   f32x4 (&acc)[MT][NT], char* smem) {
;     ...
;   for (int kt = 0; kt < nk; ++kt) {
;     __syncthreads();
;     SSTORE((kt + 1) & 1);
;     { const int kn_ = (kt + 2 < nk) ? kt + 2 : nk - 1; GLOAD(kn_); }
;     const char* as = smem + (kt & 1) * BUF;
;     const char* bs = as + ASZ;
; #pragma unroll
;     for (int kk = 0; kk < 2; ++kk) {
;       bf16x8 xf[MT], wf[NT];
; #pragma unroll
;       for (int mi = 0; mi < MT; ++mi)
;         xf[mi] = *(const bf16x8*)(as + (wm * (MT * 16) + mi * 16 + fr) * 128 + (((kk * 4 + fq) ^ fsw) * 16));
; #pragma unroll
;       for (int ni = 0; ni < NT; ++ni)
;         wf[ni] = *(const bf16x8*)(bs + (wn * (NT * 16) + ni * 16 + fr) * 128 + (((kk * 4 + fq) ^ fsw) * 16));
;       __builtin_amdgcn_s_setprio(1);
; #pragma unroll
;       for (int mi = 0; mi < MT; ++mi)
; #pragma unroll
;         for (int ni = 0; ni < NT; ++ni) acc[mi][ni] = mfma16(wf[ni], xf[mi], acc[mi][ni]);
	v_add_u32_e32 v207, v186, v188
	v_add_u32_e32 v206, v186, v187
	ds_read_b128 v[190:193], v206
	ds_read_b128 v[208:211], v206 offset:2048
	ds_read_b128 v[212:215], v206 offset:4096
	ds_read_b128 v[216:219], v206 offset:6144
	ds_read_b128 v[220:223], v207 offset:32768
	ds_read_b128 v[224:227], v207 offset:34816
	ds_read_b128 v[228:231], v207 offset:36864
	ds_read_b128 v[232:235], v207 offset:38912
	ds_read_b128 v[236:239], v207 offset:40960
	ds_read_b128 v[240:243], v207 offset:43008
	ds_read_b128 v[244:247], v207 offset:45056
	ds_read_b128 v[248:251], v207 offset:47104
	s_waitcnt lgkmcnt(0)
.LBB0_235:
	s_add_i32 s6, s1, 0x10000
	s_and_b32 s7, s6, 0x10000
	s_cmp_eq_u32 s1, 0
	s_cselect_b32 s54, 0x100, s63
	s_and_b32 s1, s1, 0x10000
	v_or_b32_e32 v206, s1, v189
	v_add_u32_e32 v207, v206, v188
	v_add_u32_e32 v206, v206, v187
	v_add3_u32 v170, s7, v0, v173
	s_waitcnt lgkmcnt(10)
	v_mfma_f32_16x16x32_bf16 v[158:161], v[220:223], v[190:193], v[158:161]
	s_waitcnt vmcnt(7)
	ds_write_b128 v170, v[110:113]
	s_waitcnt lgkmcnt(10)
	v_mfma_f32_16x16x32_bf16 v[94:97], v[220:223], v[208:211], v[94:97]
	v_lshl_add_u64 v[110:111], v[162:163], 0, s[54:55]
	global_load_dwordx4 v[110:113], v[110:111], off
	s_waitcnt lgkmcnt(8)
	v_mfma_f32_16x16x32_bf16 v[62:65], v[220:223], v[212:215], v[62:65]
	s_waitcnt vmcnt(7)
	ds_write_b128 v170, v[126:129] offset:32768
	s_waitcnt lgkmcnt(3)
	v_mfma_f32_16x16x32_bf16 v[30:33], v[220:223], v[216:219], v[30:33]
	v_lshl_add_u64 v[126:127], v[164:165], 0, s[54:55]
	global_load_dwordx4 v[126:129], v[126:127], off
	ds_read_b128 v[194:197], v206
	v_mfma_f32_16x16x32_bf16 v[154:157], v[224:227], v[190:193], v[154:157]
	ds_read_b128 v[220:223], v207 offset:32768
	s_waitcnt vmcnt(7)
	ds_write_b128 v170, v[106:109] offset:8192
	v_mfma_f32_16x16x32_bf16 v[90:93], v[224:227], v[208:211], v[90:93]
	v_lshl_add_u64 v[106:107], v[166:167], 0, s[54:55]
	global_load_dwordx4 v[106:109], v[106:107], off
	v_mfma_f32_16x16x32_bf16 v[58:61], v[224:227], v[212:215], v[58:61]
	v_mfma_f32_16x16x32_bf16 v[26:29], v[224:227], v[216:219], v[26:29]
	ds_read_b128 v[198:201], v206 offset:2048
	v_mfma_f32_16x16x32_bf16 v[150:153], v[228:231], v[190:193], v[150:153]
	ds_read_b128 v[224:227], v207 offset:34816
	s_waitcnt vmcnt(7)
	ds_write_b128 v170, v[122:125] offset:40960
	v_mfma_f32_16x16x32_bf16 v[86:89], v[228:231], v[208:211], v[86:89]
	v_lshl_add_u64 v[122:123], v[168:169], 0, s[54:55]
	global_load_dwordx4 v[122:125], v[122:123], off
	v_mfma_f32_16x16x32_bf16 v[54:57], v[228:231], v[212:215], v[54:57]
	v_mfma_f32_16x16x32_bf16 v[22:25], v[228:231], v[216:219], v[22:25]
	ds_read_b128 v[202:205], v206 offset:4096
	v_mfma_f32_16x16x32_bf16 v[146:149], v[232:235], v[190:193], v[146:149]
	ds_read_b128 v[228:231], v207 offset:36864
	s_waitcnt vmcnt(7)
	ds_write_b128 v170, v[102:105] offset:16384
	v_mfma_f32_16x16x32_bf16 v[82:85], v[232:235], v[208:211], v[82:85]
	v_lshl_add_u64 v[102:103], v[176:177], 0, s[54:55]
	global_load_dwordx4 v[102:105], v[102:103], off
	v_mfma_f32_16x16x32_bf16 v[50:53], v[232:235], v[212:215], v[50:53]
	v_mfma_f32_16x16x32_bf16 v[18:21], v[232:235], v[216:219], v[18:21]
	v_mfma_f32_16x16x32_bf16 v[142:145], v[236:239], v[190:193], v[142:145]
	ds_read_b128 v[232:235], v207 offset:38912
	s_waitcnt vmcnt(7)
	ds_write_b128 v170, v[118:121] offset:49152
	v_mfma_f32_16x16x32_bf16 v[78:81], v[236:239], v[208:211], v[78:81]
	v_lshl_add_u64 v[118:119], v[178:179], 0, s[54:55]
	global_load_dwordx4 v[118:121], v[118:119], off
	v_mfma_f32_16x16x32_bf16 v[46:49], v[236:239], v[212:215], v[46:49]
	v_mfma_f32_16x16x32_bf16 v[14:17], v[236:239], v[216:219], v[14:17]
	v_mfma_f32_16x16x32_bf16 v[138:141], v[240:243], v[190:193], v[138:141]
	ds_read_b128 v[236:239], v207 offset:40960
	s_waitcnt vmcnt(7)
	ds_write_b128 v170, v[98:101] offset:24576
	v_mfma_f32_16x16x32_bf16 v[74:77], v[240:243], v[208:211], v[74:77]
	v_lshl_add_u64 v[98:99], v[180:181], 0, s[54:55]
	global_load_dwordx4 v[98:101], v[98:99], off
	v_mfma_f32_16x16x32_bf16 v[42:45], v[240:243], v[212:215], v[42:45]
	v_mfma_f32_16x16x32_bf16 v[10:13], v[240:243], v[216:219], v[10:13]
	v_mfma_f32_16x16x32_bf16 v[134:137], v[244:247], v[190:193], v[134:137]
	ds_read_b128 v[240:243], v207 offset:43008
	s_waitcnt vmcnt(7)
	ds_write_b128 v170, v[114:117] offset:57344
	v_mfma_f32_16x16x32_bf16 v[70:73], v[244:247], v[208:211], v[70:73]
	v_lshl_add_u64 v[114:115], v[182:183], 0, s[54:55]
	global_load_dwordx4 v[114:117], v[114:115], off
	v_mfma_f32_16x16x32_bf16 v[38:41], v[244:247], v[212:215], v[38:41]
	v_mfma_f32_16x16x32_bf16 v[6:9], v[244:247], v[216:219], v[6:9]
	s_waitcnt lgkmcnt(15)
	v_mfma_f32_16x16x32_bf16 v[2:5], v[248:251], v[216:219], v[2:5]
	ds_read_b128 v[244:247], v207 offset:45056
	ds_read_b128 v[216:219], v206 offset:6144
	v_mfma_f32_16x16x32_bf16 v[130:133], v[248:251], v[190:193], v[130:133]
	v_mfma_f32_16x16x32_bf16 v[66:69], v[248:251], v[208:211], v[66:69]
	v_mfma_f32_16x16x32_bf16 v[34:37], v[248:251], v[212:215], v[34:37]
	ds_read_b128 v[248:251], v207 offset:47104
	s_waitcnt lgkmcnt(3)
	s_barrier
; DI f32x4 mfma16(bf16x8 a, bf16x8 b, f32x4 c) { return __builtin_amdgcn_mfma_f32_16x16x32_bf16(a, b, c, 0, 0, 0); }
; #define EPI_LOOP(MT_, NT_)                                                \
;   const int l_ = ltid() & 63, w_ = ltid() >> 6;                           \
;   const int wm_ = w_ >> 1, wn_ = w_ & 1, fr_ = l_ & 15, fq_ = l_ >> 4;    \
;   _Pragma("unroll") for (int mi = 0; mi < MT_; ++mi)                      \
;   _Pragma("unroll") for (int ni = 0; ni < NT_; ++ni)
; template <int MT, int NT>
; DI void gemm_core(const u16* __restrict__ A, int lda, const u16* __restrict__ B, int ldb, int K,
;                   f32x4 (&acc)[MT][NT], char* smem) {
;     ...
; #pragma unroll
;     for (int kk = 0; kk < 2; ++kk) {
;       bf16x8 xf[MT], wf[NT];
; #pragma unroll
;       for (int mi = 0; mi < MT; ++mi)
;         xf[mi] = *(const bf16x8*)(as + (wm * (MT * 16) + mi * 16 + fr) * 128 + (((kk * 4 + fq) ^ fsw) * 16));
; #pragma unroll
;       for (int ni = 0; ni < NT; ++ni)
;         wf[ni] = *(const bf16x8*)(bs + (wn * (NT * 16) + ni * 16 + fr) * 128 + (((kk * 4 + fq) ^ fsw) * 16));
;       __builtin_amdgcn_s_setprio(1);
; #pragma unroll
;       for (int mi = 0; mi < MT; ++mi)
; #pragma unroll
;         for (int ni = 0; ni < NT; ++ni) acc[mi][ni] = mfma16(wf[ni], xf[mi], acc[mi][ni]);
;       __builtin_amdgcn_s_setprio(0);
;     }
; DI void qx_tile(const Params& p, int l, int rt, int ct, char* smem) {
;     ...
;   u16* QX = (u16*)p.out;
;   EPI_LOOP(4, 8) {
;     const int rl = wm_ * 64 + mi * 16 + fr_, col = c0 + wn_ * 128 + ni * 16 + fq_ * 4;
;     const float rs = rsv[rl];
;     uint2 o;
;     o.x = pack2(acc[mi][ni][0] * rs, acc[mi][ni][1] * rs); o.y = pack2(acc[mi][ni][2] * rs, acc[mi][ni][3] * rs);
;     *(uint2*)(QX + (size_t)(r0 + rl) * LDQ + col) = o;
;   }
	v_or_b32_e32 v206, s7, v186
	v_add_u32_e32 v207, v206, v188
	v_add_u32_e32 v206, v206, v187
	v_mfma_f32_16x16x32_bf16 v[158:161], v[220:223], v[194:197], v[158:161]
	v_mfma_f32_16x16x32_bf16 v[94:97], v[220:223], v[198:201], v[94:97]
	v_mfma_f32_16x16x32_bf16 v[62:65], v[220:223], v[202:205], v[62:65]
	s_waitcnt lgkmcnt(1)
	v_mfma_f32_16x16x32_bf16 v[30:33], v[220:223], v[216:219], v[30:33]
	ds_read_b128 v[190:193], v206
	v_mfma_f32_16x16x32_bf16 v[154:157], v[224:227], v[194:197], v[154:157]
	ds_read_b128 v[220:223], v207 offset:32768
	v_mfma_f32_16x16x32_bf16 v[90:93], v[224:227], v[198:201], v[90:93]
	v_mfma_f32_16x16x32_bf16 v[58:61], v[224:227], v[202:205], v[58:61]
	v_mfma_f32_16x16x32_bf16 v[26:29], v[224:227], v[216:219], v[26:29]
	ds_read_b128 v[208:211], v206 offset:2048
	v_mfma_f32_16x16x32_bf16 v[150:153], v[228:231], v[194:197], v[150:153]
	ds_read_b128 v[224:227], v207 offset:34816
	v_mfma_f32_16x16x32_bf16 v[86:89], v[228:231], v[198:201], v[86:89]
	v_mfma_f32_16x16x32_bf16 v[54:57], v[228:231], v[202:205], v[54:57]
	v_mfma_f32_16x16x32_bf16 v[22:25], v[228:231], v[216:219], v[22:25]
	ds_read_b128 v[212:215], v206 offset:4096
	v_mfma_f32_16x16x32_bf16 v[146:149], v[232:235], v[194:197], v[146:149]
	ds_read_b128 v[228:231], v207 offset:36864
	v_mfma_f32_16x16x32_bf16 v[82:85], v[232:235], v[198:201], v[82:85]
	v_mfma_f32_16x16x32_bf16 v[50:53], v[232:235], v[202:205], v[50:53]
	v_mfma_f32_16x16x32_bf16 v[18:21], v[232:235], v[216:219], v[18:21]
	v_mfma_f32_16x16x32_bf16 v[142:145], v[236:239], v[194:197], v[142:145]
	ds_read_b128 v[232:235], v207 offset:38912
	v_mfma_f32_16x16x32_bf16 v[78:81], v[236:239], v[198:201], v[78:81]
	v_mfma_f32_16x16x32_bf16 v[46:49], v[236:239], v[202:205], v[46:49]
	v_mfma_f32_16x16x32_bf16 v[14:17], v[236:239], v[216:219], v[14:17]
	v_mfma_f32_16x16x32_bf16 v[138:141], v[240:243], v[194:197], v[138:141]
	ds_read_b128 v[236:239], v207 offset:40960
	v_mfma_f32_16x16x32_bf16 v[74:77], v[240:243], v[198:201], v[74:77]
	v_mfma_f32_16x16x32_bf16 v[42:45], v[240:243], v[202:205], v[42:45]
	v_mfma_f32_16x16x32_bf16 v[10:13], v[240:243], v[216:219], v[10:13]
	v_mfma_f32_16x16x32_bf16 v[134:137], v[244:247], v[194:197], v[134:137]
	ds_read_b128 v[240:243], v207 offset:43008
	v_mfma_f32_16x16x32_bf16 v[70:73], v[244:247], v[198:201], v[70:73]
	v_mfma_f32_16x16x32_bf16 v[38:41], v[244:247], v[202:205], v[38:41]
	v_mfma_f32_16x16x32_bf16 v[6:9], v[244:247], v[216:219], v[6:9]
	s_waitcnt lgkmcnt(9)
	v_mfma_f32_16x16x32_bf16 v[2:5], v[248:251], v[216:219], v[2:5]
	ds_read_b128 v[244:247], v207 offset:45056
	ds_read_b128 v[216:219], v206 offset:6144
	v_mfma_f32_16x16x32_bf16 v[130:133], v[248:251], v[194:197], v[130:133]
	v_mfma_f32_16x16x32_bf16 v[66:69], v[248:251], v[198:201], v[66:69]
	v_mfma_f32_16x16x32_bf16 v[34:37], v[248:251], v[202:205], v[34:37]
	ds_read_b128 v[248:251], v207 offset:47104
	s_cmp_lg_u32 s6, 0x40000
	s_mov_b32 s1, s6
	s_cbranch_scc1 .LBB0_235
	s_waitcnt vmcnt(0) lgkmcnt(0)
	v_mov_b32_e32 v170, 0x358637bd
	v_mov_b32_e32 v194, 0x25a08
	v_mbcnt_lo_u32_b32 v195, -1, 0
	v_mbcnt_hi_u32_b32 v196, -1, v195
	v_mov_b32_e32 v197, 0x24000
	v_mov_b32_e32 v198, 0x1fa0
	v_mov_b32_e32 v199, 0x41b17218
	v_mov_b32_e32 v200, 0x7e800
	v_mov_b32_e32 v201, 0xfd0
	v_mov_b32_e32 v202, 0x100
	v_mov_b32_e32 v203, 0x200
	v_mov_b32_e32 v204, 0x7f61b1e6
	v_mov_b32_e32 v205, 0xff800000
	v_mov_b32_e32 v206, 0x3f80
	v_mov_b32_e32 v207, 0x1d400
	s_waitcnt vmcnt(1)
	v_mov_b32_e32 v98, v171
	v_mov_b32_e32 v99, v171
	s_barrier
	s_movk_i32 s1, 0xffc0
	v_and_b32_e32 v0, 15, v98
	v_ashrrev_i32_e32 v100, 1, v99
	v_lshlrev_b32_e32 v99, 1, v99
	v_lshrrev_b32_e32 v98, 2, v98
	v_and_or_b32 v0, v100, s1, v0
	v_and_b32_e32 v99, 0x80, v99
	v_and_b32_e32 v98, 12, v98
	v_or3_b32 v98, v98, v99, s0
	v_lshl_add_u32 v99, v0, 2, v197
	ds_read_b32 v106, v99
	v_add_u32_e32 v102, s5, v0
	v_mov_b64_e32 v[100:101], s[86:87]
	s_movk_i32 s6, 0xc80
	v_ashrrev_i32_e32 v99, 31, v98
	v_mad_i64_i32 v[102:103], s[0:1], v102, s6, v[100:101]
	s_waitcnt lgkmcnt(0)
	v_mul_f32_e32 v104, v158, v106
	v_mul_f32_e32 v107, v159, v106
	v_mul_f32_e32 v105, v160, v106
	v_mul_f32_e32 v108, v161, v106
	v_lshlrev_b64 v[98:99], 1, v[98:99]
	v_lshl_add_u64 v[102:103], v[102:103], 0, v[98:99]
	v_cvt_pk_bf16_f32 v105, v105, v108
	v_cvt_pk_bf16_f32 v104, v104, v107
	global_store_dwordx2 v[102:103], v[104:105], off
	v_mul_f32_e32 v104, v154, v106
	v_mul_f32_e32 v107, v155, v106
	v_mul_f32_e32 v105, v156, v106
	v_mul_f32_e32 v108, v157, v106
	v_cvt_pk_bf16_f32 v105, v105, v108
	v_cvt_pk_bf16_f32 v104, v104, v107
	global_store_dwordx2 v[102:103], v[104:105], off offset:32
	v_mul_f32_e32 v104, v150, v106
	v_mul_f32_e32 v107, v151, v106
	v_mul_f32_e32 v105, v152, v106
	v_mul_f32_e32 v108, v153, v106
	v_cvt_pk_bf16_f32 v105, v105, v108
	v_cvt_pk_bf16_f32 v104, v104, v107
	global_store_dwordx2 v[102:103], v[104:105], off offset:64
	v_mul_f32_e32 v104, v146, v106
	v_mul_f32_e32 v107, v147, v106
	v_mul_f32_e32 v105, v148, v106
	v_mul_f32_e32 v108, v149, v106
	v_cvt_pk_bf16_f32 v105, v105, v108
	v_cvt_pk_bf16_f32 v104, v104, v107
	global_store_dwordx2 v[102:103], v[104:105], off offset:96
	v_mul_f32_e32 v104, v142, v106
	v_mul_f32_e32 v107, v143, v106
	v_mul_f32_e32 v105, v144, v106
	v_mul_f32_e32 v108, v145, v106
	v_cvt_pk_bf16_f32 v105, v105, v108
	v_cvt_pk_bf16_f32 v104, v104, v107
	global_store_dwordx2 v[102:103], v[104:105], off offset:128
	v_mul_f32_e32 v104, v138, v106
	v_mul_f32_e32 v107, v139, v106
	v_mul_f32_e32 v105, v140, v106
	v_mul_f32_e32 v108, v141, v106
	v_cvt_pk_bf16_f32 v105, v105, v108
	v_cvt_pk_bf16_f32 v104, v104, v107
	global_store_dwordx2 v[102:103], v[104:105], off offset:160
	v_mul_f32_e32 v104, v134, v106
	v_mul_f32_e32 v107, v135, v106
	v_mul_f32_e32 v105, v136, v106
	v_mul_f32_e32 v108, v137, v106
	v_cvt_pk_bf16_f32 v105, v105, v108
	v_cvt_pk_bf16_f32 v104, v104, v107
	global_store_dwordx2 v[102:103], v[104:105], off offset:192
	v_mul_f32_e32 v104, v130, v106
	v_mul_f32_e32 v107, v131, v106
	v_mul_f32_e32 v105, v132, v106
	v_mul_f32_e32 v106, v133, v106
	v_cvt_pk_bf16_f32 v105, v105, v106
	v_cvt_pk_bf16_f32 v104, v104, v107
	global_store_dwordx2 v[102:103], v[104:105], off offset:224
	v_or_b32_e32 v102, 16, v0
	v_lshl_add_u32 v104, v102, 2, v197
	ds_read_b32 v104, v104
	v_add_u32_e32 v102, s5, v102
	v_mad_i64_i32 v[102:103], s[0:1], v102, s6, v[100:101]
	s_add_i32 s4, s4, 1
	s_waitcnt lgkmcnt(0)
; #define EPI_LOOP(MT_, NT_)                                                \
;   const int l_ = ltid() & 63, w_ = ltid() >> 6;                           \
;   const int wm_ = w_ >> 1, wn_ = w_ & 1, fr_ = l_ & 15, fq_ = l_ >> 4;    \
;   _Pragma("unroll") for (int mi = 0; mi < MT_; ++mi)                      \
;   _Pragma("unroll") for (int ni = 0; ni < NT_; ++ni)
; DI void qx_tile(const Params& p, int l, int rt, int ct, char* smem) {
;     ...
;   EPI_LOOP(4, 8) {
;     const int rl = wm_ * 64 + mi * 16 + fr_, col = c0 + wn_ * 128 + ni * 16 + fq_ * 4;
;     const float rs = rsv[rl];
;     uint2 o;
;     o.x = pack2(acc[mi][ni][0] * rs, acc[mi][ni][1] * rs); o.y = pack2(acc[mi][ni][2] * rs, acc[mi][ni][3] * rs);
;     *(uint2*)(QX + (size_t)(r0 + rl) * LDQ + col) = o;
;   }
;   __syncthreads();
	v_mul_f32_e32 v105, v94, v104
	v_mul_f32_e32 v106, v95, v104
	v_mul_f32_e32 v96, v96, v104
	v_mul_f32_e32 v97, v97, v104
	v_lshl_add_u64 v[94:95], v[102:103], 0, v[98:99]
	v_cvt_pk_bf16_f32 v97, v96, v97
	v_cvt_pk_bf16_f32 v96, v105, v106
	global_store_dwordx2 v[94:95], v[96:97], off
	v_mul_f32_e32 v90, v90, v104
	v_mul_f32_e32 v96, v91, v104
	v_mul_f32_e32 v91, v92, v104
	v_mul_f32_e32 v92, v93, v104
	v_cvt_pk_bf16_f32 v91, v91, v92
	v_cvt_pk_bf16_f32 v90, v90, v96
	global_store_dwordx2 v[94:95], v[90:91], off offset:32
	v_mul_f32_e32 v86, v86, v104
	v_mul_f32_e32 v90, v87, v104
	v_mul_f32_e32 v87, v88, v104
	v_mul_f32_e32 v88, v89, v104
	v_cvt_pk_bf16_f32 v87, v87, v88
	v_cvt_pk_bf16_f32 v86, v86, v90
	global_store_dwordx2 v[94:95], v[86:87], off offset:64
	v_mul_f32_e32 v82, v82, v104
	v_mul_f32_e32 v86, v83, v104
	v_mul_f32_e32 v83, v84, v104
	v_mul_f32_e32 v84, v85, v104
	v_cvt_pk_bf16_f32 v83, v83, v84
	v_cvt_pk_bf16_f32 v82, v82, v86
	global_store_dwordx2 v[94:95], v[82:83], off offset:96
	v_mul_f32_e32 v78, v78, v104
	v_mul_f32_e32 v82, v79, v104
	v_mul_f32_e32 v79, v80, v104
	v_mul_f32_e32 v80, v81, v104
	v_cvt_pk_bf16_f32 v79, v79, v80
	v_cvt_pk_bf16_f32 v78, v78, v82
	global_store_dwordx2 v[94:95], v[78:79], off offset:128
	v_mul_f32_e32 v74, v74, v104
	v_mul_f32_e32 v78, v75, v104
	v_mul_f32_e32 v75, v76, v104
	v_mul_f32_e32 v76, v77, v104
	v_cvt_pk_bf16_f32 v75, v75, v76
	v_cvt_pk_bf16_f32 v74, v74, v78
	global_store_dwordx2 v[94:95], v[74:75], off offset:160
	v_mul_f32_e32 v70, v70, v104
	v_mul_f32_e32 v74, v71, v104
	v_mul_f32_e32 v71, v72, v104
	v_mul_f32_e32 v72, v73, v104
	v_cvt_pk_bf16_f32 v71, v71, v72
	v_cvt_pk_bf16_f32 v70, v70, v74
	global_store_dwordx2 v[94:95], v[70:71], off offset:192
	v_mul_f32_e32 v66, v66, v104
	v_mul_f32_e32 v70, v67, v104
	v_mul_f32_e32 v67, v68, v104
	v_mul_f32_e32 v68, v69, v104
	v_cvt_pk_bf16_f32 v67, v67, v68
	v_cvt_pk_bf16_f32 v66, v66, v70
	global_store_dwordx2 v[94:95], v[66:67], off offset:224
	v_or_b32_e32 v66, 32, v0
	v_lshl_add_u32 v68, v66, 2, v197
	ds_read_b32 v68, v68
	v_add_u32_e32 v66, s5, v66
	v_mad_i64_i32 v[66:67], s[0:1], v66, s6, v[100:101]
	v_or_b32_e32 v0, 48, v0
	s_waitcnt lgkmcnt(0)
	v_mul_f32_e32 v69, v62, v68
	v_mul_f32_e32 v70, v63, v68
	v_mul_f32_e32 v64, v64, v68
	v_mul_f32_e32 v65, v65, v68
	v_lshl_add_u64 v[62:63], v[66:67], 0, v[98:99]
	v_cvt_pk_bf16_f32 v65, v64, v65
	v_cvt_pk_bf16_f32 v64, v69, v70
	global_store_dwordx2 v[62:63], v[64:65], off
	v_mul_f32_e32 v58, v58, v68
	v_mul_f32_e32 v64, v59, v68
	v_mul_f32_e32 v59, v60, v68
	v_mul_f32_e32 v60, v61, v68
	v_cvt_pk_bf16_f32 v59, v59, v60
	v_cvt_pk_bf16_f32 v58, v58, v64
	global_store_dwordx2 v[62:63], v[58:59], off offset:32
	v_mul_f32_e32 v54, v54, v68
	v_mul_f32_e32 v58, v55, v68
	v_mul_f32_e32 v55, v56, v68
	v_mul_f32_e32 v56, v57, v68
	v_cvt_pk_bf16_f32 v55, v55, v56
	v_cvt_pk_bf16_f32 v54, v54, v58
	global_store_dwordx2 v[62:63], v[54:55], off offset:64
	v_mul_f32_e32 v50, v50, v68
	v_mul_f32_e32 v54, v51, v68
	v_mul_f32_e32 v51, v52, v68
	v_mul_f32_e32 v52, v53, v68
	v_cvt_pk_bf16_f32 v51, v51, v52
	v_cvt_pk_bf16_f32 v50, v50, v54
	global_store_dwordx2 v[62:63], v[50:51], off offset:96
	v_mul_f32_e32 v46, v46, v68
	v_mul_f32_e32 v50, v47, v68
	v_mul_f32_e32 v47, v48, v68
	v_mul_f32_e32 v48, v49, v68
	v_cvt_pk_bf16_f32 v47, v47, v48
	v_cvt_pk_bf16_f32 v46, v46, v50
	global_store_dwordx2 v[62:63], v[46:47], off offset:128
	v_mul_f32_e32 v42, v42, v68
	v_mul_f32_e32 v46, v43, v68
	v_mul_f32_e32 v43, v44, v68
	v_mul_f32_e32 v44, v45, v68
	v_cvt_pk_bf16_f32 v43, v43, v44
	v_cvt_pk_bf16_f32 v42, v42, v46
	global_store_dwordx2 v[62:63], v[42:43], off offset:160
	v_mul_f32_e32 v38, v38, v68
	v_mul_f32_e32 v42, v39, v68
	v_mul_f32_e32 v39, v40, v68
	v_mul_f32_e32 v40, v41, v68
	v_cvt_pk_bf16_f32 v39, v39, v40
	v_cvt_pk_bf16_f32 v38, v38, v42
	global_store_dwordx2 v[62:63], v[38:39], off offset:192
	v_mul_f32_e32 v34, v34, v68
	v_mul_f32_e32 v38, v35, v68
	v_mul_f32_e32 v35, v36, v68
	v_mul_f32_e32 v36, v37, v68
	v_cvt_pk_bf16_f32 v35, v35, v36
	v_cvt_pk_bf16_f32 v34, v34, v38
	v_lshl_add_u32 v36, v0, 2, v197
	v_add_u32_e32 v0, s5, v0
	global_store_dwordx2 v[62:63], v[34:35], off offset:224
	v_mad_i64_i32 v[34:35], s[0:1], v0, s6, v[100:101]
	ds_read_b32 v0, v36
	s_mov_b64 s[0:1], 0
	s_waitcnt lgkmcnt(0)
	v_mul_f32_e32 v36, v30, v0
	v_mul_f32_e32 v37, v31, v0
	v_mul_f32_e32 v32, v32, v0
	v_mul_f32_e32 v33, v33, v0
	v_lshl_add_u64 v[30:31], v[34:35], 0, v[98:99]
	v_cvt_pk_bf16_f32 v33, v32, v33
	v_cvt_pk_bf16_f32 v32, v36, v37
	global_store_dwordx2 v[30:31], v[32:33], off
	v_mul_f32_e32 v26, v26, v0
	v_mul_f32_e32 v32, v27, v0
	v_mul_f32_e32 v27, v28, v0
	v_mul_f32_e32 v28, v29, v0
	v_cvt_pk_bf16_f32 v27, v27, v28
	v_cvt_pk_bf16_f32 v26, v26, v32
	global_store_dwordx2 v[30:31], v[26:27], off offset:32
	v_mul_f32_e32 v22, v22, v0
	v_mul_f32_e32 v26, v23, v0
	v_mul_f32_e32 v23, v24, v0
	v_mul_f32_e32 v24, v25, v0
	v_cvt_pk_bf16_f32 v23, v23, v24
	v_cvt_pk_bf16_f32 v22, v22, v26
	global_store_dwordx2 v[30:31], v[22:23], off offset:64
	v_mul_f32_e32 v18, v18, v0
	v_mul_f32_e32 v22, v19, v0
	v_mul_f32_e32 v19, v20, v0
	v_mul_f32_e32 v20, v21, v0
	v_cvt_pk_bf16_f32 v19, v19, v20
	v_cvt_pk_bf16_f32 v18, v18, v22
	global_store_dwordx2 v[30:31], v[18:19], off offset:96
	v_mul_f32_e32 v14, v14, v0
	v_mul_f32_e32 v18, v15, v0
	v_mul_f32_e32 v15, v16, v0
	v_mul_f32_e32 v16, v17, v0
	v_cvt_pk_bf16_f32 v15, v15, v16
	v_cvt_pk_bf16_f32 v14, v14, v18
	global_store_dwordx2 v[30:31], v[14:15], off offset:128
	v_mul_f32_e32 v10, v10, v0
	v_mul_f32_e32 v14, v11, v0
	v_mul_f32_e32 v11, v12, v0
	v_mul_f32_e32 v12, v13, v0
	v_cvt_pk_bf16_f32 v11, v11, v12
	v_cvt_pk_bf16_f32 v10, v10, v14
	global_store_dwordx2 v[30:31], v[10:11], off offset:160
	v_mul_f32_e32 v6, v6, v0
	v_mul_f32_e32 v10, v7, v0
	v_mul_f32_e32 v7, v8, v0
	v_mul_f32_e32 v8, v9, v0
	v_cvt_pk_bf16_f32 v7, v7, v8
	v_cvt_pk_bf16_f32 v6, v6, v10
	global_store_dwordx2 v[30:31], v[6:7], off offset:192
	v_mul_f32_e32 v2, v2, v0
	v_mul_f32_e32 v6, v3, v0
	v_mul_f32_e32 v3, v4, v0
	v_mul_f32_e32 v0, v5, v0
	v_cvt_pk_bf16_f32 v3, v3, v0
	v_cvt_pk_bf16_f32 v2, v2, v6
	global_store_dwordx2 v[30:31], v[2:3], off offset:224
	s_barrier
	s_branch .LBB0_228

; DI int lbid() { int b = blockIdx.x; asm volatile("" : "+s"(b)); return b; }
; DI int lgdim() { int b = gridDim.x; asm volatile("" : "+s"(b)); return b; }
; DI int ltid() { int t = threadIdx.x; asm volatile("" : "+v"(t)); return t; }
; #define GLOAD(kt) { GL1(0, kt) GL1(1, kt) GL1(2, kt) GL1(3, kt) }
; #define SSTORE(buf)                              \
;   {                                              \
;     char* as_ = smem + (buf) * BUF;              \
;     char* bs_ = as_ + ASZ;                       \
;     SS1(0) SS1(1) SS1(2) SS1(3)                  \
;   }
; template <int MT, int NT>
; DI void gemm_core(const u16* __restrict__ A, int lda, const u16* __restrict__ B, int ldb, int K,
;                   f32x4 (&acc)[MT][NT], char* smem) {
;   constexpr int BM = 64 * MT, BN = 32 * NT;
;   constexpr int ASZ = BM * 128, BSZ = BN * 128, BUF = ASZ + BSZ;
;   constexpr int NA = BM / 64, NB = BN / 64;
;   const int tid = ltid(), l = tid & 63, w = tid >> 6, wm = w >> 1, wn = w & 1;
;   const int fr = l & 15, fq = l >> 4;
;   uint4 ra0, ra1, ra2, ra3, rb0, rb1, rb2, rb3;
;   const int nk = K >> 6;
;   const int srow = tid >> 3, sch = tid & 7;
;   const int ssw = sch ^ ((srow >> 1) & 7);
;   const int fsw = (fr >> 1) & 7;
;     ...
;   GLOAD(0);
;   SSTORE(0);
;   GLOAD(((1 < nk) ? 1 : 0));
; DI bool next_tile(int it, int RT, int CT, int PR, int PCc, int& rt, int& ct) {
;   const int bid = lbid(), x = bid & 7, j = bid >> 3, J = lgdim() >> 3;
;   const int u = j + it * J;
;   const int pcols = CT / PCc, npatch = (RT / PR) * pcols;
;   const int pid = (u >> 6) * 8 + x;
;   if (pid >= npatch) return false;
;   const int w = u & 63, pr = pid / pcols, pc = pid - pr * pcols;
;   rt = pr * PR + w / PCc;
;   ct = pc * PCc + w % PCc;
;   return true;
; DI void phase_resgemm(const Params& p, const u16* A, int lda, const u16* W, int ldw, int K, char* smem) {
;     ...
;   for (int it = 0; next_tile(it, 128, 4, 16, 4, rt, ct); ++it) {
;     const int r0 = rt * 256, c0 = ct * 256;
;     f32x4 acc[4][8];
;     zero_acc<4, 8>(acc);
;     gemm_core<4, 8>(A + (size_t)r0 * lda, lda, W + (size_t)c0 * ldw, ldw, K, acc, smem);
.LBB0_711:
	s_mov_b32 s0, s56
	v_readlane_b32 s5, v252, 23
	s_ashr_i32 s5, s5, 3
	s_and_b32 s1, s0, 7
	s_ashr_i32 s0, s0, 3
	s_mul_i32 s5, s5, s4
	s_add_i32 s5, s5, s0
	s_ashr_i32 s0, s5, 3
	s_and_b32 s0, s0, -8
	s_or_b32 s6, s0, s1
	s_cmp_gt_i32 s6, 7
	s_mov_b64 s[0:1], -1
	s_cbranch_scc1 .LBB0_710
	s_lshl_b32 s1, s5, 6
	s_lshl_b32 s0, s6, 12
	s_and_b32 s1, s1, 0xf00
	s_or_b32 s1, s0, s1
	s_lshl_b32 s0, s5, 8
	s_and_b32 s0, s0, 0x300
	s_mul_i32 s6, s1, 0x880
	s_mul_hi_i32 s5, s1, 0x880
	s_add_u32 s6, s94, s6
	s_addc_u32 s7, s95, s5
	s_mul_i32 s5, s0, 0x880
	s_add_u32 s8, s2, s5
	v_mov_b32_e32 v34, v171
	s_addc_u32 s9, s3, 0
	v_mov_b64_e32 v[26:27], s[6:7]
	v_ashrrev_i32_e32 v35, 3, v34
	v_lshlrev_b32_e32 v36, 4, v34
	v_mov_b64_e32 v[30:31], s[8:9]
	v_add_u32_e32 v37, 64, v35
	v_add_u32_e32 v38, 0x80, v35
	v_add_u32_e32 v39, 0xc0, v35
	v_mad_i64_i32 v[2:3], s[6:7], v35, s59, v[26:27]
	v_and_b32_e32 v0, 0x70, v36
	v_mad_i64_i32 v[6:7], s[6:7], v35, s59, v[30:31]
	v_mad_i64_i32 v[10:11], s[6:7], v37, s59, v[26:27]
	v_mad_i64_i32 v[14:15], s[6:7], v37, s59, v[30:31]
	v_mad_i64_i32 v[18:19], s[6:7], v38, s59, v[26:27]
	v_mad_i64_i32 v[22:23], s[6:7], v38, s59, v[30:31]
	v_mad_i64_i32 v[26:27], s[6:7], v39, s59, v[26:27]
	v_mad_i64_i32 v[30:31], s[6:7], v39, s59, v[30:31]
	s_waitcnt vmcnt(16)
	v_lshl_add_u64 v[162:163], v[2:3], 0, v[0:1]
	v_lshl_add_u64 v[164:165], v[6:7], 0, v[0:1]
	v_lshl_add_u64 v[166:167], v[10:11], 0, v[0:1]
	v_lshl_add_u64 v[168:169], v[14:15], 0, v[0:1]
	v_lshl_add_u64 v[176:177], v[18:19], 0, v[0:1]
	v_lshl_add_u64 v[178:179], v[22:23], 0, v[0:1]
	v_lshl_add_u64 v[180:181], v[26:27], 0, v[0:1]
	s_waitcnt vmcnt(0)
	v_lshl_add_u64 v[182:183], v[30:31], 0, v[0:1]
	global_load_dwordx4 v[2:5], v[162:163], off
	global_load_dwordx4 v[6:9], v[164:165], off
	global_load_dwordx4 v[10:13], v[166:167], off
	global_load_dwordx4 v[14:17], v[168:169], off
	global_load_dwordx4 v[18:21], v[176:177], off
	global_load_dwordx4 v[22:25], v[178:179], off
	global_load_dwordx4 v[26:29], v[180:181], off
	global_load_dwordx4 v[30:33], v[182:183], off
	global_load_dwordx4 v[138:141], v[180:181], off offset:128
	global_load_dwordx4 v[130:133], v[176:177], off offset:128
	global_load_dwordx4 v[118:121], v[166:167], off offset:128
	global_load_dwordx4 v[114:117], v[162:163], off offset:128
	global_load_dwordx4 v[154:157], v[182:183], off offset:128
	global_load_dwordx4 v[142:145], v[178:179], off offset:128
	global_load_dwordx4 v[134:137], v[168:169], off offset:128
	global_load_dwordx4 v[122:125], v[164:165], off offset:128
	v_lshrrev_b32_e32 v40, 4, v34
	v_lshrrev_b32_e32 v42, 1, v34
	v_bfe_u32 v43, v34, 1, 3
	v_and_b32_e32 v44, 15, v34
	v_lshlrev_b32_e32 v45, 1, v34
	v_lshlrev_b32_e32 v0, 7, v35
	v_bitop3_b32 v173, v36, s75, v34 bitop3:0x48
	v_bfe_u32 v41, v34, 4, 2
	v_and_or_b32 v34, v42, s90, v44
	v_and_or_b32 v35, v45, s57, v44
	v_bitop3_b32 v36, v40, v43, 3 bitop3:0x6c
	v_or_b32_e32 v40, v0, v173
	v_lshlrev_b32_e32 v175, 7, v37
	v_lshlrev_b32_e32 v184, 7, v38
	v_lshlrev_b32_e32 v185, 7, v39
	v_lshlrev_b32_e32 v186, 4, v36
	v_lshlrev_b32_e32 v187, 7, v34
	v_lshlrev_b32_e32 v188, 7, v35
	v_or_b32_e32 v34, v175, v173
	v_or_b32_e32 v35, v184, v173
	v_or_b32_e32 v36, v185, v173
	s_mov_b32 s5, 0
	s_mov_b32 s6, 0
	s_waitcnt vmcnt(15)
	ds_write_b128 v40, v[2:5]
	s_waitcnt vmcnt(13)
	ds_write_b128 v34, v[10:13]
	s_waitcnt vmcnt(11)
	ds_write_b128 v35, v[18:21]
	s_waitcnt vmcnt(9)
	ds_write_b128 v36, v[26:29]
	ds_write_b128 v40, v[6:9] offset:32768
	ds_write_b128 v34, v[14:17] offset:32768
	ds_write_b128 v35, v[22:25] offset:32768
	s_waitcnt vmcnt(8)
	ds_write_b128 v36, v[30:33] offset:32768
	v_bitop3_b32 v2, v41, v43, 4 bitop3:0x36
	v_lshlrev_b32_e32 v189, 4, v2
	v_mov_b32_e32 v2, 0
	v_mov_b32_e32 v3, v2
	v_mov_b32_e32 v4, v2
	v_mov_b32_e32 v5, v2
	v_mov_b32_e32 v6, v2
	v_mov_b32_e32 v7, v2
	v_mov_b32_e32 v8, v2
	v_mov_b32_e32 v9, v2
	v_mov_b32_e32 v10, v2
	v_mov_b32_e32 v11, v2
	v_mov_b32_e32 v12, v2
	v_mov_b32_e32 v13, v2
	v_mov_b32_e32 v14, v2
	v_mov_b32_e32 v15, v2
	v_mov_b32_e32 v16, v2
	v_mov_b32_e32 v17, v2
	v_mov_b32_e32 v18, v2
	v_mov_b32_e32 v19, v2
	v_mov_b32_e32 v20, v2
	v_mov_b32_e32 v21, v2
	v_mov_b32_e32 v22, v2
	v_mov_b32_e32 v23, v2
	v_mov_b32_e32 v24, v2
	v_mov_b32_e32 v25, v2
	v_mov_b32_e32 v26, v2
	v_mov_b32_e32 v27, v2
	v_mov_b32_e32 v28, v2
	v_mov_b32_e32 v29, v2
	v_mov_b32_e32 v30, v2
	v_mov_b32_e32 v31, v2
	v_mov_b32_e32 v32, v2
	v_mov_b32_e32 v33, v2
	v_mov_b32_e32 v34, v2
	v_mov_b32_e32 v35, v2
	v_mov_b32_e32 v36, v2
	v_mov_b32_e32 v37, v2
	v_mov_b32_e32 v38, v2
	v_mov_b32_e32 v39, v2
	v_mov_b32_e32 v40, v2
	v_mov_b32_e32 v41, v2
	v_mov_b32_e32 v42, v2
	v_mov_b32_e32 v43, v2
	v_mov_b32_e32 v44, v2
	v_mov_b32_e32 v45, v2
	v_mov_b32_e32 v46, v2
	v_mov_b32_e32 v47, v2
	v_mov_b32_e32 v48, v2
	v_mov_b32_e32 v49, v2
	v_mov_b32_e32 v50, v2
	v_mov_b32_e32 v51, v2
	v_mov_b32_e32 v52, v2
	v_mov_b32_e32 v53, v2
	v_mov_b32_e32 v54, v2
	v_mov_b32_e32 v55, v2
	v_mov_b32_e32 v56, v2
	v_mov_b32_e32 v57, v2
	v_mov_b32_e32 v58, v2
	v_mov_b32_e32 v59, v2
	v_mov_b32_e32 v60, v2
	v_mov_b32_e32 v61, v2
	v_mov_b32_e32 v62, v2
	v_mov_b32_e32 v63, v2
	v_mov_b32_e32 v64, v2
	v_mov_b32_e32 v65, v2
	v_mov_b32_e32 v66, v2
	v_mov_b32_e32 v67, v2
	v_mov_b32_e32 v68, v2
	v_mov_b32_e32 v69, v2
	v_mov_b32_e32 v70, v2
	v_mov_b32_e32 v71, v2
	v_mov_b32_e32 v72, v2
	v_mov_b32_e32 v73, v2
	v_mov_b32_e32 v74, v2
	v_mov_b32_e32 v75, v2
	v_mov_b32_e32 v76, v2
	v_mov_b32_e32 v77, v2
	v_mov_b32_e32 v78, v2
	v_mov_b32_e32 v79, v2
	v_mov_b32_e32 v80, v2
	v_mov_b32_e32 v81, v2
	v_mov_b32_e32 v82, v2
	v_mov_b32_e32 v83, v2
	v_mov_b32_e32 v84, v2
	v_mov_b32_e32 v85, v2
	v_mov_b32_e32 v86, v2
	v_mov_b32_e32 v87, v2
	v_mov_b32_e32 v88, v2
	v_mov_b32_e32 v89, v2
	v_mov_b32_e32 v90, v2
	v_mov_b32_e32 v91, v2
	v_mov_b32_e32 v92, v2
	v_mov_b32_e32 v93, v2
	v_mov_b32_e32 v94, v2
	v_mov_b32_e32 v95, v2
	v_mov_b32_e32 v96, v2
	v_mov_b32_e32 v97, v2
	v_mov_b32_e32 v98, v2
	v_mov_b32_e32 v99, v2
	v_mov_b32_e32 v100, v2
	v_mov_b32_e32 v101, v2
	v_mov_b32_e32 v102, v2
	v_mov_b32_e32 v103, v2
	v_mov_b32_e32 v104, v2
	v_mov_b32_e32 v105, v2
	v_mov_b32_e32 v106, v2
	v_mov_b32_e32 v107, v2
	v_mov_b32_e32 v108, v2
	v_mov_b32_e32 v109, v2
	v_mov_b32_e32 v110, v2
	v_mov_b32_e32 v111, v2
	v_mov_b32_e32 v112, v2
	v_mov_b32_e32 v113, v2
	v_mov_b32_e32 v126, v2
	v_mov_b32_e32 v127, v2
	v_mov_b32_e32 v128, v2
	v_mov_b32_e32 v129, v2
	v_mov_b32_e32 v146, v2
	v_mov_b32_e32 v147, v2
	v_mov_b32_e32 v148, v2
	v_mov_b32_e32 v149, v2
	v_mov_b32_e32 v150, v2
	v_mov_b32_e32 v151, v2
	v_mov_b32_e32 v152, v2
	v_mov_b32_e32 v153, v2
	v_mov_b32_e32 v158, v2
	v_mov_b32_e32 v159, v2
	v_mov_b32_e32 v160, v2
	v_mov_b32_e32 v161, v2
	s_waitcnt vmcnt(0) lgkmcnt(0)
	s_barrier
; DI f32x4 mfma16(bf16x8 a, bf16x8 b, f32x4 c) { return __builtin_amdgcn_mfma_f32_16x16x32_bf16(a, b, c, 0, 0, 0); }
; #define GLOAD(kt) { GL1(0, kt) GL1(1, kt) GL1(2, kt) GL1(3, kt) }
; #define SSTORE(buf)                              \
;   {                                              \
;     char* as_ = smem + (buf) * BUF;              \
;     char* bs_ = as_ + ASZ;                       \
;     SS1(0) SS1(1) SS1(2) SS1(3)                  \
;   }
; template <int MT, int NT>
; DI void gemm_core(const u16* __restrict__ A, int lda, const u16* __restrict__ B, int ldb, int K,
;                   f32x4 (&acc)[MT][NT], char* smem) {
;     ...
;   for (int kt = 0; kt < nk; ++kt) {
;     __syncthreads();
;     SSTORE((kt + 1) & 1);
;     { const int kn_ = (kt + 2 < nk) ? kt + 2 : nk - 1; GLOAD(kn_); }
;     const char* as = smem + (kt & 1) * BUF;
;     const char* bs = as + ASZ;
; #pragma unroll
;     for (int kk = 0; kk < 2; ++kk) {
;       bf16x8 xf[MT], wf[NT];
; #pragma unroll
;       for (int mi = 0; mi < MT; ++mi)
;         xf[mi] = *(const bf16x8*)(as + (wm * (MT * 16) + mi * 16 + fr) * 128 + (((kk * 4 + fq) ^ fsw) * 16));
; #pragma unroll
;       for (int ni = 0; ni < NT; ++ni)
;         wf[ni] = *(const bf16x8*)(bs + (wn * (NT * 16) + ni * 16 + fr) * 128 + (((kk * 4 + fq) ^ fsw) * 16));
;       __builtin_amdgcn_s_setprio(1);
; #pragma unroll
;       for (int mi = 0; mi < MT; ++mi)
; #pragma unroll
;         for (int ni = 0; ni < NT; ++ni) acc[mi][ni] = mfma16(wf[ni], xf[mi], acc[mi][ni]);
	v_add_u32_e32 v207, v186, v188
	v_add_u32_e32 v206, v186, v187
	ds_read_b128 v[190:193], v206
	ds_read_b128 v[208:211], v206 offset:2048
	ds_read_b128 v[212:215], v206 offset:4096
	ds_read_b128 v[216:219], v206 offset:6144
	ds_read_b128 v[220:223], v207 offset:32768
	ds_read_b128 v[224:227], v207 offset:34816
	ds_read_b128 v[228:231], v207 offset:36864
	ds_read_b128 v[232:235], v207 offset:38912
	ds_read_b128 v[236:239], v207 offset:40960
	ds_read_b128 v[240:243], v207 offset:43008
	ds_read_b128 v[244:247], v207 offset:45056
	ds_read_b128 v[248:251], v207 offset:47104
	s_waitcnt lgkmcnt(0)
.LBB0_713:
	s_add_i32 s8, s5, 0x10000
	s_and_b32 s9, s8, 0x10000
	s_add_i32 s7, s6, 1
	s_min_u32 s6, s6, 13
	s_lshl_b32 s54, s6, 7
	s_and_b32 s5, s5, 0x10000
	v_or_b32_e32 v206, s5, v189
	v_add_u32_e32 v207, v206, v188
	v_add_u32_e32 v206, v206, v187
	v_add3_u32 v170, s9, v0, v173
	s_waitcnt lgkmcnt(10)
	v_mfma_f32_16x16x32_bf16 v[158:161], v[220:223], v[190:193], v[158:161]
	s_waitcnt vmcnt(7)
	ds_write_b128 v170, v[114:117]
	s_waitcnt lgkmcnt(10)
	v_mfma_f32_16x16x32_bf16 v[94:97], v[220:223], v[208:211], v[94:97]
	v_lshl_add_u64 v[114:115], v[162:163], 0, s[54:55]
	global_load_dwordx4 v[114:117], v[114:115], off offset:256
	s_waitcnt lgkmcnt(8)
	v_mfma_f32_16x16x32_bf16 v[62:65], v[220:223], v[212:215], v[62:65]
	s_waitcnt vmcnt(7)
	ds_write_b128 v170, v[122:125] offset:32768
	s_waitcnt lgkmcnt(3)
	v_mfma_f32_16x16x32_bf16 v[30:33], v[220:223], v[216:219], v[30:33]
	v_lshl_add_u64 v[122:123], v[164:165], 0, s[54:55]
	global_load_dwordx4 v[122:125], v[122:123], off offset:256
	ds_read_b128 v[194:197], v206
	v_mfma_f32_16x16x32_bf16 v[150:153], v[224:227], v[190:193], v[150:153]
	ds_read_b128 v[220:223], v207 offset:32768
	s_waitcnt vmcnt(7)
	ds_write_b128 v170, v[118:121] offset:8192
	v_mfma_f32_16x16x32_bf16 v[90:93], v[224:227], v[208:211], v[90:93]
	v_lshl_add_u64 v[118:119], v[166:167], 0, s[54:55]
	global_load_dwordx4 v[118:121], v[118:119], off offset:256
	v_mfma_f32_16x16x32_bf16 v[58:61], v[224:227], v[212:215], v[58:61]
	v_mfma_f32_16x16x32_bf16 v[26:29], v[224:227], v[216:219], v[26:29]
	ds_read_b128 v[198:201], v206 offset:2048
	v_mfma_f32_16x16x32_bf16 v[146:149], v[228:231], v[190:193], v[146:149]
	ds_read_b128 v[224:227], v207 offset:34816
	s_waitcnt vmcnt(7)
	ds_write_b128 v170, v[134:137] offset:40960
	v_mfma_f32_16x16x32_bf16 v[86:89], v[228:231], v[208:211], v[86:89]
	v_lshl_add_u64 v[134:135], v[168:169], 0, s[54:55]
	global_load_dwordx4 v[134:137], v[134:135], off offset:256
	v_mfma_f32_16x16x32_bf16 v[54:57], v[228:231], v[212:215], v[54:57]
	v_mfma_f32_16x16x32_bf16 v[22:25], v[228:231], v[216:219], v[22:25]
	ds_read_b128 v[202:205], v206 offset:4096
	v_mfma_f32_16x16x32_bf16 v[126:129], v[232:235], v[190:193], v[126:129]
	ds_read_b128 v[228:231], v207 offset:36864
	s_waitcnt vmcnt(7)
	ds_write_b128 v170, v[130:133] offset:16384
	v_mfma_f32_16x16x32_bf16 v[82:85], v[232:235], v[208:211], v[82:85]
	v_lshl_add_u64 v[130:131], v[176:177], 0, s[54:55]
	global_load_dwordx4 v[130:133], v[130:131], off offset:256
	v_mfma_f32_16x16x32_bf16 v[50:53], v[232:235], v[212:215], v[50:53]
	v_mfma_f32_16x16x32_bf16 v[18:21], v[232:235], v[216:219], v[18:21]
	v_mfma_f32_16x16x32_bf16 v[110:113], v[236:239], v[190:193], v[110:113]
	ds_read_b128 v[232:235], v207 offset:38912
	s_waitcnt vmcnt(7)
	ds_write_b128 v170, v[142:145] offset:49152
	v_mfma_f32_16x16x32_bf16 v[78:81], v[236:239], v[208:211], v[78:81]
	v_lshl_add_u64 v[142:143], v[178:179], 0, s[54:55]
	global_load_dwordx4 v[142:145], v[142:143], off offset:256
	v_mfma_f32_16x16x32_bf16 v[46:49], v[236:239], v[212:215], v[46:49]
	v_mfma_f32_16x16x32_bf16 v[14:17], v[236:239], v[216:219], v[14:17]
	v_mfma_f32_16x16x32_bf16 v[106:109], v[240:243], v[190:193], v[106:109]
	ds_read_b128 v[236:239], v207 offset:40960
	s_waitcnt vmcnt(7)
	ds_write_b128 v170, v[138:141] offset:24576
	v_mfma_f32_16x16x32_bf16 v[74:77], v[240:243], v[208:211], v[74:77]
	v_lshl_add_u64 v[138:139], v[180:181], 0, s[54:55]
	global_load_dwordx4 v[138:141], v[138:139], off offset:256
	v_mfma_f32_16x16x32_bf16 v[42:45], v[240:243], v[212:215], v[42:45]
	v_mfma_f32_16x16x32_bf16 v[10:13], v[240:243], v[216:219], v[10:13]
	v_mfma_f32_16x16x32_bf16 v[102:105], v[244:247], v[190:193], v[102:105]
	ds_read_b128 v[240:243], v207 offset:43008
	s_waitcnt vmcnt(7)
	ds_write_b128 v170, v[154:157] offset:57344
	v_mfma_f32_16x16x32_bf16 v[70:73], v[244:247], v[208:211], v[70:73]
	v_lshl_add_u64 v[154:155], v[182:183], 0, s[54:55]
	global_load_dwordx4 v[154:157], v[154:155], off offset:256
	v_mfma_f32_16x16x32_bf16 v[38:41], v[244:247], v[212:215], v[38:41]
	v_mfma_f32_16x16x32_bf16 v[6:9], v[244:247], v[216:219], v[6:9]
	s_waitcnt lgkmcnt(15)
	v_mfma_f32_16x16x32_bf16 v[2:5], v[248:251], v[216:219], v[2:5]
	ds_read_b128 v[244:247], v207 offset:45056
	ds_read_b128 v[216:219], v206 offset:6144
	v_mfma_f32_16x16x32_bf16 v[98:101], v[248:251], v[190:193], v[98:101]
	v_mfma_f32_16x16x32_bf16 v[66:69], v[248:251], v[208:211], v[66:69]
	v_mfma_f32_16x16x32_bf16 v[34:37], v[248:251], v[212:215], v[34:37]
	ds_read_b128 v[248:251], v207 offset:47104
	s_waitcnt lgkmcnt(3)
	s_barrier
;   __device__ __forceinline__ u16* XB() const { return (u16*)(ws + O_XB); }
; DI float bflo(u32 v) { return __uint_as_float(v << 16); }
; DI float bfhi(u32 v) { return __uint_as_float(v & 0xffff0000u); }
; DI f32x4 mfma16(bf16x8 a, bf16x8 b, f32x4 c) { return __builtin_amdgcn_mfma_f32_16x16x32_bf16(a, b, c, 0, 0, 0); }
; #define EPI_LOOP(MT_, NT_)                                                \
;   const int l_ = ltid() & 63, w_ = ltid() >> 6;                           \
;   const int wm_ = w_ >> 1, wn_ = w_ & 1, fr_ = l_ & 15, fq_ = l_ >> 4;    \
;   _Pragma("unroll") for (int mi = 0; mi < MT_; ++mi)                      \
;   _Pragma("unroll") for (int ni = 0; ni < NT_; ++ni)
; template <int MT, int NT>
; DI void gemm_core(const u16* __restrict__ A, int lda, const u16* __restrict__ B, int ldb, int K,
;                   f32x4 (&acc)[MT][NT], char* smem) {
;     ...
; #pragma unroll
;     for (int kk = 0; kk < 2; ++kk) {
;       bf16x8 xf[MT], wf[NT];
; #pragma unroll
;       for (int mi = 0; mi < MT; ++mi)
;         xf[mi] = *(const bf16x8*)(as + (wm * (MT * 16) + mi * 16 + fr) * 128 + (((kk * 4 + fq) ^ fsw) * 16));
; #pragma unroll
;       for (int ni = 0; ni < NT; ++ni)
;         wf[ni] = *(const bf16x8*)(bs + (wn * (NT * 16) + ni * 16 + fr) * 128 + (((kk * 4 + fq) ^ fsw) * 16));
;       __builtin_amdgcn_s_setprio(1);
; #pragma unroll
;       for (int mi = 0; mi < MT; ++mi)
; #pragma unroll
;         for (int ni = 0; ni < NT; ++ni) acc[mi][ni] = mfma16(wf[ni], xf[mi], acc[mi][ni]);
;       __builtin_amdgcn_s_setprio(0);
;     }
; DI void phase_resgemm(const Params& p, const u16* A, int lda, const u16* W, int ldw, int K, char* smem) {
;     ...
;     EPI_LOOP(4, 8) {
;       const int row = r0 + wm_ * 64 + mi * 16 + fr_, col = c0 + wn_ * 128 + ni * 16 + fq_ * 4;
;       const uint2 xb = *(const uint2*)(p.XB() + (size_t)row * LDX + col);
;       float4 o;
;       o.x = DN_ALPHA * bflo(xb.x) + acc[mi][ni][0]; o.y = DN_ALPHA * bfhi(xb.x) + acc[mi][ni][1];
;       o.z = DN_ALPHA * bflo(xb.y) + acc[mi][ni][2]; o.w = DN_ALPHA * bfhi(xb.y) + acc[mi][ni][3];
;       *(float4*)(p.out + (size_t)row * 1024 + col) = o;
;     }
	v_or_b32_e32 v206, s9, v186
	v_add_u32_e32 v207, v206, v188
	v_add_u32_e32 v206, v206, v187
	v_mfma_f32_16x16x32_bf16 v[158:161], v[220:223], v[194:197], v[158:161]
	v_mfma_f32_16x16x32_bf16 v[94:97], v[220:223], v[198:201], v[94:97]
	v_mfma_f32_16x16x32_bf16 v[62:65], v[220:223], v[202:205], v[62:65]
	s_waitcnt lgkmcnt(1)
	v_mfma_f32_16x16x32_bf16 v[30:33], v[220:223], v[216:219], v[30:33]
	ds_read_b128 v[190:193], v206
	v_mfma_f32_16x16x32_bf16 v[150:153], v[224:227], v[194:197], v[150:153]
	ds_read_b128 v[220:223], v207 offset:32768
	v_mfma_f32_16x16x32_bf16 v[90:93], v[224:227], v[198:201], v[90:93]
	v_mfma_f32_16x16x32_bf16 v[58:61], v[224:227], v[202:205], v[58:61]
	v_mfma_f32_16x16x32_bf16 v[26:29], v[224:227], v[216:219], v[26:29]
	ds_read_b128 v[208:211], v206 offset:2048
	v_mfma_f32_16x16x32_bf16 v[146:149], v[228:231], v[194:197], v[146:149]
	ds_read_b128 v[224:227], v207 offset:34816
	v_mfma_f32_16x16x32_bf16 v[86:89], v[228:231], v[198:201], v[86:89]
	v_mfma_f32_16x16x32_bf16 v[54:57], v[228:231], v[202:205], v[54:57]
	v_mfma_f32_16x16x32_bf16 v[22:25], v[228:231], v[216:219], v[22:25]
	ds_read_b128 v[212:215], v206 offset:4096
	v_mfma_f32_16x16x32_bf16 v[126:129], v[232:235], v[194:197], v[126:129]
	ds_read_b128 v[228:231], v207 offset:36864
	v_mfma_f32_16x16x32_bf16 v[82:85], v[232:235], v[198:201], v[82:85]
	v_mfma_f32_16x16x32_bf16 v[50:53], v[232:235], v[202:205], v[50:53]
	v_mfma_f32_16x16x32_bf16 v[18:21], v[232:235], v[216:219], v[18:21]
	v_mfma_f32_16x16x32_bf16 v[110:113], v[236:239], v[194:197], v[110:113]
	ds_read_b128 v[232:235], v207 offset:38912
	v_mfma_f32_16x16x32_bf16 v[78:81], v[236:239], v[198:201], v[78:81]
	v_mfma_f32_16x16x32_bf16 v[46:49], v[236:239], v[202:205], v[46:49]
	v_mfma_f32_16x16x32_bf16 v[14:17], v[236:239], v[216:219], v[14:17]
	v_mfma_f32_16x16x32_bf16 v[106:109], v[240:243], v[194:197], v[106:109]
	ds_read_b128 v[236:239], v207 offset:40960
	v_mfma_f32_16x16x32_bf16 v[74:77], v[240:243], v[198:201], v[74:77]
	v_mfma_f32_16x16x32_bf16 v[42:45], v[240:243], v[202:205], v[42:45]
	v_mfma_f32_16x16x32_bf16 v[10:13], v[240:243], v[216:219], v[10:13]
	v_mfma_f32_16x16x32_bf16 v[102:105], v[244:247], v[194:197], v[102:105]
	ds_read_b128 v[240:243], v207 offset:43008
	v_mfma_f32_16x16x32_bf16 v[70:73], v[244:247], v[198:201], v[70:73]
	v_mfma_f32_16x16x32_bf16 v[38:41], v[244:247], v[202:205], v[38:41]
	v_mfma_f32_16x16x32_bf16 v[6:9], v[244:247], v[216:219], v[6:9]
	s_waitcnt lgkmcnt(9)
	v_mfma_f32_16x16x32_bf16 v[2:5], v[248:251], v[216:219], v[2:5]
	ds_read_b128 v[244:247], v207 offset:45056
	ds_read_b128 v[216:219], v206 offset:6144
	v_mfma_f32_16x16x32_bf16 v[98:101], v[248:251], v[194:197], v[98:101]
	v_mfma_f32_16x16x32_bf16 v[66:69], v[248:251], v[198:201], v[66:69]
	v_mfma_f32_16x16x32_bf16 v[34:37], v[248:251], v[202:205], v[34:37]
	ds_read_b128 v[248:251], v207 offset:47104
	s_cmp_lg_u32 s7, 16
	s_mov_b32 s5, s8
	s_mov_b32 s6, s7
	s_cbranch_scc1 .LBB0_713
	s_waitcnt vmcnt(0) lgkmcnt(0)
	v_mov_b32_e32 v170, 0x358637bd
	v_mov_b32_e32 v194, 0x25a08
	v_mbcnt_lo_u32_b32 v195, -1, 0
	v_mbcnt_hi_u32_b32 v196, -1, v195
	v_mov_b32_e32 v197, 0x24000
	v_mov_b32_e32 v198, 0x1fa0
	v_mov_b32_e32 v199, 0x41b17218
	v_mov_b32_e32 v200, 0x7e800
	v_mov_b32_e32 v201, 0xfd0
	v_mov_b32_e32 v202, 0x100
	v_mov_b32_e32 v203, 0x200
	v_mov_b32_e32 v204, 0x7f61b1e6
	v_mov_b32_e32 v205, 0xff800000
	v_mov_b32_e32 v206, 0x3f80
	v_mov_b32_e32 v207, 0x1d400
	v_mov_b32_e32 v0, v171
	s_waitcnt vmcnt(7)
	v_mov_b32_e32 v115, v171
	s_barrier
	s_waitcnt vmcnt(5)
	v_mov_b64_e32 v[118:119], s[60:61]
	v_ashrrev_i32_e32 v114, 1, v115
	v_and_b32_e32 v114, 0xffffffc0, v114
	v_add_u32_e32 v114, s1, v114
	v_and_or_b32 v114, v0, 15, v114
	v_lshlrev_b32_e32 v115, 1, v115
	v_lshrrev_b32_e32 v0, 2, v0
	v_and_b32_e32 v115, 0x80, v115
	v_and_b32_e32 v0, 12, v0
	v_or3_b32 v115, v0, v115, s0
	v_mad_i64_i32 v[116:117], s[0:1], v114, s59, v[118:119]
	v_lshlrev_b32_e32 v0, 1, v115
	v_lshl_add_u64 v[124:125], v[116:117], 0, v[0:1]
	global_load_dwordx2 v[120:121], v[124:125], off
	v_lshlrev_b32_e32 v116, 2, v115
	v_ashrrev_i32_e32 v115, 31, v114
	v_lshlrev_b64 v[122:123], 12, v[114:115]
	v_mov_b32_e32 v117, v1
	v_lshl_add_u64 v[122:123], s[86:87], 0, v[122:123]
	s_waitcnt vmcnt(4)
	v_lshl_add_u64 v[130:131], v[122:123], 0, v[116:117]
	s_add_i32 s4, s4, 1
	s_waitcnt vmcnt(0)
	v_lshlrev_b32_e32 v122, 16, v120
	v_and_b32_e32 v123, 0xffff0000, v120
	v_lshlrev_b32_e32 v132, 16, v121
	v_and_b32_e32 v133, 0xffff0000, v121
	v_pk_fma_f32 v[120:121], v[122:123], s[74:75], v[158:159] op_sel_hi:[1,0,1]
	v_pk_fma_f32 v[122:123], v[132:133], s[74:75], v[160:161] op_sel_hi:[1,0,1]
	global_store_dwordx4 v[130:131], v[120:123], off
	global_load_dwordx2 v[120:121], v[124:125], off offset:32
	s_waitcnt vmcnt(0)
	v_lshlrev_b32_e32 v132, 16, v121
	v_lshlrev_b32_e32 v122, 16, v120
	v_and_b32_e32 v123, 0xffff0000, v120
	v_and_b32_e32 v133, 0xffff0000, v121
	v_pk_fma_f32 v[120:121], v[122:123], s[74:75], v[150:151] op_sel_hi:[1,0,1]
	v_pk_fma_f32 v[122:123], v[132:133], s[74:75], v[152:153] op_sel_hi:[1,0,1]
	global_store_dwordx4 v[130:131], v[120:123], off offset:64
	global_load_dwordx2 v[120:121], v[124:125], off offset:64
	s_waitcnt vmcnt(0)
	v_lshlrev_b32_e32 v132, 16, v121
	v_lshlrev_b32_e32 v122, 16, v120
	v_and_b32_e32 v123, 0xffff0000, v120
	v_and_b32_e32 v133, 0xffff0000, v121
	v_pk_fma_f32 v[120:121], v[122:123], s[74:75], v[146:147] op_sel_hi:[1,0,1]
	v_pk_fma_f32 v[122:123], v[132:133], s[74:75], v[148:149] op_sel_hi:[1,0,1]
	global_store_dwordx4 v[130:131], v[120:123], off offset:128
	global_load_dwordx2 v[120:121], v[124:125], off offset:96
	s_waitcnt vmcnt(0)
;   __device__ __forceinline__ u16* XB() const { return (u16*)(ws + O_XB); }
; DI float bflo(u32 v) { return __uint_as_float(v << 16); }
; DI float bfhi(u32 v) { return __uint_as_float(v & 0xffff0000u); }
; #define EPI_LOOP(MT_, NT_)                                                \
;   const int l_ = ltid() & 63, w_ = ltid() >> 6;                           \
;   const int wm_ = w_ >> 1, wn_ = w_ & 1, fr_ = l_ & 15, fq_ = l_ >> 4;    \
;   _Pragma("unroll") for (int mi = 0; mi < MT_; ++mi)                      \
;   _Pragma("unroll") for (int ni = 0; ni < NT_; ++ni)
; DI void phase_resgemm(const Params& p, const u16* A, int lda, const u16* W, int ldw, int K, char* smem) {
;     ...
;     EPI_LOOP(4, 8) {
;       const int row = r0 + wm_ * 64 + mi * 16 + fr_, col = c0 + wn_ * 128 + ni * 16 + fq_ * 4;
;       const uint2 xb = *(const uint2*)(p.XB() + (size_t)row * LDX + col);
;       float4 o;
;       o.x = DN_ALPHA * bflo(xb.x) + acc[mi][ni][0]; o.y = DN_ALPHA * bfhi(xb.x) + acc[mi][ni][1];
;       o.z = DN_ALPHA * bflo(xb.y) + acc[mi][ni][2]; o.w = DN_ALPHA * bfhi(xb.y) + acc[mi][ni][3];
;       *(float4*)(p.out + (size_t)row * 1024 + col) = o;
;     }
	v_lshlrev_b32_e32 v132, 16, v121
	v_lshlrev_b32_e32 v122, 16, v120
	v_and_b32_e32 v123, 0xffff0000, v120
	v_and_b32_e32 v133, 0xffff0000, v121
	v_pk_fma_f32 v[120:121], v[122:123], s[74:75], v[126:127] op_sel_hi:[1,0,1]
	v_pk_fma_f32 v[122:123], v[132:133], s[74:75], v[128:129] op_sel_hi:[1,0,1]
	global_store_dwordx4 v[130:131], v[120:123], off offset:192
	global_load_dwordx2 v[120:121], v[124:125], off offset:128
	s_waitcnt vmcnt(0)
	v_lshlrev_b32_e32 v122, 16, v120
	v_and_b32_e32 v123, 0xffff0000, v120
	v_lshlrev_b32_e32 v120, 16, v121
	v_and_b32_e32 v121, 0xffff0000, v121
	v_pk_fma_f32 v[110:111], v[122:123], s[74:75], v[110:111] op_sel_hi:[1,0,1]
	v_pk_fma_f32 v[112:113], v[120:121], s[74:75], v[112:113] op_sel_hi:[1,0,1]
	global_store_dwordx4 v[130:131], v[110:113], off offset:256
	global_load_dwordx2 v[110:111], v[124:125], off offset:160
	s_waitcnt vmcnt(0)
	v_lshlrev_b32_e32 v112, 16, v110
	v_and_b32_e32 v113, 0xffff0000, v110
	v_lshlrev_b32_e32 v110, 16, v111
	v_and_b32_e32 v111, 0xffff0000, v111
	v_pk_fma_f32 v[106:107], v[112:113], s[74:75], v[106:107] op_sel_hi:[1,0,1]
	v_pk_fma_f32 v[108:109], v[110:111], s[74:75], v[108:109] op_sel_hi:[1,0,1]
	global_store_dwordx4 v[130:131], v[106:109], off offset:320
	global_load_dwordx2 v[106:107], v[124:125], off offset:192
	s_waitcnt vmcnt(0)
	v_lshlrev_b32_e32 v108, 16, v106
	v_and_b32_e32 v109, 0xffff0000, v106
	v_lshlrev_b32_e32 v106, 16, v107
	v_and_b32_e32 v107, 0xffff0000, v107
	v_pk_fma_f32 v[102:103], v[108:109], s[74:75], v[102:103] op_sel_hi:[1,0,1]
	v_pk_fma_f32 v[104:105], v[106:107], s[74:75], v[104:105] op_sel_hi:[1,0,1]
	global_store_dwordx4 v[130:131], v[102:105], off offset:384
	global_load_dwordx2 v[102:103], v[124:125], off offset:224
	s_waitcnt vmcnt(0)
	v_lshlrev_b32_e32 v108, 16, v102
	v_or_b32_e32 v104, 16, v114
	v_and_b32_e32 v109, 0xffff0000, v102
	v_lshlrev_b32_e32 v102, 16, v103
	v_and_b32_e32 v103, 0xffff0000, v103
	v_mad_i64_i32 v[106:107], s[0:1], v104, s59, v[118:119]
	v_pk_fma_f32 v[98:99], v[108:109], s[74:75], v[98:99] op_sel_hi:[1,0,1]
	v_pk_fma_f32 v[100:101], v[102:103], s[74:75], v[100:101] op_sel_hi:[1,0,1]
	v_lshl_add_u64 v[106:107], v[106:107], 0, v[0:1]
	global_store_dwordx4 v[130:131], v[98:101], off offset:448
	global_load_dwordx2 v[98:99], v[106:107], off
	v_ashrrev_i32_e32 v105, 31, v104
	v_lshlrev_b64 v[100:101], 12, v[104:105]
	v_lshl_add_u64 v[100:101], s[86:87], 0, v[100:101]
	v_lshl_add_u64 v[100:101], v[100:101], 0, v[116:117]
	s_waitcnt vmcnt(0)
	v_lshlrev_b32_e32 v102, 16, v98
	v_and_b32_e32 v103, 0xffff0000, v98
	v_lshlrev_b32_e32 v98, 16, v99
	v_and_b32_e32 v99, 0xffff0000, v99
	v_pk_fma_f32 v[94:95], v[102:103], s[74:75], v[94:95] op_sel_hi:[1,0,1]
	v_pk_fma_f32 v[96:97], v[98:99], s[74:75], v[96:97] op_sel_hi:[1,0,1]
	global_store_dwordx4 v[100:101], v[94:97], off
	global_load_dwordx2 v[94:95], v[106:107], off offset:32
	s_waitcnt vmcnt(0)
	v_lshlrev_b32_e32 v96, 16, v94
	v_and_b32_e32 v97, 0xffff0000, v94
	v_lshlrev_b32_e32 v94, 16, v95
	v_and_b32_e32 v95, 0xffff0000, v95
	v_pk_fma_f32 v[90:91], v[96:97], s[74:75], v[90:91] op_sel_hi:[1,0,1]
	v_pk_fma_f32 v[92:93], v[94:95], s[74:75], v[92:93] op_sel_hi:[1,0,1]
	global_store_dwordx4 v[100:101], v[90:93], off offset:64
	global_load_dwordx2 v[90:91], v[106:107], off offset:64
	s_waitcnt vmcnt(0)
	v_lshlrev_b32_e32 v92, 16, v90
	v_and_b32_e32 v93, 0xffff0000, v90
	v_lshlrev_b32_e32 v90, 16, v91
	v_and_b32_e32 v91, 0xffff0000, v91
	v_pk_fma_f32 v[86:87], v[92:93], s[74:75], v[86:87] op_sel_hi:[1,0,1]
	v_pk_fma_f32 v[88:89], v[90:91], s[74:75], v[88:89] op_sel_hi:[1,0,1]
	global_store_dwordx4 v[100:101], v[86:89], off offset:128
	global_load_dwordx2 v[86:87], v[106:107], off offset:96
	s_waitcnt vmcnt(0)
	v_lshlrev_b32_e32 v88, 16, v86
	v_and_b32_e32 v89, 0xffff0000, v86
	v_lshlrev_b32_e32 v86, 16, v87
	v_and_b32_e32 v87, 0xffff0000, v87
	v_pk_fma_f32 v[82:83], v[88:89], s[74:75], v[82:83] op_sel_hi:[1,0,1]
	v_pk_fma_f32 v[84:85], v[86:87], s[74:75], v[84:85] op_sel_hi:[1,0,1]
	global_store_dwordx4 v[100:101], v[82:85], off offset:192
	global_load_dwordx2 v[82:83], v[106:107], off offset:128
	s_waitcnt vmcnt(0)
	v_lshlrev_b32_e32 v84, 16, v82
	v_and_b32_e32 v85, 0xffff0000, v82
	v_lshlrev_b32_e32 v82, 16, v83
	v_and_b32_e32 v83, 0xffff0000, v83
	v_pk_fma_f32 v[78:79], v[84:85], s[74:75], v[78:79] op_sel_hi:[1,0,1]
	v_pk_fma_f32 v[80:81], v[82:83], s[74:75], v[80:81] op_sel_hi:[1,0,1]
	global_store_dwordx4 v[100:101], v[78:81], off offset:256
	global_load_dwordx2 v[78:79], v[106:107], off offset:160
	s_waitcnt vmcnt(0)
	v_lshlrev_b32_e32 v80, 16, v78
	v_and_b32_e32 v81, 0xffff0000, v78
	v_lshlrev_b32_e32 v78, 16, v79
	v_and_b32_e32 v79, 0xffff0000, v79
	v_pk_fma_f32 v[74:75], v[80:81], s[74:75], v[74:75] op_sel_hi:[1,0,1]
	v_pk_fma_f32 v[76:77], v[78:79], s[74:75], v[76:77] op_sel_hi:[1,0,1]
	global_store_dwordx4 v[100:101], v[74:77], off offset:320
	global_load_dwordx2 v[74:75], v[106:107], off offset:192
	s_waitcnt vmcnt(0)
	v_lshlrev_b32_e32 v76, 16, v74
	v_and_b32_e32 v77, 0xffff0000, v74
	v_lshlrev_b32_e32 v74, 16, v75
	v_and_b32_e32 v75, 0xffff0000, v75
	v_pk_fma_f32 v[70:71], v[76:77], s[74:75], v[70:71] op_sel_hi:[1,0,1]
	v_pk_fma_f32 v[72:73], v[74:75], s[74:75], v[72:73] op_sel_hi:[1,0,1]
	global_store_dwordx4 v[100:101], v[70:73], off offset:384
	global_load_dwordx2 v[70:71], v[106:107], off offset:224
	s_waitcnt vmcnt(0)
;   __device__ __forceinline__ u16* XB() const { return (u16*)(ws + O_XB); }
; DI float bflo(u32 v) { return __uint_as_float(v << 16); }
; DI float bfhi(u32 v) { return __uint_as_float(v & 0xffff0000u); }
; #define EPI_LOOP(MT_, NT_)                                                \
;   const int l_ = ltid() & 63, w_ = ltid() >> 6;                           \
;   const int wm_ = w_ >> 1, wn_ = w_ & 1, fr_ = l_ & 15, fq_ = l_ >> 4;    \
;   _Pragma("unroll") for (int mi = 0; mi < MT_; ++mi)                      \
;   _Pragma("unroll") for (int ni = 0; ni < NT_; ++ni)
; DI void phase_resgemm(const Params& p, const u16* A, int lda, const u16* W, int ldw, int K, char* smem) {
;     ...
;     EPI_LOOP(4, 8) {
;       const int row = r0 + wm_ * 64 + mi * 16 + fr_, col = c0 + wn_ * 128 + ni * 16 + fq_ * 4;
;       const uint2 xb = *(const uint2*)(p.XB() + (size_t)row * LDX + col);
;       float4 o;
;       o.x = DN_ALPHA * bflo(xb.x) + acc[mi][ni][0]; o.y = DN_ALPHA * bfhi(xb.x) + acc[mi][ni][1];
;       o.z = DN_ALPHA * bflo(xb.y) + acc[mi][ni][2]; o.w = DN_ALPHA * bfhi(xb.y) + acc[mi][ni][3];
;       *(float4*)(p.out + (size_t)row * 1024 + col) = o;
;     }
	v_lshlrev_b32_e32 v76, 16, v70
	v_or_b32_e32 v72, 32, v114
	v_and_b32_e32 v77, 0xffff0000, v70
	v_lshlrev_b32_e32 v70, 16, v71
	v_and_b32_e32 v71, 0xffff0000, v71
	v_mad_i64_i32 v[74:75], s[0:1], v72, s59, v[118:119]
	v_pk_fma_f32 v[66:67], v[76:77], s[74:75], v[66:67] op_sel_hi:[1,0,1]
	v_pk_fma_f32 v[68:69], v[70:71], s[74:75], v[68:69] op_sel_hi:[1,0,1]
	v_lshl_add_u64 v[74:75], v[74:75], 0, v[0:1]
	global_store_dwordx4 v[100:101], v[66:69], off offset:448
	global_load_dwordx2 v[66:67], v[74:75], off
	v_ashrrev_i32_e32 v73, 31, v72
	v_lshlrev_b64 v[68:69], 12, v[72:73]
	v_lshl_add_u64 v[68:69], s[86:87], 0, v[68:69]
	v_lshl_add_u64 v[68:69], v[68:69], 0, v[116:117]
	s_waitcnt vmcnt(0)
	v_lshlrev_b32_e32 v70, 16, v66
	v_and_b32_e32 v71, 0xffff0000, v66
	v_lshlrev_b32_e32 v66, 16, v67
	v_and_b32_e32 v67, 0xffff0000, v67
	v_pk_fma_f32 v[62:63], v[70:71], s[74:75], v[62:63] op_sel_hi:[1,0,1]
	v_pk_fma_f32 v[64:65], v[66:67], s[74:75], v[64:65] op_sel_hi:[1,0,1]
	global_store_dwordx4 v[68:69], v[62:65], off
	global_load_dwordx2 v[62:63], v[74:75], off offset:32
	s_waitcnt vmcnt(0)
	v_lshlrev_b32_e32 v64, 16, v62
	v_and_b32_e32 v65, 0xffff0000, v62
	v_lshlrev_b32_e32 v62, 16, v63
	v_and_b32_e32 v63, 0xffff0000, v63
	v_pk_fma_f32 v[58:59], v[64:65], s[74:75], v[58:59] op_sel_hi:[1,0,1]
	v_pk_fma_f32 v[60:61], v[62:63], s[74:75], v[60:61] op_sel_hi:[1,0,1]
	global_store_dwordx4 v[68:69], v[58:61], off offset:64
	global_load_dwordx2 v[58:59], v[74:75], off offset:64
	s_waitcnt vmcnt(0)
	v_lshlrev_b32_e32 v60, 16, v58
	v_and_b32_e32 v61, 0xffff0000, v58
	v_lshlrev_b32_e32 v58, 16, v59
	v_and_b32_e32 v59, 0xffff0000, v59
	v_pk_fma_f32 v[54:55], v[60:61], s[74:75], v[54:55] op_sel_hi:[1,0,1]
	v_pk_fma_f32 v[56:57], v[58:59], s[74:75], v[56:57] op_sel_hi:[1,0,1]
	global_store_dwordx4 v[68:69], v[54:57], off offset:128
	global_load_dwordx2 v[54:55], v[74:75], off offset:96
	s_waitcnt vmcnt(0)
	v_lshlrev_b32_e32 v56, 16, v54
	v_and_b32_e32 v57, 0xffff0000, v54
	v_lshlrev_b32_e32 v54, 16, v55
	v_and_b32_e32 v55, 0xffff0000, v55
	v_pk_fma_f32 v[50:51], v[56:57], s[74:75], v[50:51] op_sel_hi:[1,0,1]
	v_pk_fma_f32 v[52:53], v[54:55], s[74:75], v[52:53] op_sel_hi:[1,0,1]
	global_store_dwordx4 v[68:69], v[50:53], off offset:192
	global_load_dwordx2 v[50:51], v[74:75], off offset:128
	s_waitcnt vmcnt(0)
	v_lshlrev_b32_e32 v52, 16, v50
	v_and_b32_e32 v53, 0xffff0000, v50
	v_lshlrev_b32_e32 v50, 16, v51
	v_and_b32_e32 v51, 0xffff0000, v51
	v_pk_fma_f32 v[46:47], v[52:53], s[74:75], v[46:47] op_sel_hi:[1,0,1]
	v_pk_fma_f32 v[48:49], v[50:51], s[74:75], v[48:49] op_sel_hi:[1,0,1]
	global_store_dwordx4 v[68:69], v[46:49], off offset:256
	global_load_dwordx2 v[46:47], v[74:75], off offset:160
	s_waitcnt vmcnt(0)
	v_lshlrev_b32_e32 v48, 16, v46
	v_and_b32_e32 v49, 0xffff0000, v46
	v_lshlrev_b32_e32 v46, 16, v47
	v_and_b32_e32 v47, 0xffff0000, v47
	v_pk_fma_f32 v[42:43], v[48:49], s[74:75], v[42:43] op_sel_hi:[1,0,1]
	v_pk_fma_f32 v[44:45], v[46:47], s[74:75], v[44:45] op_sel_hi:[1,0,1]
	global_store_dwordx4 v[68:69], v[42:45], off offset:320
	global_load_dwordx2 v[42:43], v[74:75], off offset:192
	s_waitcnt vmcnt(0)
	v_lshlrev_b32_e32 v44, 16, v42
	v_and_b32_e32 v45, 0xffff0000, v42
	v_lshlrev_b32_e32 v42, 16, v43
	v_and_b32_e32 v43, 0xffff0000, v43
	v_pk_fma_f32 v[38:39], v[44:45], s[74:75], v[38:39] op_sel_hi:[1,0,1]
	v_pk_fma_f32 v[40:41], v[42:43], s[74:75], v[40:41] op_sel_hi:[1,0,1]
	global_store_dwordx4 v[68:69], v[38:41], off offset:384
	global_load_dwordx2 v[38:39], v[74:75], off offset:224
	s_waitcnt vmcnt(0)
;   __device__ __forceinline__ u16* XB() const { return (u16*)(ws + O_XB); }
; DI float bflo(u32 v) { return __uint_as_float(v << 16); }
; DI float bfhi(u32 v) { return __uint_as_float(v & 0xffff0000u); }
; #define EPI_LOOP(MT_, NT_)                                                \
;   const int l_ = ltid() & 63, w_ = ltid() >> 6;                           \
;   const int wm_ = w_ >> 1, wn_ = w_ & 1, fr_ = l_ & 15, fq_ = l_ >> 4;    \
;   _Pragma("unroll") for (int mi = 0; mi < MT_; ++mi)                      \
;   _Pragma("unroll") for (int ni = 0; ni < NT_; ++ni)
; DI void phase_resgemm(const Params& p, const u16* A, int lda, const u16* W, int ldw, int K, char* smem) {
;     ...
;     EPI_LOOP(4, 8) {
;       const int row = r0 + wm_ * 64 + mi * 16 + fr_, col = c0 + wn_ * 128 + ni * 16 + fq_ * 4;
;       const uint2 xb = *(const uint2*)(p.XB() + (size_t)row * LDX + col);
;       float4 o;
;       o.x = DN_ALPHA * bflo(xb.x) + acc[mi][ni][0]; o.y = DN_ALPHA * bfhi(xb.x) + acc[mi][ni][1];
;       o.z = DN_ALPHA * bflo(xb.y) + acc[mi][ni][2]; o.w = DN_ALPHA * bfhi(xb.y) + acc[mi][ni][3];
;       *(float4*)(p.out + (size_t)row * 1024 + col) = o;
;     }
	v_lshlrev_b32_e32 v44, 16, v38
	v_or_b32_e32 v40, 48, v114
	v_and_b32_e32 v45, 0xffff0000, v38
	v_lshlrev_b32_e32 v38, 16, v39
	v_and_b32_e32 v39, 0xffff0000, v39
	v_mad_i64_i32 v[42:43], s[0:1], v40, s59, v[118:119]
	v_pk_fma_f32 v[34:35], v[44:45], s[74:75], v[34:35] op_sel_hi:[1,0,1]
	v_pk_fma_f32 v[36:37], v[38:39], s[74:75], v[36:37] op_sel_hi:[1,0,1]
	v_lshl_add_u64 v[42:43], v[42:43], 0, v[0:1]
	global_store_dwordx4 v[68:69], v[34:37], off offset:448
	global_load_dwordx2 v[34:35], v[42:43], off
	v_ashrrev_i32_e32 v41, 31, v40
	v_lshlrev_b64 v[36:37], 12, v[40:41]
	v_lshl_add_u64 v[36:37], s[86:87], 0, v[36:37]
	v_lshl_add_u64 v[36:37], v[36:37], 0, v[116:117]
	s_mov_b64 s[0:1], 0
	s_waitcnt vmcnt(0)
	v_lshlrev_b32_e32 v38, 16, v34
	v_and_b32_e32 v39, 0xffff0000, v34
	v_lshlrev_b32_e32 v34, 16, v35
	v_and_b32_e32 v35, 0xffff0000, v35
	v_pk_fma_f32 v[30:31], v[38:39], s[74:75], v[30:31] op_sel_hi:[1,0,1]
	v_pk_fma_f32 v[32:33], v[34:35], s[74:75], v[32:33] op_sel_hi:[1,0,1]
	global_store_dwordx4 v[36:37], v[30:33], off
	global_load_dwordx2 v[30:31], v[42:43], off offset:32
	s_waitcnt vmcnt(0)
	v_lshlrev_b32_e32 v32, 16, v30
	v_and_b32_e32 v33, 0xffff0000, v30
	v_lshlrev_b32_e32 v30, 16, v31
	v_and_b32_e32 v31, 0xffff0000, v31
	v_pk_fma_f32 v[26:27], v[32:33], s[74:75], v[26:27] op_sel_hi:[1,0,1]
	v_pk_fma_f32 v[28:29], v[30:31], s[74:75], v[28:29] op_sel_hi:[1,0,1]
	global_store_dwordx4 v[36:37], v[26:29], off offset:64
	global_load_dwordx2 v[26:27], v[42:43], off offset:64
	s_waitcnt vmcnt(0)
	v_lshlrev_b32_e32 v28, 16, v26
	v_and_b32_e32 v29, 0xffff0000, v26
	v_lshlrev_b32_e32 v26, 16, v27
	v_and_b32_e32 v27, 0xffff0000, v27
	v_pk_fma_f32 v[22:23], v[28:29], s[74:75], v[22:23] op_sel_hi:[1,0,1]
	v_pk_fma_f32 v[24:25], v[26:27], s[74:75], v[24:25] op_sel_hi:[1,0,1]
	global_store_dwordx4 v[36:37], v[22:25], off offset:128
	global_load_dwordx2 v[22:23], v[42:43], off offset:96
	s_waitcnt vmcnt(0)
	v_lshlrev_b32_e32 v24, 16, v22
	v_and_b32_e32 v25, 0xffff0000, v22
	v_lshlrev_b32_e32 v22, 16, v23
	v_and_b32_e32 v23, 0xffff0000, v23
	v_pk_fma_f32 v[18:19], v[24:25], s[74:75], v[18:19] op_sel_hi:[1,0,1]
	v_pk_fma_f32 v[20:21], v[22:23], s[74:75], v[20:21] op_sel_hi:[1,0,1]
	global_store_dwordx4 v[36:37], v[18:21], off offset:192
	global_load_dwordx2 v[18:19], v[42:43], off offset:128
	s_waitcnt vmcnt(0)
	v_lshlrev_b32_e32 v20, 16, v18
	v_and_b32_e32 v21, 0xffff0000, v18
	v_lshlrev_b32_e32 v18, 16, v19
	v_and_b32_e32 v19, 0xffff0000, v19
	v_pk_fma_f32 v[14:15], v[20:21], s[74:75], v[14:15] op_sel_hi:[1,0,1]
	v_pk_fma_f32 v[16:17], v[18:19], s[74:75], v[16:17] op_sel_hi:[1,0,1]
	global_store_dwordx4 v[36:37], v[14:17], off offset:256
	global_load_dwordx2 v[14:15], v[42:43], off offset:160
	s_waitcnt vmcnt(0)
	v_lshlrev_b32_e32 v16, 16, v14
	v_and_b32_e32 v17, 0xffff0000, v14
	v_lshlrev_b32_e32 v14, 16, v15
	v_and_b32_e32 v15, 0xffff0000, v15
	v_pk_fma_f32 v[10:11], v[16:17], s[74:75], v[10:11] op_sel_hi:[1,0,1]
	v_pk_fma_f32 v[12:13], v[14:15], s[74:75], v[12:13] op_sel_hi:[1,0,1]
	global_store_dwordx4 v[36:37], v[10:13], off offset:320
	global_load_dwordx2 v[10:11], v[42:43], off offset:192
	s_waitcnt vmcnt(0)
	v_lshlrev_b32_e32 v12, 16, v10
	v_and_b32_e32 v13, 0xffff0000, v10
	v_lshlrev_b32_e32 v10, 16, v11
	v_and_b32_e32 v11, 0xffff0000, v11
	v_pk_fma_f32 v[6:7], v[12:13], s[74:75], v[6:7] op_sel_hi:[1,0,1]
	v_pk_fma_f32 v[8:9], v[10:11], s[74:75], v[8:9] op_sel_hi:[1,0,1]
	global_store_dwordx4 v[36:37], v[6:9], off offset:384
	global_load_dwordx2 v[6:7], v[42:43], off offset:224
	s_waitcnt vmcnt(0)
	v_lshlrev_b32_e32 v8, 16, v6
	v_and_b32_e32 v9, 0xffff0000, v6
	v_lshlrev_b32_e32 v6, 16, v7
	v_and_b32_e32 v7, 0xffff0000, v7
	v_pk_fma_f32 v[2:3], v[8:9], s[74:75], v[2:3] op_sel_hi:[1,0,1]
	v_pk_fma_f32 v[4:5], v[6:7], s[74:75], v[4:5] op_sel_hi:[1,0,1]
	global_store_dwordx4 v[36:37], v[2:5], off offset:448
	s_branch .LBB0_710

;   __device__ __forceinline__ u16* wf1(int l) const { return (u16*)(ws + l * LAYER_W + O_WF1); }
;   __device__ __forceinline__ u16* XB() const { return (u16*)(ws + O_XB); }
; DI int lbid() { int b = blockIdx.x; asm volatile("" : "+s"(b)); return b; }
; DI int lgdim() { int b = gridDim.x; asm volatile("" : "+s"(b)); return b; }
; DI int ltid() { int t = threadIdx.x; asm volatile("" : "+v"(t)); return t; }
; #define GLOAD(kt) { GL1(0, kt) GL1(1, kt) GL1(2, kt) GL1(3, kt) }
; #define SSTORE(buf)                              \
;   {                                              \
;     char* as_ = smem + (buf) * BUF;              \
;     char* bs_ = as_ + ASZ;                       \
;     SS1(0) SS1(1) SS1(2) SS1(3)                  \
;   }
; template <int MT, int NT>
; DI void gemm_core(const u16* __restrict__ A, int lda, const u16* __restrict__ B, int ldb, int K,
;                   f32x4 (&acc)[MT][NT], char* smem) {
;   constexpr int BM = 64 * MT, BN = 32 * NT;
;   constexpr int ASZ = BM * 128, BSZ = BN * 128, BUF = ASZ + BSZ;
;   constexpr int NA = BM / 64, NB = BN / 64;
;   const int tid = ltid(), l = tid & 63, w = tid >> 6, wm = w >> 1, wn = w & 1;
;   const int fr = l & 15, fq = l >> 4;
;   uint4 ra0, ra1, ra2, ra3, rb0, rb1, rb2, rb3;
;   const int nk = K >> 6;
;   const int srow = tid >> 3, sch = tid & 7;
;   const int ssw = sch ^ ((srow >> 1) & 7);
;   const int fsw = (fr >> 1) & 7;
;     ...
;   GLOAD(0);
;   SSTORE(0);
;   GLOAD(((1 < nk) ? 1 : 0));
; DI bool next_tile(int it, int RT, int CT, int PR, int PCc, int& rt, int& ct) {
;   const int bid = lbid(), x = bid & 7, j = bid >> 3, J = lgdim() >> 3;
;   const int u = j + it * J;
;   const int pcols = CT / PCc, npatch = (RT / PR) * pcols;
;   const int pid = (u >> 6) * 8 + x;
;   if (pid >= npatch) return false;
;   const int w = u & 63, pr = pid / pcols, pc = pid - pr * pcols;
;   rt = pr * PR + w / PCc;
;   ct = pc * PCc + w % PCc;
;   return true;
; DI void phase_ff1(const Params& p, int l, char* smem) {
;     ...
;   for (int it = 0; next_tile(it, 128, 16, 8, 8, rt, ct); ++it) {
;     const int r0 = rt * 256, c0 = ct * 256;
;     f32x4 acc[4][8];
;     zero_acc<4, 8>(acc);
;     gemm_core<4, 8>(p.XB() + (size_t)r0 * LDX, LDX, p.wf1(l) + (size_t)c0 * KP1024, KP1024, 1024, acc, smem);
.LBB0_766:
	s_mov_b32 s0, s56
	v_readlane_b32 s5, v252, 23
	s_ashr_i32 s5, s5, 3
	s_and_b32 s1, s0, 7
	s_ashr_i32 s0, s0, 3
	s_mul_i32 s5, s5, s4
	s_add_i32 s5, s5, s0
	s_ashr_i32 s0, s5, 3
	s_and_b32 s0, s0, -8
	s_or_b32 s6, s0, s1
	s_cmp_gt_i32 s6, 31
	s_mov_b64 s[0:1], -1
	s_cbranch_scc1 .LBB0_765
	s_lshr_b32 s0, s6, 31
	s_add_i32 s0, s6, s0
	s_ashr_i32 s0, s0, 1
	s_lshl_b32 s1, s0, 4
	s_lshl_b32 s6, s6, 3
	s_sub_i32 s1, s6, s1
	s_and_b32 s6, s5, 7
	s_or_b32 s8, s1, s6
	s_lshl_b32 s1, s5, 5
	s_lshl_b32 s0, s0, 11
	s_and_b32 s1, s1, 0x700
	s_or_b32 s1, s0, s1
	s_lshl_b32 s0, s8, 8
	s_mul_i32 s6, s1, 0x880
	s_mul_hi_i32 s5, s1, 0x880
	s_add_u32 s6, s60, s6
	s_addc_u32 s7, s61, s5
	s_mul_i32 s8, s8, 0x88000
	s_mul_hi_i32 s5, s0, 0x880
	s_add_u32 s8, s2, s8
	v_mov_b32_e32 v34, v171
	s_addc_u32 s9, s3, s5
	v_mov_b64_e32 v[26:27], s[6:7]
	v_ashrrev_i32_e32 v35, 3, v34
	v_lshlrev_b32_e32 v36, 4, v34
	v_mov_b64_e32 v[30:31], s[8:9]
	v_add_u32_e32 v37, 64, v35
	v_add_u32_e32 v38, 0x80, v35
	v_add_u32_e32 v39, 0xc0, v35
	v_mad_i64_i32 v[2:3], s[6:7], v35, s59, v[26:27]
	v_and_b32_e32 v0, 0x70, v36
	v_mad_i64_i32 v[6:7], s[6:7], v35, s59, v[30:31]
	v_mad_i64_i32 v[10:11], s[6:7], v37, s59, v[26:27]
	v_mad_i64_i32 v[14:15], s[6:7], v37, s59, v[30:31]
	v_mad_i64_i32 v[18:19], s[6:7], v38, s59, v[26:27]
	v_mad_i64_i32 v[22:23], s[6:7], v38, s59, v[30:31]
	v_mad_i64_i32 v[26:27], s[6:7], v39, s59, v[26:27]
	v_mad_i64_i32 v[30:31], s[6:7], v39, s59, v[30:31]
	s_waitcnt vmcnt(16)
	v_lshl_add_u64 v[162:163], v[2:3], 0, v[0:1]
	v_lshl_add_u64 v[164:165], v[6:7], 0, v[0:1]
	v_lshl_add_u64 v[166:167], v[10:11], 0, v[0:1]
	v_lshl_add_u64 v[168:169], v[14:15], 0, v[0:1]
	v_lshl_add_u64 v[176:177], v[18:19], 0, v[0:1]
	v_lshl_add_u64 v[178:179], v[22:23], 0, v[0:1]
	v_lshl_add_u64 v[180:181], v[26:27], 0, v[0:1]
	s_waitcnt vmcnt(0)
	v_lshl_add_u64 v[182:183], v[30:31], 0, v[0:1]
	global_load_dwordx4 v[2:5], v[162:163], off
	global_load_dwordx4 v[6:9], v[164:165], off
	global_load_dwordx4 v[10:13], v[166:167], off
	global_load_dwordx4 v[14:17], v[168:169], off
	global_load_dwordx4 v[18:21], v[176:177], off
	global_load_dwordx4 v[22:25], v[178:179], off
	global_load_dwordx4 v[26:29], v[180:181], off
	global_load_dwordx4 v[30:33], v[182:183], off
	global_load_dwordx4 v[130:133], v[180:181], off offset:128
	global_load_dwordx4 v[122:125], v[176:177], off offset:128
	global_load_dwordx4 v[114:117], v[166:167], off offset:128
	global_load_dwordx4 v[110:113], v[162:163], off offset:128
	global_load_dwordx4 v[150:153], v[182:183], off offset:128
	global_load_dwordx4 v[134:137], v[178:179], off offset:128
	global_load_dwordx4 v[126:129], v[168:169], off offset:128
	global_load_dwordx4 v[118:121], v[164:165], off offset:128
	v_lshlrev_b32_e32 v0, 7, v35
	v_bitop3_b32 v173, v36, s75, v34 bitop3:0x48
	v_and_b32_e32 v44, 15, v34
	v_lshlrev_b32_e32 v45, 1, v34
	v_or_b32_e32 v35, v0, v173
	v_lshlrev_b32_e32 v175, 7, v37
	v_lshlrev_b32_e32 v184, 7, v38
	v_lshlrev_b32_e32 v185, 7, v39
	v_bfe_u32 v41, v34, 4, 2
	v_bfe_u32 v43, v34, 1, 3
	v_or_b32_e32 v36, v175, v173
	v_or_b32_e32 v37, v184, v173
	v_or_b32_e32 v38, v185, v173
	v_lshrrev_b32_e32 v40, 4, v34
	v_lshrrev_b32_e32 v42, 1, v34
	v_and_or_b32 v34, v42, s90, v44
	v_lshlrev_b32_e32 v187, 7, v34
	s_mov_b32 s5, 0
	s_mov_b32 s6, 0
	s_waitcnt vmcnt(15)
	ds_write_b128 v35, v[2:5]
	s_waitcnt vmcnt(13)
	ds_write_b128 v36, v[10:13]
	s_waitcnt vmcnt(11)
	ds_write_b128 v37, v[18:21]
	s_waitcnt vmcnt(9)
	ds_write_b128 v38, v[26:29]
	ds_write_b128 v35, v[6:9] offset:32768
	ds_write_b128 v36, v[14:17] offset:32768
	ds_write_b128 v37, v[22:25] offset:32768
	s_waitcnt vmcnt(8)
	ds_write_b128 v38, v[30:33] offset:32768
	v_and_or_b32 v2, v45, s57, v44
	v_lshlrev_b32_e32 v188, 7, v2
	v_bitop3_b32 v2, v41, v43, 4 bitop3:0x36
	v_bitop3_b32 v3, v40, v43, 3 bitop3:0x6c
	v_lshlrev_b32_e32 v189, 4, v2
	v_mov_b32_e32 v2, 0
	v_lshlrev_b32_e32 v186, 4, v3
	v_mov_b32_e32 v3, v2
	v_mov_b32_e32 v4, v2
	v_mov_b32_e32 v5, v2
	v_mov_b32_e32 v6, v2
	v_mov_b32_e32 v7, v2
	v_mov_b32_e32 v8, v2
	v_mov_b32_e32 v9, v2
	v_mov_b32_e32 v10, v2
	v_mov_b32_e32 v11, v2
	v_mov_b32_e32 v12, v2
	v_mov_b32_e32 v13, v2
	v_mov_b32_e32 v14, v2
	v_mov_b32_e32 v15, v2
	v_mov_b32_e32 v16, v2
	v_mov_b32_e32 v17, v2
	v_mov_b32_e32 v18, v2
	v_mov_b32_e32 v19, v2
	v_mov_b32_e32 v20, v2
	v_mov_b32_e32 v21, v2
	v_mov_b32_e32 v22, v2
	v_mov_b32_e32 v23, v2
	v_mov_b32_e32 v24, v2
	v_mov_b32_e32 v25, v2
	v_mov_b32_e32 v26, v2
	v_mov_b32_e32 v27, v2
	v_mov_b32_e32 v28, v2
	v_mov_b32_e32 v29, v2
	v_mov_b32_e32 v30, v2
	v_mov_b32_e32 v31, v2
	v_mov_b32_e32 v32, v2
	v_mov_b32_e32 v33, v2
	v_mov_b32_e32 v34, v2
	v_mov_b32_e32 v35, v2
	v_mov_b32_e32 v36, v2
	v_mov_b32_e32 v37, v2
	v_mov_b32_e32 v38, v2
	v_mov_b32_e32 v39, v2
	v_mov_b32_e32 v40, v2
	v_mov_b32_e32 v41, v2
	v_mov_b32_e32 v42, v2
	v_mov_b32_e32 v43, v2
	v_mov_b32_e32 v44, v2
	v_mov_b32_e32 v45, v2
	v_mov_b32_e32 v46, v2
	v_mov_b32_e32 v47, v2
	v_mov_b32_e32 v48, v2
	v_mov_b32_e32 v49, v2
	v_mov_b32_e32 v50, v2
	v_mov_b32_e32 v51, v2
	v_mov_b32_e32 v52, v2
	v_mov_b32_e32 v53, v2
	v_mov_b32_e32 v54, v2
	v_mov_b32_e32 v55, v2
	v_mov_b32_e32 v56, v2
	v_mov_b32_e32 v57, v2
	v_mov_b32_e32 v58, v2
	v_mov_b32_e32 v59, v2
	v_mov_b32_e32 v60, v2
	v_mov_b32_e32 v61, v2
	v_mov_b32_e32 v62, v2
	v_mov_b32_e32 v63, v2
	v_mov_b32_e32 v64, v2
	v_mov_b32_e32 v65, v2
	v_mov_b32_e32 v66, v2
	v_mov_b32_e32 v67, v2
	v_mov_b32_e32 v68, v2
	v_mov_b32_e32 v69, v2
	v_mov_b32_e32 v70, v2
	v_mov_b32_e32 v71, v2
	v_mov_b32_e32 v72, v2
	v_mov_b32_e32 v73, v2
	v_mov_b32_e32 v74, v2
	v_mov_b32_e32 v75, v2
	v_mov_b32_e32 v76, v2
	v_mov_b32_e32 v77, v2
	v_mov_b32_e32 v78, v2
	v_mov_b32_e32 v79, v2
	v_mov_b32_e32 v80, v2
	v_mov_b32_e32 v81, v2
	v_mov_b32_e32 v82, v2
	v_mov_b32_e32 v83, v2
	v_mov_b32_e32 v84, v2
	v_mov_b32_e32 v85, v2
	v_mov_b32_e32 v86, v2
	v_mov_b32_e32 v87, v2
	v_mov_b32_e32 v88, v2
	v_mov_b32_e32 v89, v2
	v_mov_b32_e32 v90, v2
	v_mov_b32_e32 v91, v2
	v_mov_b32_e32 v92, v2
	v_mov_b32_e32 v93, v2
	v_mov_b32_e32 v94, v2
	v_mov_b32_e32 v95, v2
	v_mov_b32_e32 v96, v2
	v_mov_b32_e32 v97, v2
	v_mov_b32_e32 v98, v2
	v_mov_b32_e32 v99, v2
	v_mov_b32_e32 v100, v2
	v_mov_b32_e32 v101, v2
	v_mov_b32_e32 v102, v2
	v_mov_b32_e32 v103, v2
	v_mov_b32_e32 v104, v2
	v_mov_b32_e32 v105, v2
	v_mov_b32_e32 v106, v2
	v_mov_b32_e32 v107, v2
	v_mov_b32_e32 v108, v2
	v_mov_b32_e32 v109, v2
	v_mov_b32_e32 v138, v2
	v_mov_b32_e32 v139, v2
	v_mov_b32_e32 v140, v2
	v_mov_b32_e32 v141, v2
	v_mov_b32_e32 v142, v2
	v_mov_b32_e32 v143, v2
	v_mov_b32_e32 v144, v2
	v_mov_b32_e32 v145, v2
	v_mov_b32_e32 v146, v2
	v_mov_b32_e32 v147, v2
	v_mov_b32_e32 v148, v2
	v_mov_b32_e32 v149, v2
	v_mov_b32_e32 v154, v2
	v_mov_b32_e32 v155, v2
	v_mov_b32_e32 v156, v2
	v_mov_b32_e32 v157, v2
	v_mov_b32_e32 v158, v2
	v_mov_b32_e32 v159, v2
	v_mov_b32_e32 v160, v2
	v_mov_b32_e32 v161, v2
	s_waitcnt vmcnt(0) lgkmcnt(0)
	s_barrier
; DI f32x4 mfma16(bf16x8 a, bf16x8 b, f32x4 c) { return __builtin_amdgcn_mfma_f32_16x16x32_bf16(a, b, c, 0, 0, 0); }
; #define GLOAD(kt) { GL1(0, kt) GL1(1, kt) GL1(2, kt) GL1(3, kt) }
; #define SSTORE(buf)                              \
;   {                                              \
;     char* as_ = smem + (buf) * BUF;              \
;     char* bs_ = as_ + ASZ;                       \
;     SS1(0) SS1(1) SS1(2) SS1(3)                  \
;   }
; template <int MT, int NT>
; DI void gemm_core(const u16* __restrict__ A, int lda, const u16* __restrict__ B, int ldb, int K,
;                   f32x4 (&acc)[MT][NT], char* smem) {
;     ...
;   for (int kt = 0; kt < nk; ++kt) {
;     __syncthreads();
;     SSTORE((kt + 1) & 1);
;     { const int kn_ = (kt + 2 < nk) ? kt + 2 : nk - 1; GLOAD(kn_); }
;     const char* as = smem + (kt & 1) * BUF;
;     const char* bs = as + ASZ;
; #pragma unroll
;     for (int kk = 0; kk < 2; ++kk) {
;       bf16x8 xf[MT], wf[NT];
; #pragma unroll
;       for (int mi = 0; mi < MT; ++mi)
;         xf[mi] = *(const bf16x8*)(as + (wm * (MT * 16) + mi * 16 + fr) * 128 + (((kk * 4 + fq) ^ fsw) * 16));
; #pragma unroll
;       for (int ni = 0; ni < NT; ++ni)
;         wf[ni] = *(const bf16x8*)(bs + (wn * (NT * 16) + ni * 16 + fr) * 128 + (((kk * 4 + fq) ^ fsw) * 16));
;       __builtin_amdgcn_s_setprio(1);
; #pragma unroll
;       for (int mi = 0; mi < MT; ++mi)
; #pragma unroll
;         for (int ni = 0; ni < NT; ++ni) acc[mi][ni] = mfma16(wf[ni], xf[mi], acc[mi][ni]);
	v_add_u32_e32 v207, v186, v188
	v_add_u32_e32 v206, v186, v187
	ds_read_b128 v[190:193], v206
	ds_read_b128 v[208:211], v206 offset:2048
	ds_read_b128 v[212:215], v206 offset:4096
	ds_read_b128 v[216:219], v206 offset:6144
	ds_read_b128 v[220:223], v207 offset:32768
	ds_read_b128 v[224:227], v207 offset:34816
	ds_read_b128 v[228:231], v207 offset:36864
	ds_read_b128 v[232:235], v207 offset:38912
	ds_read_b128 v[236:239], v207 offset:40960
	ds_read_b128 v[240:243], v207 offset:43008
	ds_read_b128 v[244:247], v207 offset:45056
	ds_read_b128 v[248:251], v207 offset:47104
	s_waitcnt lgkmcnt(0)
.LBB0_768:
	s_add_i32 s8, s5, 0x10000
	s_and_b32 s9, s8, 0x10000
	s_add_i32 s7, s6, 1
	s_min_u32 s6, s6, 13
	s_lshl_b32 s54, s6, 7
	s_and_b32 s5, s5, 0x10000
	v_or_b32_e32 v206, s5, v189
	v_add_u32_e32 v207, v206, v188
	v_add_u32_e32 v206, v206, v187
	v_add3_u32 v170, s9, v0, v173
	s_waitcnt lgkmcnt(10)
	v_mfma_f32_16x16x32_bf16 v[158:161], v[220:223], v[190:193], v[158:161]
	s_waitcnt vmcnt(7)
	ds_write_b128 v170, v[110:113]
	s_waitcnt lgkmcnt(10)
	v_mfma_f32_16x16x32_bf16 v[94:97], v[220:223], v[208:211], v[94:97]
	v_lshl_add_u64 v[110:111], v[162:163], 0, s[54:55]
	global_load_dwordx4 v[110:113], v[110:111], off offset:256
	s_waitcnt lgkmcnt(8)
	v_mfma_f32_16x16x32_bf16 v[62:65], v[220:223], v[212:215], v[62:65]
	s_waitcnt vmcnt(7)
	ds_write_b128 v170, v[118:121] offset:32768
	s_waitcnt lgkmcnt(3)
	v_mfma_f32_16x16x32_bf16 v[30:33], v[220:223], v[216:219], v[30:33]
	v_lshl_add_u64 v[118:119], v[164:165], 0, s[54:55]
	global_load_dwordx4 v[118:121], v[118:119], off offset:256
	ds_read_b128 v[194:197], v206
	v_mfma_f32_16x16x32_bf16 v[154:157], v[224:227], v[190:193], v[154:157]
	ds_read_b128 v[220:223], v207 offset:32768
	s_waitcnt vmcnt(7)
	ds_write_b128 v170, v[114:117] offset:8192
	v_mfma_f32_16x16x32_bf16 v[90:93], v[224:227], v[208:211], v[90:93]
	v_lshl_add_u64 v[114:115], v[166:167], 0, s[54:55]
	global_load_dwordx4 v[114:117], v[114:115], off offset:256
	v_mfma_f32_16x16x32_bf16 v[58:61], v[224:227], v[212:215], v[58:61]
	v_mfma_f32_16x16x32_bf16 v[26:29], v[224:227], v[216:219], v[26:29]
	ds_read_b128 v[198:201], v206 offset:2048
	v_mfma_f32_16x16x32_bf16 v[146:149], v[228:231], v[190:193], v[146:149]
	ds_read_b128 v[224:227], v207 offset:34816
	s_waitcnt vmcnt(7)
	ds_write_b128 v170, v[126:129] offset:40960
	v_mfma_f32_16x16x32_bf16 v[86:89], v[228:231], v[208:211], v[86:89]
	v_lshl_add_u64 v[126:127], v[168:169], 0, s[54:55]
	global_load_dwordx4 v[126:129], v[126:127], off offset:256
	v_mfma_f32_16x16x32_bf16 v[54:57], v[228:231], v[212:215], v[54:57]
	v_mfma_f32_16x16x32_bf16 v[22:25], v[228:231], v[216:219], v[22:25]
	ds_read_b128 v[202:205], v206 offset:4096
	v_mfma_f32_16x16x32_bf16 v[142:145], v[232:235], v[190:193], v[142:145]
	ds_read_b128 v[228:231], v207 offset:36864
	s_waitcnt vmcnt(7)
	ds_write_b128 v170, v[122:125] offset:16384
	v_mfma_f32_16x16x32_bf16 v[82:85], v[232:235], v[208:211], v[82:85]
	v_lshl_add_u64 v[122:123], v[176:177], 0, s[54:55]
	global_load_dwordx4 v[122:125], v[122:123], off offset:256
	v_mfma_f32_16x16x32_bf16 v[50:53], v[232:235], v[212:215], v[50:53]
	v_mfma_f32_16x16x32_bf16 v[18:21], v[232:235], v[216:219], v[18:21]
	v_mfma_f32_16x16x32_bf16 v[138:141], v[236:239], v[190:193], v[138:141]
	ds_read_b128 v[232:235], v207 offset:38912
	s_waitcnt vmcnt(7)
	ds_write_b128 v170, v[134:137] offset:49152
	v_mfma_f32_16x16x32_bf16 v[78:81], v[236:239], v[208:211], v[78:81]
	v_lshl_add_u64 v[134:135], v[178:179], 0, s[54:55]
	global_load_dwordx4 v[134:137], v[134:135], off offset:256
	v_mfma_f32_16x16x32_bf16 v[46:49], v[236:239], v[212:215], v[46:49]
	v_mfma_f32_16x16x32_bf16 v[14:17], v[236:239], v[216:219], v[14:17]
	v_mfma_f32_16x16x32_bf16 v[106:109], v[240:243], v[190:193], v[106:109]
	ds_read_b128 v[236:239], v207 offset:40960
	s_waitcnt vmcnt(7)
	ds_write_b128 v170, v[130:133] offset:24576
	v_mfma_f32_16x16x32_bf16 v[74:77], v[240:243], v[208:211], v[74:77]
	v_lshl_add_u64 v[130:131], v[180:181], 0, s[54:55]
	global_load_dwordx4 v[130:133], v[130:131], off offset:256
	v_mfma_f32_16x16x32_bf16 v[42:45], v[240:243], v[212:215], v[42:45]
	v_mfma_f32_16x16x32_bf16 v[10:13], v[240:243], v[216:219], v[10:13]
	v_mfma_f32_16x16x32_bf16 v[102:105], v[244:247], v[190:193], v[102:105]
	ds_read_b128 v[240:243], v207 offset:43008
	s_waitcnt vmcnt(7)
	ds_write_b128 v170, v[150:153] offset:57344
	v_mfma_f32_16x16x32_bf16 v[70:73], v[244:247], v[208:211], v[70:73]
	v_lshl_add_u64 v[150:151], v[182:183], 0, s[54:55]
	global_load_dwordx4 v[150:153], v[150:151], off offset:256
	v_mfma_f32_16x16x32_bf16 v[38:41], v[244:247], v[212:215], v[38:41]
	v_mfma_f32_16x16x32_bf16 v[6:9], v[244:247], v[216:219], v[6:9]
	s_waitcnt lgkmcnt(15)
	v_mfma_f32_16x16x32_bf16 v[2:5], v[248:251], v[216:219], v[2:5]
	ds_read_b128 v[244:247], v207 offset:45056
	ds_read_b128 v[216:219], v206 offset:6144
	v_mfma_f32_16x16x32_bf16 v[98:101], v[248:251], v[190:193], v[98:101]
	v_mfma_f32_16x16x32_bf16 v[66:69], v[248:251], v[208:211], v[66:69]
	v_mfma_f32_16x16x32_bf16 v[34:37], v[248:251], v[212:215], v[34:37]
	ds_read_b128 v[248:251], v207 offset:47104
	s_waitcnt lgkmcnt(3)
	s_barrier
;   __device__ __forceinline__ u16* P() const { return (u16*)(ws + O_P); }
; DI f32x4 mfma16(bf16x8 a, bf16x8 b, f32x4 c) { return __builtin_amdgcn_mfma_f32_16x16x32_bf16(a, b, c, 0, 0, 0); }
; #define EPI_LOOP(MT_, NT_)                                                \
;   const int l_ = ltid() & 63, w_ = ltid() >> 6;                           \
;   const int wm_ = w_ >> 1, wn_ = w_ & 1, fr_ = l_ & 15, fq_ = l_ >> 4;    \
;   _Pragma("unroll") for (int mi = 0; mi < MT_; ++mi)                      \
;   _Pragma("unroll") for (int ni = 0; ni < NT_; ++ni)
; template <int MT, int NT>
; DI void gemm_core(const u16* __restrict__ A, int lda, const u16* __restrict__ B, int ldb, int K,
;                   f32x4 (&acc)[MT][NT], char* smem) {
;     ...
; #pragma unroll
;     for (int kk = 0; kk < 2; ++kk) {
;       bf16x8 xf[MT], wf[NT];
; #pragma unroll
;       for (int mi = 0; mi < MT; ++mi)
;         xf[mi] = *(const bf16x8*)(as + (wm * (MT * 16) + mi * 16 + fr) * 128 + (((kk * 4 + fq) ^ fsw) * 16));
; #pragma unroll
;       for (int ni = 0; ni < NT; ++ni)
;         wf[ni] = *(const bf16x8*)(bs + (wn * (NT * 16) + ni * 16 + fr) * 128 + (((kk * 4 + fq) ^ fsw) * 16));
;       __builtin_amdgcn_s_setprio(1);
; #pragma unroll
;       for (int mi = 0; mi < MT; ++mi)
; #pragma unroll
;         for (int ni = 0; ni < NT; ++ni) acc[mi][ni] = mfma16(wf[ni], xf[mi], acc[mi][ni]);
;       __builtin_amdgcn_s_setprio(0);
;     }
; DI void phase_ff1(const Params& p, int l, char* smem) {
;     ...
;     EPI_LOOP(4, 8) {
;       const int row = r0 + wm_ * 64 + mi * 16 + fr_, col = c0 + wn_ * 128 + ni * 16 + fq_ * 4;
;       float a0 = fmaxf(acc[mi][ni][0], 0.f), a1 = fmaxf(acc[mi][ni][1], 0.f), a2 = fmaxf(acc[mi][ni][2], 0.f), a3 = fmaxf(acc[mi][ni][3], 0.f);
;       uint2 o;
;       o.x = pack2(a0 * a0, a1 * a1); o.y = pack2(a2 * a2, a3 * a3);
;       *(uint2*)(p.P() + (size_t)row * LDH + col) = o;
;     }
	v_or_b32_e32 v206, s9, v186
	v_add_u32_e32 v207, v206, v188
	v_add_u32_e32 v206, v206, v187
	v_mfma_f32_16x16x32_bf16 v[158:161], v[220:223], v[194:197], v[158:161]
	v_mfma_f32_16x16x32_bf16 v[94:97], v[220:223], v[198:201], v[94:97]
	v_mfma_f32_16x16x32_bf16 v[62:65], v[220:223], v[202:205], v[62:65]
	s_waitcnt lgkmcnt(1)
	v_mfma_f32_16x16x32_bf16 v[30:33], v[220:223], v[216:219], v[30:33]
	ds_read_b128 v[190:193], v206
	v_mfma_f32_16x16x32_bf16 v[154:157], v[224:227], v[194:197], v[154:157]
	ds_read_b128 v[220:223], v207 offset:32768
	v_mfma_f32_16x16x32_bf16 v[90:93], v[224:227], v[198:201], v[90:93]
	v_mfma_f32_16x16x32_bf16 v[58:61], v[224:227], v[202:205], v[58:61]
	v_mfma_f32_16x16x32_bf16 v[26:29], v[224:227], v[216:219], v[26:29]
	ds_read_b128 v[208:211], v206 offset:2048
	v_mfma_f32_16x16x32_bf16 v[146:149], v[228:231], v[194:197], v[146:149]
	ds_read_b128 v[224:227], v207 offset:34816
	v_mfma_f32_16x16x32_bf16 v[86:89], v[228:231], v[198:201], v[86:89]
	v_mfma_f32_16x16x32_bf16 v[54:57], v[228:231], v[202:205], v[54:57]
	v_mfma_f32_16x16x32_bf16 v[22:25], v[228:231], v[216:219], v[22:25]
	ds_read_b128 v[212:215], v206 offset:4096
	v_mfma_f32_16x16x32_bf16 v[142:145], v[232:235], v[194:197], v[142:145]
	ds_read_b128 v[228:231], v207 offset:36864
	v_mfma_f32_16x16x32_bf16 v[82:85], v[232:235], v[198:201], v[82:85]
	v_mfma_f32_16x16x32_bf16 v[50:53], v[232:235], v[202:205], v[50:53]
	v_mfma_f32_16x16x32_bf16 v[18:21], v[232:235], v[216:219], v[18:21]
	v_mfma_f32_16x16x32_bf16 v[138:141], v[236:239], v[194:197], v[138:141]
	ds_read_b128 v[232:235], v207 offset:38912
	v_mfma_f32_16x16x32_bf16 v[78:81], v[236:239], v[198:201], v[78:81]
	v_mfma_f32_16x16x32_bf16 v[46:49], v[236:239], v[202:205], v[46:49]
	v_mfma_f32_16x16x32_bf16 v[14:17], v[236:239], v[216:219], v[14:17]
	v_mfma_f32_16x16x32_bf16 v[106:109], v[240:243], v[194:197], v[106:109]
	ds_read_b128 v[236:239], v207 offset:40960
	v_mfma_f32_16x16x32_bf16 v[74:77], v[240:243], v[198:201], v[74:77]
	v_mfma_f32_16x16x32_bf16 v[42:45], v[240:243], v[202:205], v[42:45]
	v_mfma_f32_16x16x32_bf16 v[10:13], v[240:243], v[216:219], v[10:13]
	v_mfma_f32_16x16x32_bf16 v[102:105], v[244:247], v[194:197], v[102:105]
	ds_read_b128 v[240:243], v207 offset:43008
	v_mfma_f32_16x16x32_bf16 v[70:73], v[244:247], v[198:201], v[70:73]
	v_mfma_f32_16x16x32_bf16 v[38:41], v[244:247], v[202:205], v[38:41]
	v_mfma_f32_16x16x32_bf16 v[6:9], v[244:247], v[216:219], v[6:9]
	s_waitcnt lgkmcnt(9)
	v_mfma_f32_16x16x32_bf16 v[2:5], v[248:251], v[216:219], v[2:5]
	ds_read_b128 v[244:247], v207 offset:45056
	ds_read_b128 v[216:219], v206 offset:6144
	v_mfma_f32_16x16x32_bf16 v[98:101], v[248:251], v[194:197], v[98:101]
	v_mfma_f32_16x16x32_bf16 v[66:69], v[248:251], v[198:201], v[66:69]
	v_mfma_f32_16x16x32_bf16 v[34:37], v[248:251], v[202:205], v[34:37]
	ds_read_b128 v[248:251], v207 offset:47104
	s_cmp_lg_u32 s7, 16
	s_mov_b32 s5, s8
	s_mov_b32 s6, s7
	s_cbranch_scc1 .LBB0_768
	s_waitcnt vmcnt(0) lgkmcnt(0)
	v_mov_b32_e32 v170, 0x358637bd
	v_mov_b32_e32 v194, 0x25a08
	v_mbcnt_lo_u32_b32 v195, -1, 0
	v_mbcnt_hi_u32_b32 v196, -1, v195
	v_mov_b32_e32 v197, 0x24000
	v_mov_b32_e32 v198, 0x1fa0
	v_mov_b32_e32 v199, 0x41b17218
	v_mov_b32_e32 v200, 0x7e800
	v_mov_b32_e32 v201, 0xfd0
	v_mov_b32_e32 v202, 0x100
	v_mov_b32_e32 v203, 0x200
	v_mov_b32_e32 v204, 0x7f61b1e6
	v_mov_b32_e32 v205, 0xff800000
	v_mov_b32_e32 v206, 0x3f80
	v_mov_b32_e32 v207, 0x1d400
	v_mov_b32_e32 v0, v171
	s_waitcnt vmcnt(7)
	v_mov_b32_e32 v110, v171
	s_barrier
	v_max_f32_e32 v113, v159, v159
	v_ashrrev_i32_e32 v111, 1, v110
	v_and_b32_e32 v111, 0xffffffc0, v111
	v_add_u32_e32 v111, s1, v111
	s_waitcnt vmcnt(6)
	v_and_or_b32 v118, v0, 15, v111
	v_lshlrev_b32_e32 v110, 1, v110
	v_lshrrev_b32_e32 v0, 2, v0
	v_and_b32_e32 v110, 0x80, v110
	v_and_b32_e32 v0, 12, v0
	v_or3_b32 v112, v0, v110, s0
	v_max_f32_e32 v0, v158, v158
	v_max_f32_e32 v113, 0, v113
	s_waitcnt vmcnt(5)
	v_max_f32_e32 v116, v160, v160
	v_max_f32_e32 v117, v161, v161
	v_mov_b64_e32 v[110:111], s[78:79]
	v_max_f32_e32 v0, 0, v0
	v_max_f32_e32 v116, 0, v116
	v_max_f32_e32 v117, 0, v117
	v_mul_f32_e32 v119, v113, v113
	v_ashrrev_i32_e32 v113, 31, v112
	v_mad_i64_i32 v[114:115], s[0:1], v118, s10, v[110:111]
	v_mul_f32_e32 v0, v0, v0
	v_mul_f32_e32 v116, v116, v116
	v_mul_f32_e32 v117, v117, v117
	v_lshlrev_b64 v[112:113], 1, v[112:113]
	v_lshl_add_u64 v[114:115], v[114:115], 0, v[112:113]
	v_cvt_pk_bf16_f32 v117, v116, v117
	v_cvt_pk_bf16_f32 v116, v0, v119
	global_store_dwordx2 v[114:115], v[116:117], off
	v_max_f32_e32 v0, v154, v154
	v_max_f32_e32 v116, v155, v155
	v_max_f32_e32 v117, v156, v156
	v_max_f32_e32 v119, v157, v157
	v_max_f32_e32 v0, 0, v0
	v_max_f32_e32 v116, 0, v116
	v_max_f32_e32 v117, 0, v117
	v_max_f32_e32 v119, 0, v119
	v_mul_f32_e32 v0, v0, v0
	v_mul_f32_e32 v116, v116, v116
	v_mul_f32_e32 v117, v117, v117
	v_mul_f32_e32 v119, v119, v119
	v_cvt_pk_bf16_f32 v117, v117, v119
	v_cvt_pk_bf16_f32 v116, v0, v116
	global_store_dwordx2 v[114:115], v[116:117], off offset:32
	v_max_f32_e32 v0, v146, v146
	v_max_f32_e32 v116, v147, v147
	v_max_f32_e32 v117, v148, v148
	v_max_f32_e32 v119, v149, v149
	v_max_f32_e32 v0, 0, v0
	v_max_f32_e32 v116, 0, v116
	v_max_f32_e32 v117, 0, v117
	v_max_f32_e32 v119, 0, v119
	v_mul_f32_e32 v0, v0, v0
	v_mul_f32_e32 v116, v116, v116
	v_mul_f32_e32 v117, v117, v117
	v_mul_f32_e32 v119, v119, v119
	v_cvt_pk_bf16_f32 v117, v117, v119
	v_cvt_pk_bf16_f32 v116, v0, v116
	global_store_dwordx2 v[114:115], v[116:117], off offset:64
	v_max_f32_e32 v0, v142, v142
	v_max_f32_e32 v116, v143, v143
	v_max_f32_e32 v117, v144, v144
	v_max_f32_e32 v119, v145, v145
;   __device__ __forceinline__ u16* P() const { return (u16*)(ws + O_P); }
; #define EPI_LOOP(MT_, NT_)                                                \
;   const int l_ = ltid() & 63, w_ = ltid() >> 6;                           \
;   const int wm_ = w_ >> 1, wn_ = w_ & 1, fr_ = l_ & 15, fq_ = l_ >> 4;    \
;   _Pragma("unroll") for (int mi = 0; mi < MT_; ++mi)                      \
;   _Pragma("unroll") for (int ni = 0; ni < NT_; ++ni)
; DI void phase_ff1(const Params& p, int l, char* smem) {
;     ...
;     EPI_LOOP(4, 8) {
;       const int row = r0 + wm_ * 64 + mi * 16 + fr_, col = c0 + wn_ * 128 + ni * 16 + fq_ * 4;
;       float a0 = fmaxf(acc[mi][ni][0], 0.f), a1 = fmaxf(acc[mi][ni][1], 0.f), a2 = fmaxf(acc[mi][ni][2], 0.f), a3 = fmaxf(acc[mi][ni][3], 0.f);
;       uint2 o;
;       o.x = pack2(a0 * a0, a1 * a1); o.y = pack2(a2 * a2, a3 * a3);
;       *(uint2*)(p.P() + (size_t)row * LDH + col) = o;
;     }
	v_max_f32_e32 v0, 0, v0
	v_max_f32_e32 v116, 0, v116
	v_max_f32_e32 v117, 0, v117
	v_max_f32_e32 v119, 0, v119
	v_mul_f32_e32 v0, v0, v0
	v_mul_f32_e32 v116, v116, v116
	v_mul_f32_e32 v117, v117, v117
	v_mul_f32_e32 v119, v119, v119
	v_cvt_pk_bf16_f32 v117, v117, v119
	v_cvt_pk_bf16_f32 v116, v0, v116
	global_store_dwordx2 v[114:115], v[116:117], off offset:96
	v_max_f32_e32 v0, v138, v138
	v_max_f32_e32 v116, v139, v139
	v_max_f32_e32 v0, 0, v0
	v_max_f32_e32 v116, 0, v116
	v_mul_f32_e32 v0, v0, v0
	v_mul_f32_e32 v116, v116, v116
	v_cvt_pk_bf16_f32 v116, v0, v116
	v_max_f32_e32 v0, v106, v106
	v_max_f32_e32 v106, v107, v107
	v_max_f32_e32 v0, 0, v0
	v_max_f32_e32 v106, 0, v106
	v_mul_f32_e32 v0, v0, v0
	v_mul_f32_e32 v106, v106, v106
	v_cvt_pk_bf16_f32 v106, v0, v106
	v_max_f32_e32 v0, v102, v102
	v_max_f32_e32 v102, v103, v103
	v_max_f32_e32 v0, 0, v0
	v_max_f32_e32 v102, 0, v102
	v_mul_f32_e32 v0, v0, v0
	v_mul_f32_e32 v102, v102, v102
	v_cvt_pk_bf16_f32 v102, v0, v102
	v_max_f32_e32 v0, v98, v98
	v_max_f32_e32 v98, v99, v99
	v_max_f32_e32 v99, v100, v100
	v_max_f32_e32 v100, v101, v101
	v_max_f32_e32 v0, 0, v0
	v_max_f32_e32 v98, 0, v98
	v_max_f32_e32 v99, 0, v99
	v_max_f32_e32 v100, 0, v100
	v_mul_f32_e32 v0, v0, v0
	v_mul_f32_e32 v98, v98, v98
	v_mul_f32_e32 v99, v99, v99
	v_mul_f32_e32 v100, v100, v100
	v_cvt_pk_bf16_f32 v99, v99, v100
	v_cvt_pk_bf16_f32 v98, v0, v98
	v_or_b32_e32 v0, 16, v118
	global_store_dwordx2 v[114:115], v[98:99], off offset:224
	v_mad_i64_i32 v[98:99], s[0:1], v0, s10, v[110:111]
	v_max_f32_e32 v0, v94, v94
	v_max_f32_e32 v94, v95, v95
	v_max_f32_e32 v95, v96, v96
	v_max_f32_e32 v96, v97, v97
	v_max_f32_e32 v0, 0, v0
	v_max_f32_e32 v94, 0, v94
	v_max_f32_e32 v95, 0, v95
	v_max_f32_e32 v96, 0, v96
	v_mul_f32_e32 v0, v0, v0
	v_mul_f32_e32 v100, v94, v94
	v_mul_f32_e32 v97, v95, v95
	v_mul_f32_e32 v96, v96, v96
	v_cvt_pk_bf16_f32 v97, v97, v96
	v_cvt_pk_bf16_f32 v96, v0, v100
	v_max_f32_e32 v0, v90, v90
	v_max_f32_e32 v90, v91, v91
	v_max_f32_e32 v0, 0, v0
	v_max_f32_e32 v90, 0, v90
	v_mul_f32_e32 v0, v0, v0
	v_mul_f32_e32 v90, v90, v90
	v_cvt_pk_bf16_f32 v90, v0, v90
	v_max_f32_e32 v0, v86, v86
	v_max_f32_e32 v86, v87, v87
	v_max_f32_e32 v0, 0, v0
	v_max_f32_e32 v86, 0, v86
	v_mul_f32_e32 v0, v0, v0
	v_mul_f32_e32 v86, v86, v86
	v_cvt_pk_bf16_f32 v86, v0, v86
	v_max_f32_e32 v0, v82, v82
	v_max_f32_e32 v82, v83, v83
	v_max_f32_e32 v0, 0, v0
	v_max_f32_e32 v82, 0, v82
	v_mul_f32_e32 v0, v0, v0
	v_mul_f32_e32 v82, v82, v82
	v_cvt_pk_bf16_f32 v82, v0, v82
	v_max_f32_e32 v0, v78, v78
	v_max_f32_e32 v78, v79, v79
	v_max_f32_e32 v0, 0, v0
	v_max_f32_e32 v78, 0, v78
	v_mul_f32_e32 v0, v0, v0
	v_mul_f32_e32 v78, v78, v78
	v_cvt_pk_bf16_f32 v78, v0, v78
	v_max_f32_e32 v0, v74, v74
	v_max_f32_e32 v74, v75, v75
	v_max_f32_e32 v0, 0, v0
	v_max_f32_e32 v74, 0, v74
	v_mul_f32_e32 v0, v0, v0
	v_mul_f32_e32 v74, v74, v74
	v_cvt_pk_bf16_f32 v74, v0, v74
	v_max_f32_e32 v0, v70, v70
	v_max_f32_e32 v70, v71, v71
	v_max_f32_e32 v0, 0, v0
	v_max_f32_e32 v70, 0, v70
	v_mul_f32_e32 v0, v0, v0
	v_mul_f32_e32 v70, v70, v70
	v_cvt_pk_bf16_f32 v70, v0, v70
	v_max_f32_e32 v0, v66, v66
	v_max_f32_e32 v66, v67, v67
	v_max_f32_e32 v67, v68, v68
	v_max_f32_e32 v68, v69, v69
	v_max_f32_e32 v0, 0, v0
	v_max_f32_e32 v66, 0, v66
	v_max_f32_e32 v67, 0, v67
	v_max_f32_e32 v68, 0, v68
	v_mul_f32_e32 v0, v0, v0
	v_mul_f32_e32 v66, v66, v66
	v_mul_f32_e32 v67, v67, v67
	v_mul_f32_e32 v68, v68, v68
	v_lshl_add_u64 v[94:95], v[98:99], 0, v[112:113]
	v_cvt_pk_bf16_f32 v67, v67, v68
	v_cvt_pk_bf16_f32 v66, v0, v66
	v_or_b32_e32 v0, 32, v118
	global_store_dwordx2 v[94:95], v[66:67], off offset:224
	v_mad_i64_i32 v[66:67], s[0:1], v0, s10, v[110:111]
	v_max_f32_e32 v0, v62, v62
	v_max_f32_e32 v62, v63, v63
	v_max_f32_e32 v63, v64, v64
	v_max_f32_e32 v64, v65, v65
	v_max_f32_e32 v0, 0, v0
	v_max_f32_e32 v62, 0, v62
	v_max_f32_e32 v63, 0, v63
	v_max_f32_e32 v64, 0, v64
	v_mul_f32_e32 v0, v0, v0
	v_mul_f32_e32 v68, v62, v62
	v_mul_f32_e32 v65, v63, v63
	v_mul_f32_e32 v64, v64, v64
	v_cvt_pk_bf16_f32 v65, v65, v64
	v_cvt_pk_bf16_f32 v64, v0, v68
	v_max_f32_e32 v0, v58, v58
	v_max_f32_e32 v58, v59, v59
	v_max_f32_e32 v0, 0, v0
	v_max_f32_e32 v58, 0, v58
	v_mul_f32_e32 v0, v0, v0
	v_mul_f32_e32 v58, v58, v58
	v_cvt_pk_bf16_f32 v58, v0, v58
	v_max_f32_e32 v0, v54, v54
	v_max_f32_e32 v54, v55, v55
	v_max_f32_e32 v0, 0, v0
	v_max_f32_e32 v54, 0, v54
	v_mul_f32_e32 v0, v0, v0
	v_mul_f32_e32 v54, v54, v54
	v_cvt_pk_bf16_f32 v54, v0, v54
	v_max_f32_e32 v0, v50, v50
	v_max_f32_e32 v50, v51, v51
	v_max_f32_e32 v0, 0, v0
	v_max_f32_e32 v50, 0, v50
	v_mul_f32_e32 v0, v0, v0
	v_mul_f32_e32 v50, v50, v50
	v_cvt_pk_bf16_f32 v50, v0, v50
	v_max_f32_e32 v0, v46, v46
	v_max_f32_e32 v46, v47, v47
	v_max_f32_e32 v0, 0, v0
	v_max_f32_e32 v46, 0, v46
	v_mul_f32_e32 v0, v0, v0
	v_mul_f32_e32 v46, v46, v46
	v_cvt_pk_bf16_f32 v46, v0, v46
	v_max_f32_e32 v0, v42, v42
	v_max_f32_e32 v42, v43, v43
	v_max_f32_e32 v0, 0, v0
	v_max_f32_e32 v42, 0, v42
	v_mul_f32_e32 v0, v0, v0
	v_mul_f32_e32 v42, v42, v42
	v_cvt_pk_bf16_f32 v42, v0, v42
	v_max_f32_e32 v0, v38, v38
	v_max_f32_e32 v38, v39, v39
	v_max_f32_e32 v0, 0, v0
	v_max_f32_e32 v38, 0, v38
	v_mul_f32_e32 v0, v0, v0
	v_mul_f32_e32 v38, v38, v38
	v_cvt_pk_bf16_f32 v38, v0, v38
	v_max_f32_e32 v0, v34, v34
	v_max_f32_e32 v34, v35, v35
	v_max_f32_e32 v35, v36, v36
	v_max_f32_e32 v36, v37, v37
	v_max_f32_e32 v0, 0, v0
	v_max_f32_e32 v34, 0, v34
	v_max_f32_e32 v35, 0, v35
	v_max_f32_e32 v36, 0, v36
	v_mul_f32_e32 v0, v0, v0
	v_mul_f32_e32 v34, v34, v34
	v_mul_f32_e32 v35, v35, v35
	v_mul_f32_e32 v36, v36, v36
	v_lshl_add_u64 v[62:63], v[66:67], 0, v[112:113]
;   __device__ __forceinline__ u16* P() const { return (u16*)(ws + O_P); }
; #define EPI_LOOP(MT_, NT_)                                                \
;   const int l_ = ltid() & 63, w_ = ltid() >> 6;                           \
;   const int wm_ = w_ >> 1, wn_ = w_ & 1, fr_ = l_ & 15, fq_ = l_ >> 4;    \
;   _Pragma("unroll") for (int mi = 0; mi < MT_; ++mi)                      \
;   _Pragma("unroll") for (int ni = 0; ni < NT_; ++ni)
; DI void phase_ff1(const Params& p, int l, char* smem) {
;     ...
;     EPI_LOOP(4, 8) {
;       const int row = r0 + wm_ * 64 + mi * 16 + fr_, col = c0 + wn_ * 128 + ni * 16 + fq_ * 4;
;       float a0 = fmaxf(acc[mi][ni][0], 0.f), a1 = fmaxf(acc[mi][ni][1], 0.f), a2 = fmaxf(acc[mi][ni][2], 0.f), a3 = fmaxf(acc[mi][ni][3], 0.f);
;       uint2 o;
;       o.x = pack2(a0 * a0, a1 * a1); o.y = pack2(a2 * a2, a3 * a3);
;       *(uint2*)(p.P() + (size_t)row * LDH + col) = o;
;     }
	v_cvt_pk_bf16_f32 v35, v35, v36
	v_cvt_pk_bf16_f32 v34, v0, v34
	v_or_b32_e32 v0, 48, v118
	global_store_dwordx2 v[62:63], v[34:35], off offset:224
	v_mad_i64_i32 v[34:35], s[0:1], v0, s10, v[110:111]
	v_max_f32_e32 v0, v30, v30
	v_max_f32_e32 v30, v31, v31
	v_max_f32_e32 v31, v32, v32
	v_max_f32_e32 v32, v33, v33
	v_max_f32_e32 v0, 0, v0
	v_max_f32_e32 v30, 0, v30
	v_max_f32_e32 v31, 0, v31
	v_max_f32_e32 v32, 0, v32
	v_mul_f32_e32 v0, v0, v0
	v_mul_f32_e32 v36, v30, v30
	v_mul_f32_e32 v33, v31, v31
	v_mul_f32_e32 v32, v32, v32
	v_cvt_pk_bf16_f32 v33, v33, v32
	v_cvt_pk_bf16_f32 v32, v0, v36
	v_max_f32_e32 v0, v26, v26
	v_max_f32_e32 v26, v27, v27
	v_max_f32_e32 v0, 0, v0
	v_max_f32_e32 v26, 0, v26
	v_mul_f32_e32 v0, v0, v0
	v_mul_f32_e32 v26, v26, v26
	v_cvt_pk_bf16_f32 v26, v0, v26
	v_max_f32_e32 v0, v22, v22
	v_max_f32_e32 v22, v23, v23
	v_max_f32_e32 v0, 0, v0
	v_max_f32_e32 v22, 0, v22
	v_mul_f32_e32 v0, v0, v0
	v_mul_f32_e32 v22, v22, v22
	v_cvt_pk_bf16_f32 v22, v0, v22
	v_max_f32_e32 v0, v18, v18
	v_max_f32_e32 v18, v19, v19
	v_max_f32_e32 v0, 0, v0
	v_max_f32_e32 v18, 0, v18
	v_mul_f32_e32 v0, v0, v0
	v_mul_f32_e32 v18, v18, v18
	v_cvt_pk_bf16_f32 v18, v0, v18
	v_max_f32_e32 v0, v14, v14
	v_max_f32_e32 v14, v15, v15
	v_max_f32_e32 v0, 0, v0
	v_max_f32_e32 v14, 0, v14
	v_mul_f32_e32 v0, v0, v0
	v_mul_f32_e32 v14, v14, v14
	v_cvt_pk_bf16_f32 v14, v0, v14
	v_max_f32_e32 v0, v10, v10
	v_max_f32_e32 v10, v11, v11
	v_max_f32_e32 v0, 0, v0
	v_max_f32_e32 v10, 0, v10
	v_mul_f32_e32 v0, v0, v0
	v_mul_f32_e32 v10, v10, v10
	v_cvt_pk_bf16_f32 v10, v0, v10
	v_max_f32_e32 v0, v6, v6
	v_max_f32_e32 v6, v7, v7
	v_max_f32_e32 v0, 0, v0
	v_max_f32_e32 v6, 0, v6
	v_mul_f32_e32 v0, v0, v0
	v_mul_f32_e32 v6, v6, v6
	v_max_f32_e32 v117, v140, v140
	v_max_f32_e32 v119, v141, v141
	v_max_f32_e32 v107, v108, v108
	v_max_f32_e32 v108, v109, v109
	v_max_f32_e32 v103, v104, v104
	v_max_f32_e32 v104, v105, v105
	v_max_f32_e32 v91, v92, v92
	v_max_f32_e32 v92, v93, v93
	v_max_f32_e32 v87, v88, v88
	v_max_f32_e32 v88, v89, v89
	v_max_f32_e32 v83, v84, v84
	v_max_f32_e32 v84, v85, v85
	v_max_f32_e32 v79, v80, v80
	v_max_f32_e32 v80, v81, v81
	v_max_f32_e32 v75, v76, v76
	v_max_f32_e32 v76, v77, v77
	v_max_f32_e32 v71, v72, v72
	v_max_f32_e32 v72, v73, v73
	v_max_f32_e32 v59, v60, v60
	v_max_f32_e32 v60, v61, v61
	v_max_f32_e32 v55, v56, v56
	v_max_f32_e32 v56, v57, v57
	v_max_f32_e32 v51, v52, v52
	v_max_f32_e32 v52, v53, v53
	v_max_f32_e32 v47, v48, v48
	v_max_f32_e32 v48, v49, v49
	v_max_f32_e32 v43, v44, v44
	v_max_f32_e32 v44, v45, v45
	v_max_f32_e32 v39, v40, v40
	v_max_f32_e32 v40, v41, v41
	v_max_f32_e32 v27, v28, v28
	v_max_f32_e32 v28, v29, v29
	v_max_f32_e32 v23, v24, v24
	v_max_f32_e32 v24, v25, v25
	v_max_f32_e32 v19, v20, v20
	v_max_f32_e32 v20, v21, v21
	v_max_f32_e32 v15, v16, v16
	v_max_f32_e32 v16, v17, v17
	v_max_f32_e32 v11, v12, v12
	v_max_f32_e32 v12, v13, v13
	v_max_f32_e32 v7, v8, v8
	v_max_f32_e32 v8, v9, v9
	v_cvt_pk_bf16_f32 v6, v0, v6
	v_max_f32_e32 v0, v2, v2
	v_max_f32_e32 v2, v3, v3
	v_max_f32_e32 v3, v4, v4
	v_max_f32_e32 v4, v5, v5
	v_max_f32_e32 v117, 0, v117
	v_max_f32_e32 v119, 0, v119
	v_max_f32_e32 v107, 0, v107
	v_max_f32_e32 v108, 0, v108
	v_max_f32_e32 v103, 0, v103
	v_max_f32_e32 v104, 0, v104
	v_max_f32_e32 v91, 0, v91
	v_max_f32_e32 v92, 0, v92
	v_max_f32_e32 v87, 0, v87
	v_max_f32_e32 v88, 0, v88
	v_max_f32_e32 v83, 0, v83
	v_max_f32_e32 v84, 0, v84
	v_max_f32_e32 v79, 0, v79
	v_max_f32_e32 v80, 0, v80
	v_max_f32_e32 v75, 0, v75
	v_max_f32_e32 v76, 0, v76
	v_max_f32_e32 v71, 0, v71
	v_max_f32_e32 v72, 0, v72
	v_max_f32_e32 v59, 0, v59
	v_max_f32_e32 v60, 0, v60
	v_max_f32_e32 v55, 0, v55
	v_max_f32_e32 v56, 0, v56
	v_max_f32_e32 v51, 0, v51
	v_max_f32_e32 v52, 0, v52
	v_max_f32_e32 v47, 0, v47
	v_max_f32_e32 v48, 0, v48
	v_max_f32_e32 v43, 0, v43
	v_max_f32_e32 v44, 0, v44
	v_max_f32_e32 v39, 0, v39
	v_max_f32_e32 v40, 0, v40
	v_max_f32_e32 v27, 0, v27
	v_max_f32_e32 v28, 0, v28
;   __device__ __forceinline__ u16* P() const { return (u16*)(ws + O_P); }
; #define EPI_LOOP(MT_, NT_)                                                \
;   const int l_ = ltid() & 63, w_ = ltid() >> 6;                           \
;   const int wm_ = w_ >> 1, wn_ = w_ & 1, fr_ = l_ & 15, fq_ = l_ >> 4;    \
;   _Pragma("unroll") for (int mi = 0; mi < MT_; ++mi)                      \
;   _Pragma("unroll") for (int ni = 0; ni < NT_; ++ni)
; DI void phase_ff1(const Params& p, int l, char* smem) {
;     ...
;     EPI_LOOP(4, 8) {
;       const int row = r0 + wm_ * 64 + mi * 16 + fr_, col = c0 + wn_ * 128 + ni * 16 + fq_ * 4;
;       float a0 = fmaxf(acc[mi][ni][0], 0.f), a1 = fmaxf(acc[mi][ni][1], 0.f), a2 = fmaxf(acc[mi][ni][2], 0.f), a3 = fmaxf(acc[mi][ni][3], 0.f);
;       uint2 o;
;       o.x = pack2(a0 * a0, a1 * a1); o.y = pack2(a2 * a2, a3 * a3);
;       *(uint2*)(p.P() + (size_t)row * LDH + col) = o;
;     }
	v_max_f32_e32 v23, 0, v23
	v_max_f32_e32 v24, 0, v24
	v_max_f32_e32 v19, 0, v19
	v_max_f32_e32 v20, 0, v20
	v_max_f32_e32 v15, 0, v15
	v_max_f32_e32 v16, 0, v16
	v_max_f32_e32 v11, 0, v11
	v_max_f32_e32 v12, 0, v12
	v_max_f32_e32 v7, 0, v7
	v_max_f32_e32 v8, 0, v8
	v_max_f32_e32 v0, 0, v0
	v_max_f32_e32 v2, 0, v2
	v_max_f32_e32 v3, 0, v3
	v_max_f32_e32 v4, 0, v4
	v_mul_f32_e32 v117, v117, v117
	v_mul_f32_e32 v119, v119, v119
	v_mul_f32_e32 v107, v107, v107
	v_mul_f32_e32 v108, v108, v108
	v_mul_f32_e32 v103, v103, v103
	v_mul_f32_e32 v104, v104, v104
	v_mul_f32_e32 v91, v91, v91
	v_mul_f32_e32 v92, v92, v92
	v_mul_f32_e32 v87, v87, v87
	v_mul_f32_e32 v88, v88, v88
	v_mul_f32_e32 v83, v83, v83
	v_mul_f32_e32 v84, v84, v84
	v_mul_f32_e32 v79, v79, v79
	v_mul_f32_e32 v80, v80, v80
	v_mul_f32_e32 v75, v75, v75
	v_mul_f32_e32 v76, v76, v76
	v_mul_f32_e32 v71, v71, v71
	v_mul_f32_e32 v72, v72, v72
	v_mul_f32_e32 v59, v59, v59
	v_mul_f32_e32 v60, v60, v60
	v_mul_f32_e32 v55, v55, v55
	v_mul_f32_e32 v56, v56, v56
	v_mul_f32_e32 v51, v51, v51
	v_mul_f32_e32 v52, v52, v52
	v_mul_f32_e32 v47, v47, v47
	v_mul_f32_e32 v48, v48, v48
	v_mul_f32_e32 v43, v43, v43
	v_mul_f32_e32 v44, v44, v44
	v_mul_f32_e32 v39, v39, v39
	v_mul_f32_e32 v40, v40, v40
	v_mul_f32_e32 v27, v27, v27
	v_mul_f32_e32 v28, v28, v28
	v_mul_f32_e32 v23, v23, v23
	v_mul_f32_e32 v24, v24, v24
	v_mul_f32_e32 v19, v19, v19
	v_mul_f32_e32 v20, v20, v20
	v_mul_f32_e32 v15, v15, v15
	v_mul_f32_e32 v16, v16, v16
	v_mul_f32_e32 v11, v11, v11
	v_mul_f32_e32 v12, v12, v12
	v_mul_f32_e32 v7, v7, v7
	v_mul_f32_e32 v8, v8, v8
	v_mul_f32_e32 v0, v0, v0
	v_mul_f32_e32 v2, v2, v2
	v_mul_f32_e32 v3, v3, v3
	v_mul_f32_e32 v4, v4, v4
	v_cvt_pk_bf16_f32 v117, v117, v119
	v_cvt_pk_bf16_f32 v107, v107, v108
	v_cvt_pk_bf16_f32 v103, v103, v104
	v_cvt_pk_bf16_f32 v91, v91, v92
	v_cvt_pk_bf16_f32 v87, v87, v88
	v_cvt_pk_bf16_f32 v83, v83, v84
	v_cvt_pk_bf16_f32 v79, v79, v80
	v_cvt_pk_bf16_f32 v75, v75, v76
	v_cvt_pk_bf16_f32 v71, v71, v72
	v_cvt_pk_bf16_f32 v59, v59, v60
	v_cvt_pk_bf16_f32 v55, v55, v56
	v_cvt_pk_bf16_f32 v51, v51, v52
	v_cvt_pk_bf16_f32 v47, v47, v48
	v_cvt_pk_bf16_f32 v43, v43, v44
	v_cvt_pk_bf16_f32 v39, v39, v40
	v_lshl_add_u64 v[30:31], v[34:35], 0, v[112:113]
	v_cvt_pk_bf16_f32 v27, v27, v28
	v_cvt_pk_bf16_f32 v23, v23, v24
	v_cvt_pk_bf16_f32 v19, v19, v20
	v_cvt_pk_bf16_f32 v15, v15, v16
	v_cvt_pk_bf16_f32 v11, v11, v12
	v_cvt_pk_bf16_f32 v7, v7, v8
	v_cvt_pk_bf16_f32 v3, v3, v4
	v_cvt_pk_bf16_f32 v2, v0, v2
	s_add_i32 s4, s4, 1
	s_mov_b64 s[0:1], 0
	global_store_dwordx2 v[114:115], v[116:117], off offset:128
	global_store_dwordx2 v[114:115], v[106:107], off offset:160
	global_store_dwordx2 v[114:115], v[102:103], off offset:192
	global_store_dwordx2 v[94:95], v[96:97], off
	global_store_dwordx2 v[94:95], v[90:91], off offset:32
	global_store_dwordx2 v[94:95], v[86:87], off offset:64
	global_store_dwordx2 v[94:95], v[82:83], off offset:96
	global_store_dwordx2 v[94:95], v[78:79], off offset:128
	global_store_dwordx2 v[94:95], v[74:75], off offset:160
	global_store_dwordx2 v[94:95], v[70:71], off offset:192
	global_store_dwordx2 v[62:63], v[64:65], off
	global_store_dwordx2 v[62:63], v[58:59], off offset:32
	global_store_dwordx2 v[62:63], v[54:55], off offset:64
	global_store_dwordx2 v[62:63], v[50:51], off offset:96
	global_store_dwordx2 v[62:63], v[46:47], off offset:128
	global_store_dwordx2 v[62:63], v[42:43], off offset:160
	global_store_dwordx2 v[62:63], v[38:39], off offset:192
	global_store_dwordx2 v[30:31], v[32:33], off
	global_store_dwordx2 v[30:31], v[26:27], off offset:32
	global_store_dwordx2 v[30:31], v[22:23], off offset:64
	global_store_dwordx2 v[30:31], v[18:19], off offset:96
	global_store_dwordx2 v[30:31], v[14:15], off offset:128
	global_store_dwordx2 v[30:31], v[10:11], off offset:160
	global_store_dwordx2 v[30:31], v[6:7], off offset:192
	global_store_dwordx2 v[30:31], v[2:3], off offset:224
	s_branch .LBB0_765

; DI int lbid() { int b = blockIdx.x; asm volatile("" : "+s"(b)); return b; }
; DI int lgdim() { int b = gridDim.x; asm volatile("" : "+s"(b)); return b; }
; DI int ltid() { int t = threadIdx.x; asm volatile("" : "+v"(t)); return t; }
; #define GLOAD(kt) { GL1(0, kt) GL1(1, kt) GL1(2, kt) GL1(3, kt) }
; #define SSTORE(buf)                              \
;   {                                              \
;     char* as_ = smem + (buf) * BUF;              \
;     char* bs_ = as_ + ASZ;                       \
;     SS1(0) SS1(1) SS1(2) SS1(3)                  \
;   }
; template <int MT, int NT>
; DI void gemm_core(const u16* __restrict__ A, int lda, const u16* __restrict__ B, int ldb, int K,
;                   f32x4 (&acc)[MT][NT], char* smem) {
;   constexpr int BM = 64 * MT, BN = 32 * NT;
;   constexpr int ASZ = BM * 128, BSZ = BN * 128, BUF = ASZ + BSZ;
;   constexpr int NA = BM / 64, NB = BN / 64;
;   const int tid = ltid(), l = tid & 63, w = tid >> 6, wm = w >> 1, wn = w & 1;
;   const int fr = l & 15, fq = l >> 4;
;   uint4 ra0, ra1, ra2, ra3, rb0, rb1, rb2, rb3;
;   const int nk = K >> 6;
;   const int srow = tid >> 3, sch = tid & 7;
;   const int ssw = sch ^ ((srow >> 1) & 7);
;   const int fsw = (fr >> 1) & 7;
;     ...
;   GLOAD(0);
;   SSTORE(0);
;   GLOAD(((1 < nk) ? 1 : 0));
; DI bool next_tile(int it, int RT, int CT, int PR, int PCc, int& rt, int& ct) {
;   const int bid = lbid(), x = bid & 7, j = bid >> 3, J = lgdim() >> 3;
;   const int u = j + it * J;
;   const int pcols = CT / PCc, npatch = (RT / PR) * pcols;
;   const int pid = (u >> 6) * 8 + x;
;   if (pid >= npatch) return false;
;   const int w = u & 63, pr = pid / pcols, pc = pid - pr * pcols;
;   rt = pr * PR + w / PCc;
;   ct = pc * PCc + w % PCc;
;   return true;
; DI void phase_resgemm(const Params& p, const u16* A, int lda, const u16* W, int ldw, int K, char* smem) {
;     ...
;   for (int it = 0; next_tile(it, 128, 4, 16, 4, rt, ct); ++it) {
;     const int r0 = rt * 256, c0 = ct * 256;
;     f32x4 acc[4][8];
;     zero_acc<4, 8>(acc);
;     gemm_core<4, 8>(A + (size_t)r0 * lda, lda, W + (size_t)c0 * ldw, ldw, K, acc, smem);
.LBB0_795:
	s_mov_b32 s0, s56
	s_mov_b32 s5, s14
	s_ashr_i32 s5, s5, 3
	s_and_b32 s1, s0, 7
	s_ashr_i32 s0, s0, 3
	s_mul_i32 s5, s5, s4
	s_add_i32 s5, s5, s0
	s_ashr_i32 s0, s5, 3
	s_and_b32 s0, s0, -8
	s_or_b32 s6, s0, s1
	s_cmp_gt_i32 s6, 7
	s_mov_b64 s[0:1], -1
	s_cbranch_scc1 .LBB0_794
	s_lshl_b32 s1, s5, 6
	s_lshl_b32 s0, s6, 12
	s_and_b32 s1, s1, 0xf00
	s_or_b32 s1, s0, s1
	s_lshl_b32 s0, s5, 8
	s_and_b32 s0, s0, 0x300
	s_mul_i32 s6, s1, 0x2080
	s_mul_hi_i32 s5, s1, 0x2080
	s_add_u32 s6, s78, s6
	s_addc_u32 s7, s79, s5
	s_mul_i32 s5, s0, 0x2080
	s_add_u32 s8, s2, s5
	v_mov_b32_e32 v34, v171
	s_addc_u32 s9, s3, 0
	v_mov_b64_e32 v[26:27], s[6:7]
	v_ashrrev_i32_e32 v35, 3, v34
	v_lshlrev_b32_e32 v36, 4, v34
	v_mov_b64_e32 v[30:31], s[8:9]
	v_add_u32_e32 v37, 64, v35
	v_add_u32_e32 v38, 0x80, v35
	v_add_u32_e32 v39, 0xc0, v35
	v_mad_i64_i32 v[2:3], s[6:7], v35, s10, v[26:27]
	v_and_b32_e32 v0, 0x70, v36
	v_mad_i64_i32 v[6:7], s[6:7], v35, s10, v[30:31]
	v_mad_i64_i32 v[10:11], s[6:7], v37, s10, v[26:27]
	v_mad_i64_i32 v[14:15], s[6:7], v37, s10, v[30:31]
	v_mad_i64_i32 v[18:19], s[6:7], v38, s10, v[26:27]
	v_mad_i64_i32 v[22:23], s[6:7], v38, s10, v[30:31]
	v_mad_i64_i32 v[26:27], s[6:7], v39, s10, v[26:27]
	v_mad_i64_i32 v[30:31], s[6:7], v39, s10, v[30:31]
	s_waitcnt vmcnt(16)
	v_lshl_add_u64 v[162:163], v[2:3], 0, v[0:1]
	v_lshl_add_u64 v[164:165], v[6:7], 0, v[0:1]
	v_lshl_add_u64 v[166:167], v[10:11], 0, v[0:1]
	v_lshl_add_u64 v[168:169], v[14:15], 0, v[0:1]
	v_lshl_add_u64 v[176:177], v[18:19], 0, v[0:1]
	v_lshl_add_u64 v[178:179], v[22:23], 0, v[0:1]
	v_lshl_add_u64 v[180:181], v[26:27], 0, v[0:1]
	s_waitcnt vmcnt(0)
	v_lshl_add_u64 v[182:183], v[30:31], 0, v[0:1]
	global_load_dwordx4 v[2:5], v[162:163], off
	global_load_dwordx4 v[6:9], v[164:165], off
	global_load_dwordx4 v[10:13], v[166:167], off
	global_load_dwordx4 v[14:17], v[168:169], off
	global_load_dwordx4 v[18:21], v[176:177], off
	global_load_dwordx4 v[22:25], v[178:179], off
	global_load_dwordx4 v[26:29], v[180:181], off
	global_load_dwordx4 v[30:33], v[182:183], off
	global_load_dwordx4 v[138:141], v[180:181], off offset:128
	global_load_dwordx4 v[130:133], v[176:177], off offset:128
	global_load_dwordx4 v[118:121], v[166:167], off offset:128
	global_load_dwordx4 v[114:117], v[162:163], off offset:128
	global_load_dwordx4 v[154:157], v[182:183], off offset:128
	global_load_dwordx4 v[142:145], v[178:179], off offset:128
	global_load_dwordx4 v[134:137], v[168:169], off offset:128
	global_load_dwordx4 v[122:125], v[164:165], off offset:128
	v_lshrrev_b32_e32 v40, 4, v34
	v_lshrrev_b32_e32 v42, 1, v34
	v_bfe_u32 v43, v34, 1, 3
	v_and_b32_e32 v44, 15, v34
	v_lshlrev_b32_e32 v45, 1, v34
	v_lshlrev_b32_e32 v0, 7, v35
	v_bitop3_b32 v173, v36, s75, v34 bitop3:0x48
	v_bfe_u32 v41, v34, 4, 2
	v_and_or_b32 v34, v42, s90, v44
	v_and_or_b32 v35, v45, s57, v44
	v_bitop3_b32 v36, v40, v43, 3 bitop3:0x6c
	v_or_b32_e32 v40, v0, v173
	v_lshlrev_b32_e32 v175, 7, v37
	v_lshlrev_b32_e32 v184, 7, v38
	v_lshlrev_b32_e32 v185, 7, v39
	v_lshlrev_b32_e32 v186, 4, v36
	v_lshlrev_b32_e32 v187, 7, v34
	v_lshlrev_b32_e32 v188, 7, v35
	v_or_b32_e32 v34, v175, v173
	v_or_b32_e32 v35, v184, v173
	v_or_b32_e32 v36, v185, v173
	s_mov_b32 s5, 0
	s_mov_b32 s6, 0
	s_waitcnt vmcnt(15)
	ds_write_b128 v40, v[2:5]
	s_waitcnt vmcnt(13)
	ds_write_b128 v34, v[10:13]
	s_waitcnt vmcnt(11)
	ds_write_b128 v35, v[18:21]
	s_waitcnt vmcnt(9)
	ds_write_b128 v36, v[26:29]
	ds_write_b128 v40, v[6:9] offset:32768
	ds_write_b128 v34, v[14:17] offset:32768
	ds_write_b128 v35, v[22:25] offset:32768
	s_waitcnt vmcnt(8)
	ds_write_b128 v36, v[30:33] offset:32768
	v_bitop3_b32 v2, v41, v43, 4 bitop3:0x36
	v_lshlrev_b32_e32 v189, 4, v2
	v_mov_b32_e32 v2, 0
	v_mov_b32_e32 v3, v2
	v_mov_b32_e32 v4, v2
	v_mov_b32_e32 v5, v2
	v_mov_b32_e32 v6, v2
	v_mov_b32_e32 v7, v2
	v_mov_b32_e32 v8, v2
	v_mov_b32_e32 v9, v2
	v_mov_b32_e32 v10, v2
	v_mov_b32_e32 v11, v2
	v_mov_b32_e32 v12, v2
	v_mov_b32_e32 v13, v2
	v_mov_b32_e32 v14, v2
	v_mov_b32_e32 v15, v2
	v_mov_b32_e32 v16, v2
	v_mov_b32_e32 v17, v2
	v_mov_b32_e32 v18, v2
	v_mov_b32_e32 v19, v2
	v_mov_b32_e32 v20, v2
	v_mov_b32_e32 v21, v2
	v_mov_b32_e32 v22, v2
	v_mov_b32_e32 v23, v2
	v_mov_b32_e32 v24, v2
	v_mov_b32_e32 v25, v2
	v_mov_b32_e32 v26, v2
	v_mov_b32_e32 v27, v2
	v_mov_b32_e32 v28, v2
	v_mov_b32_e32 v29, v2
	v_mov_b32_e32 v30, v2
	v_mov_b32_e32 v31, v2
	v_mov_b32_e32 v32, v2
	v_mov_b32_e32 v33, v2
	v_mov_b32_e32 v34, v2
	v_mov_b32_e32 v35, v2
	v_mov_b32_e32 v36, v2
	v_mov_b32_e32 v37, v2
	v_mov_b32_e32 v38, v2
	v_mov_b32_e32 v39, v2
	v_mov_b32_e32 v40, v2
	v_mov_b32_e32 v41, v2
	v_mov_b32_e32 v42, v2
	v_mov_b32_e32 v43, v2
	v_mov_b32_e32 v44, v2
	v_mov_b32_e32 v45, v2
	v_mov_b32_e32 v46, v2
	v_mov_b32_e32 v47, v2
	v_mov_b32_e32 v48, v2
	v_mov_b32_e32 v49, v2
	v_mov_b32_e32 v50, v2
	v_mov_b32_e32 v51, v2
	v_mov_b32_e32 v52, v2
	v_mov_b32_e32 v53, v2
	v_mov_b32_e32 v54, v2
	v_mov_b32_e32 v55, v2
	v_mov_b32_e32 v56, v2
	v_mov_b32_e32 v57, v2
	v_mov_b32_e32 v58, v2
	v_mov_b32_e32 v59, v2
	v_mov_b32_e32 v60, v2
	v_mov_b32_e32 v61, v2
	v_mov_b32_e32 v62, v2
	v_mov_b32_e32 v63, v2
	v_mov_b32_e32 v64, v2
	v_mov_b32_e32 v65, v2
	v_mov_b32_e32 v66, v2
	v_mov_b32_e32 v67, v2
	v_mov_b32_e32 v68, v2
	v_mov_b32_e32 v69, v2
	v_mov_b32_e32 v70, v2
	v_mov_b32_e32 v71, v2
	v_mov_b32_e32 v72, v2
	v_mov_b32_e32 v73, v2
	v_mov_b32_e32 v74, v2
	v_mov_b32_e32 v75, v2
	v_mov_b32_e32 v76, v2
	v_mov_b32_e32 v77, v2
	v_mov_b32_e32 v78, v2
	v_mov_b32_e32 v79, v2
	v_mov_b32_e32 v80, v2
	v_mov_b32_e32 v81, v2
	v_mov_b32_e32 v82, v2
	v_mov_b32_e32 v83, v2
	v_mov_b32_e32 v84, v2
	v_mov_b32_e32 v85, v2
	v_mov_b32_e32 v86, v2
	v_mov_b32_e32 v87, v2
	v_mov_b32_e32 v88, v2
	v_mov_b32_e32 v89, v2
	v_mov_b32_e32 v90, v2
	v_mov_b32_e32 v91, v2
	v_mov_b32_e32 v92, v2
	v_mov_b32_e32 v93, v2
	v_mov_b32_e32 v94, v2
	v_mov_b32_e32 v95, v2
	v_mov_b32_e32 v96, v2
	v_mov_b32_e32 v97, v2
	v_mov_b32_e32 v98, v2
	v_mov_b32_e32 v99, v2
	v_mov_b32_e32 v100, v2
	v_mov_b32_e32 v101, v2
	v_mov_b32_e32 v102, v2
	v_mov_b32_e32 v103, v2
	v_mov_b32_e32 v104, v2
	v_mov_b32_e32 v105, v2
	v_mov_b32_e32 v106, v2
	v_mov_b32_e32 v107, v2
	v_mov_b32_e32 v108, v2
	v_mov_b32_e32 v109, v2
	v_mov_b32_e32 v110, v2
	v_mov_b32_e32 v111, v2
	v_mov_b32_e32 v112, v2
	v_mov_b32_e32 v113, v2
	v_mov_b32_e32 v126, v2
	v_mov_b32_e32 v127, v2
	v_mov_b32_e32 v128, v2
	v_mov_b32_e32 v129, v2
	v_mov_b32_e32 v146, v2
	v_mov_b32_e32 v147, v2
	v_mov_b32_e32 v148, v2
	v_mov_b32_e32 v149, v2
	v_mov_b32_e32 v150, v2
	v_mov_b32_e32 v151, v2
	v_mov_b32_e32 v152, v2
	v_mov_b32_e32 v153, v2
	v_mov_b32_e32 v158, v2
	v_mov_b32_e32 v159, v2
	v_mov_b32_e32 v160, v2
	v_mov_b32_e32 v161, v2
	s_waitcnt vmcnt(0) lgkmcnt(0)
	s_barrier
; DI f32x4 mfma16(bf16x8 a, bf16x8 b, f32x4 c) { return __builtin_amdgcn_mfma_f32_16x16x32_bf16(a, b, c, 0, 0, 0); }
; #define GLOAD(kt) { GL1(0, kt) GL1(1, kt) GL1(2, kt) GL1(3, kt) }
; #define SSTORE(buf)                              \
;   {                                              \
;     char* as_ = smem + (buf) * BUF;              \
;     char* bs_ = as_ + ASZ;                       \
;     SS1(0) SS1(1) SS1(2) SS1(3)                  \
;   }
; template <int MT, int NT>
; DI void gemm_core(const u16* __restrict__ A, int lda, const u16* __restrict__ B, int ldb, int K,
;                   f32x4 (&acc)[MT][NT], char* smem) {
;     ...
;   for (int kt = 0; kt < nk; ++kt) {
;     __syncthreads();
;     SSTORE((kt + 1) & 1);
;     { const int kn_ = (kt + 2 < nk) ? kt + 2 : nk - 1; GLOAD(kn_); }
;     const char* as = smem + (kt & 1) * BUF;
;     const char* bs = as + ASZ;
; #pragma unroll
;     for (int kk = 0; kk < 2; ++kk) {
;       bf16x8 xf[MT], wf[NT];
; #pragma unroll
;       for (int mi = 0; mi < MT; ++mi)
;         xf[mi] = *(const bf16x8*)(as + (wm * (MT * 16) + mi * 16 + fr) * 128 + (((kk * 4 + fq) ^ fsw) * 16));
; #pragma unroll
;       for (int ni = 0; ni < NT; ++ni)
;         wf[ni] = *(const bf16x8*)(bs + (wn * (NT * 16) + ni * 16 + fr) * 128 + (((kk * 4 + fq) ^ fsw) * 16));
;       __builtin_amdgcn_s_setprio(1);
; #pragma unroll
;       for (int mi = 0; mi < MT; ++mi)
; #pragma unroll
;         for (int ni = 0; ni < NT; ++ni) acc[mi][ni] = mfma16(wf[ni], xf[mi], acc[mi][ni]);
	v_add_u32_e32 v207, v186, v188
	v_add_u32_e32 v206, v186, v187
	ds_read_b128 v[190:193], v206
	ds_read_b128 v[208:211], v206 offset:2048
	ds_read_b128 v[212:215], v206 offset:4096
	ds_read_b128 v[216:219], v206 offset:6144
	ds_read_b128 v[220:223], v207 offset:32768
	ds_read_b128 v[224:227], v207 offset:34816
	ds_read_b128 v[228:231], v207 offset:36864
	ds_read_b128 v[232:235], v207 offset:38912
	ds_read_b128 v[236:239], v207 offset:40960
	ds_read_b128 v[240:243], v207 offset:43008
	ds_read_b128 v[244:247], v207 offset:45056
	ds_read_b128 v[248:251], v207 offset:47104
	s_waitcnt lgkmcnt(0)
.LBB0_797:
	s_add_i32 s8, s5, 0x10000
	s_and_b32 s9, s8, 0x10000
	s_add_i32 s7, s6, 1
	s_min_u32 s6, s6, 61
	s_lshl_b32 s54, s6, 7
	s_and_b32 s5, s5, 0x10000
	v_or_b32_e32 v206, s5, v189
	v_add_u32_e32 v207, v206, v188
	v_add_u32_e32 v206, v206, v187
	v_add3_u32 v170, s9, v0, v173
	s_waitcnt lgkmcnt(10)
	v_mfma_f32_16x16x32_bf16 v[158:161], v[220:223], v[190:193], v[158:161]
	s_waitcnt vmcnt(7)
	ds_write_b128 v170, v[114:117]
	s_waitcnt lgkmcnt(10)
	v_mfma_f32_16x16x32_bf16 v[94:97], v[220:223], v[208:211], v[94:97]
	v_lshl_add_u64 v[114:115], v[162:163], 0, s[54:55]
	global_load_dwordx4 v[114:117], v[114:115], off offset:256
	s_waitcnt lgkmcnt(8)
	v_mfma_f32_16x16x32_bf16 v[62:65], v[220:223], v[212:215], v[62:65]
	s_waitcnt vmcnt(7)
	ds_write_b128 v170, v[122:125] offset:32768
	s_waitcnt lgkmcnt(3)
	v_mfma_f32_16x16x32_bf16 v[30:33], v[220:223], v[216:219], v[30:33]
	v_lshl_add_u64 v[122:123], v[164:165], 0, s[54:55]
	global_load_dwordx4 v[122:125], v[122:123], off offset:256
	ds_read_b128 v[194:197], v206
	v_mfma_f32_16x16x32_bf16 v[150:153], v[224:227], v[190:193], v[150:153]
	ds_read_b128 v[220:223], v207 offset:32768
	s_waitcnt vmcnt(7)
	ds_write_b128 v170, v[118:121] offset:8192
	v_mfma_f32_16x16x32_bf16 v[90:93], v[224:227], v[208:211], v[90:93]
	v_lshl_add_u64 v[118:119], v[166:167], 0, s[54:55]
	global_load_dwordx4 v[118:121], v[118:119], off offset:256
	v_mfma_f32_16x16x32_bf16 v[58:61], v[224:227], v[212:215], v[58:61]
	v_mfma_f32_16x16x32_bf16 v[26:29], v[224:227], v[216:219], v[26:29]
	ds_read_b128 v[198:201], v206 offset:2048
	v_mfma_f32_16x16x32_bf16 v[146:149], v[228:231], v[190:193], v[146:149]
	ds_read_b128 v[224:227], v207 offset:34816
	s_waitcnt vmcnt(7)
	ds_write_b128 v170, v[134:137] offset:40960
	v_mfma_f32_16x16x32_bf16 v[86:89], v[228:231], v[208:211], v[86:89]
	v_lshl_add_u64 v[134:135], v[168:169], 0, s[54:55]
	global_load_dwordx4 v[134:137], v[134:135], off offset:256
	v_mfma_f32_16x16x32_bf16 v[54:57], v[228:231], v[212:215], v[54:57]
	v_mfma_f32_16x16x32_bf16 v[22:25], v[228:231], v[216:219], v[22:25]
	ds_read_b128 v[202:205], v206 offset:4096
	v_mfma_f32_16x16x32_bf16 v[126:129], v[232:235], v[190:193], v[126:129]
	ds_read_b128 v[228:231], v207 offset:36864
	s_waitcnt vmcnt(7)
	ds_write_b128 v170, v[130:133] offset:16384
	v_mfma_f32_16x16x32_bf16 v[82:85], v[232:235], v[208:211], v[82:85]
	v_lshl_add_u64 v[130:131], v[176:177], 0, s[54:55]
	global_load_dwordx4 v[130:133], v[130:131], off offset:256
	v_mfma_f32_16x16x32_bf16 v[50:53], v[232:235], v[212:215], v[50:53]
	v_mfma_f32_16x16x32_bf16 v[18:21], v[232:235], v[216:219], v[18:21]
	v_mfma_f32_16x16x32_bf16 v[110:113], v[236:239], v[190:193], v[110:113]
	ds_read_b128 v[232:235], v207 offset:38912
	s_waitcnt vmcnt(7)
	ds_write_b128 v170, v[142:145] offset:49152
	v_mfma_f32_16x16x32_bf16 v[78:81], v[236:239], v[208:211], v[78:81]
	v_lshl_add_u64 v[142:143], v[178:179], 0, s[54:55]
	global_load_dwordx4 v[142:145], v[142:143], off offset:256
	v_mfma_f32_16x16x32_bf16 v[46:49], v[236:239], v[212:215], v[46:49]
	v_mfma_f32_16x16x32_bf16 v[14:17], v[236:239], v[216:219], v[14:17]
	v_mfma_f32_16x16x32_bf16 v[106:109], v[240:243], v[190:193], v[106:109]
	ds_read_b128 v[236:239], v207 offset:40960
	s_waitcnt vmcnt(7)
	ds_write_b128 v170, v[138:141] offset:24576
	v_mfma_f32_16x16x32_bf16 v[74:77], v[240:243], v[208:211], v[74:77]
	v_lshl_add_u64 v[138:139], v[180:181], 0, s[54:55]
	global_load_dwordx4 v[138:141], v[138:139], off offset:256
	v_mfma_f32_16x16x32_bf16 v[42:45], v[240:243], v[212:215], v[42:45]
	v_mfma_f32_16x16x32_bf16 v[10:13], v[240:243], v[216:219], v[10:13]
	v_mfma_f32_16x16x32_bf16 v[102:105], v[244:247], v[190:193], v[102:105]
	ds_read_b128 v[240:243], v207 offset:43008
	s_waitcnt vmcnt(7)
	ds_write_b128 v170, v[154:157] offset:57344
	v_mfma_f32_16x16x32_bf16 v[70:73], v[244:247], v[208:211], v[70:73]
	v_lshl_add_u64 v[154:155], v[182:183], 0, s[54:55]
	global_load_dwordx4 v[154:157], v[154:155], off offset:256
	v_mfma_f32_16x16x32_bf16 v[38:41], v[244:247], v[212:215], v[38:41]
	v_mfma_f32_16x16x32_bf16 v[6:9], v[244:247], v[216:219], v[6:9]
	s_waitcnt lgkmcnt(15)
	v_mfma_f32_16x16x32_bf16 v[2:5], v[248:251], v[216:219], v[2:5]
	ds_read_b128 v[244:247], v207 offset:45056
	ds_read_b128 v[216:219], v206 offset:6144
	v_mfma_f32_16x16x32_bf16 v[98:101], v[248:251], v[190:193], v[98:101]
	v_mfma_f32_16x16x32_bf16 v[66:69], v[248:251], v[208:211], v[66:69]
	v_mfma_f32_16x16x32_bf16 v[34:37], v[248:251], v[212:215], v[34:37]
	ds_read_b128 v[248:251], v207 offset:47104
	s_waitcnt lgkmcnt(3)
	s_barrier
;   __device__ __forceinline__ u16* XB() const { return (u16*)(ws + O_XB); }
; DI float bflo(u32 v) { return __uint_as_float(v << 16); }
; DI float bfhi(u32 v) { return __uint_as_float(v & 0xffff0000u); }
; DI f32x4 mfma16(bf16x8 a, bf16x8 b, f32x4 c) { return __builtin_amdgcn_mfma_f32_16x16x32_bf16(a, b, c, 0, 0, 0); }
; #define EPI_LOOP(MT_, NT_)                                                \
;   const int l_ = ltid() & 63, w_ = ltid() >> 6;                           \
;   const int wm_ = w_ >> 1, wn_ = w_ & 1, fr_ = l_ & 15, fq_ = l_ >> 4;    \
;   _Pragma("unroll") for (int mi = 0; mi < MT_; ++mi)                      \
;   _Pragma("unroll") for (int ni = 0; ni < NT_; ++ni)
; template <int MT, int NT>
; DI void gemm_core(const u16* __restrict__ A, int lda, const u16* __restrict__ B, int ldb, int K,
;                   f32x4 (&acc)[MT][NT], char* smem) {
;     ...
; #pragma unroll
;     for (int kk = 0; kk < 2; ++kk) {
;       bf16x8 xf[MT], wf[NT];
; #pragma unroll
;       for (int mi = 0; mi < MT; ++mi)
;         xf[mi] = *(const bf16x8*)(as + (wm * (MT * 16) + mi * 16 + fr) * 128 + (((kk * 4 + fq) ^ fsw) * 16));
; #pragma unroll
;       for (int ni = 0; ni < NT; ++ni)
;         wf[ni] = *(const bf16x8*)(bs + (wn * (NT * 16) + ni * 16 + fr) * 128 + (((kk * 4 + fq) ^ fsw) * 16));
;       __builtin_amdgcn_s_setprio(1);
; #pragma unroll
;       for (int mi = 0; mi < MT; ++mi)
; #pragma unroll
;         for (int ni = 0; ni < NT; ++ni) acc[mi][ni] = mfma16(wf[ni], xf[mi], acc[mi][ni]);
;       __builtin_amdgcn_s_setprio(0);
;     }
; DI void phase_resgemm(const Params& p, const u16* A, int lda, const u16* W, int ldw, int K, char* smem) {
;     ...
;     EPI_LOOP(4, 8) {
;       const int row = r0 + wm_ * 64 + mi * 16 + fr_, col = c0 + wn_ * 128 + ni * 16 + fq_ * 4;
;       const uint2 xb = *(const uint2*)(p.XB() + (size_t)row * LDX + col);
;       float4 o;
;       o.x = DN_ALPHA * bflo(xb.x) + acc[mi][ni][0]; o.y = DN_ALPHA * bfhi(xb.x) + acc[mi][ni][1];
;       o.z = DN_ALPHA * bflo(xb.y) + acc[mi][ni][2]; o.w = DN_ALPHA * bfhi(xb.y) + acc[mi][ni][3];
;       *(float4*)(p.out + (size_t)row * 1024 + col) = o;
;     }
	v_or_b32_e32 v206, s9, v186
	v_add_u32_e32 v207, v206, v188
	v_add_u32_e32 v206, v206, v187
	v_mfma_f32_16x16x32_bf16 v[158:161], v[220:223], v[194:197], v[158:161]
	v_mfma_f32_16x16x32_bf16 v[94:97], v[220:223], v[198:201], v[94:97]
	v_mfma_f32_16x16x32_bf16 v[62:65], v[220:223], v[202:205], v[62:65]
	s_waitcnt lgkmcnt(1)
	v_mfma_f32_16x16x32_bf16 v[30:33], v[220:223], v[216:219], v[30:33]
	ds_read_b128 v[190:193], v206
	v_mfma_f32_16x16x32_bf16 v[150:153], v[224:227], v[194:197], v[150:153]
	ds_read_b128 v[220:223], v207 offset:32768
	v_mfma_f32_16x16x32_bf16 v[90:93], v[224:227], v[198:201], v[90:93]
	v_mfma_f32_16x16x32_bf16 v[58:61], v[224:227], v[202:205], v[58:61]
	v_mfma_f32_16x16x32_bf16 v[26:29], v[224:227], v[216:219], v[26:29]
	ds_read_b128 v[208:211], v206 offset:2048
	v_mfma_f32_16x16x32_bf16 v[146:149], v[228:231], v[194:197], v[146:149]
	ds_read_b128 v[224:227], v207 offset:34816
	v_mfma_f32_16x16x32_bf16 v[86:89], v[228:231], v[198:201], v[86:89]
	v_mfma_f32_16x16x32_bf16 v[54:57], v[228:231], v[202:205], v[54:57]
	v_mfma_f32_16x16x32_bf16 v[22:25], v[228:231], v[216:219], v[22:25]
	ds_read_b128 v[212:215], v206 offset:4096
	v_mfma_f32_16x16x32_bf16 v[126:129], v[232:235], v[194:197], v[126:129]
	ds_read_b128 v[228:231], v207 offset:36864
	v_mfma_f32_16x16x32_bf16 v[82:85], v[232:235], v[198:201], v[82:85]
	v_mfma_f32_16x16x32_bf16 v[50:53], v[232:235], v[202:205], v[50:53]
	v_mfma_f32_16x16x32_bf16 v[18:21], v[232:235], v[216:219], v[18:21]
	v_mfma_f32_16x16x32_bf16 v[110:113], v[236:239], v[194:197], v[110:113]
	ds_read_b128 v[232:235], v207 offset:38912
	v_mfma_f32_16x16x32_bf16 v[78:81], v[236:239], v[198:201], v[78:81]
	v_mfma_f32_16x16x32_bf16 v[46:49], v[236:239], v[202:205], v[46:49]
	v_mfma_f32_16x16x32_bf16 v[14:17], v[236:239], v[216:219], v[14:17]
	v_mfma_f32_16x16x32_bf16 v[106:109], v[240:243], v[194:197], v[106:109]
	ds_read_b128 v[236:239], v207 offset:40960
	v_mfma_f32_16x16x32_bf16 v[74:77], v[240:243], v[198:201], v[74:77]
	v_mfma_f32_16x16x32_bf16 v[42:45], v[240:243], v[202:205], v[42:45]
	v_mfma_f32_16x16x32_bf16 v[10:13], v[240:243], v[216:219], v[10:13]
	v_mfma_f32_16x16x32_bf16 v[102:105], v[244:247], v[194:197], v[102:105]
	ds_read_b128 v[240:243], v207 offset:43008
	v_mfma_f32_16x16x32_bf16 v[70:73], v[244:247], v[198:201], v[70:73]
	v_mfma_f32_16x16x32_bf16 v[38:41], v[244:247], v[202:205], v[38:41]
	v_mfma_f32_16x16x32_bf16 v[6:9], v[244:247], v[216:219], v[6:9]
	s_waitcnt lgkmcnt(9)
	v_mfma_f32_16x16x32_bf16 v[2:5], v[248:251], v[216:219], v[2:5]
	ds_read_b128 v[244:247], v207 offset:45056
	ds_read_b128 v[216:219], v206 offset:6144
	v_mfma_f32_16x16x32_bf16 v[98:101], v[248:251], v[194:197], v[98:101]
	v_mfma_f32_16x16x32_bf16 v[66:69], v[248:251], v[198:201], v[66:69]
	v_mfma_f32_16x16x32_bf16 v[34:37], v[248:251], v[202:205], v[34:37]
	ds_read_b128 v[248:251], v207 offset:47104
	s_cmp_lg_u32 s7, 64
	s_mov_b32 s5, s8
	s_mov_b32 s6, s7
	s_cbranch_scc1 .LBB0_797
	s_waitcnt vmcnt(0) lgkmcnt(0)
	v_mov_b32_e32 v170, 0x358637bd
	v_mov_b32_e32 v194, 0x25a08
	v_mbcnt_lo_u32_b32 v195, -1, 0
	v_mbcnt_hi_u32_b32 v196, -1, v195
	v_mov_b32_e32 v197, 0x24000
	v_mov_b32_e32 v198, 0x1fa0
	v_mov_b32_e32 v199, 0x41b17218
	v_mov_b32_e32 v200, 0x7e800
	v_mov_b32_e32 v201, 0xfd0
	v_mov_b32_e32 v202, 0x100
	v_mov_b32_e32 v203, 0x200
	v_mov_b32_e32 v204, 0x7f61b1e6
	v_mov_b32_e32 v205, 0xff800000
	v_mov_b32_e32 v206, 0x3f80
	v_mov_b32_e32 v207, 0x1d400
	v_mov_b32_e32 v0, v171
	s_waitcnt vmcnt(7)
	v_mov_b32_e32 v115, v171
	s_barrier
	s_waitcnt vmcnt(5)
	v_mov_b64_e32 v[118:119], s[60:61]
	v_ashrrev_i32_e32 v114, 1, v115
	v_and_b32_e32 v114, 0xffffffc0, v114
	v_add_u32_e32 v114, s1, v114
	v_and_or_b32 v114, v0, 15, v114
	v_lshlrev_b32_e32 v115, 1, v115
	v_lshrrev_b32_e32 v0, 2, v0
	v_and_b32_e32 v115, 0x80, v115
	v_and_b32_e32 v0, 12, v0
	v_or3_b32 v115, v0, v115, s0
	v_mad_i64_i32 v[116:117], s[0:1], v114, s59, v[118:119]
	v_lshlrev_b32_e32 v0, 1, v115
	v_lshl_add_u64 v[124:125], v[116:117], 0, v[0:1]
	global_load_dwordx2 v[120:121], v[124:125], off
	v_lshlrev_b32_e32 v116, 2, v115
	v_ashrrev_i32_e32 v115, 31, v114
	v_lshlrev_b64 v[122:123], 12, v[114:115]
	v_mov_b32_e32 v117, v1
	v_lshl_add_u64 v[122:123], s[86:87], 0, v[122:123]
	s_waitcnt vmcnt(4)
	v_lshl_add_u64 v[130:131], v[122:123], 0, v[116:117]
	s_add_i32 s4, s4, 1
	s_waitcnt vmcnt(0)
	v_lshlrev_b32_e32 v122, 16, v120
	v_and_b32_e32 v123, 0xffff0000, v120
	v_lshlrev_b32_e32 v132, 16, v121
	v_and_b32_e32 v133, 0xffff0000, v121
	v_pk_fma_f32 v[120:121], v[122:123], s[74:75], v[158:159] op_sel_hi:[1,0,1]
	v_pk_fma_f32 v[122:123], v[132:133], s[74:75], v[160:161] op_sel_hi:[1,0,1]
	global_store_dwordx4 v[130:131], v[120:123], off
	global_load_dwordx2 v[120:121], v[124:125], off offset:32
	s_waitcnt vmcnt(0)
	v_lshlrev_b32_e32 v132, 16, v121
	v_lshlrev_b32_e32 v122, 16, v120
	v_and_b32_e32 v123, 0xffff0000, v120
	v_and_b32_e32 v133, 0xffff0000, v121
	v_pk_fma_f32 v[120:121], v[122:123], s[74:75], v[150:151] op_sel_hi:[1,0,1]
	v_pk_fma_f32 v[122:123], v[132:133], s[74:75], v[152:153] op_sel_hi:[1,0,1]
	global_store_dwordx4 v[130:131], v[120:123], off offset:64
	global_load_dwordx2 v[120:121], v[124:125], off offset:64
	s_waitcnt vmcnt(0)
	v_lshlrev_b32_e32 v132, 16, v121
	v_lshlrev_b32_e32 v122, 16, v120
	v_and_b32_e32 v123, 0xffff0000, v120
	v_and_b32_e32 v133, 0xffff0000, v121
	v_pk_fma_f32 v[120:121], v[122:123], s[74:75], v[146:147] op_sel_hi:[1,0,1]
	v_pk_fma_f32 v[122:123], v[132:133], s[74:75], v[148:149] op_sel_hi:[1,0,1]
	global_store_dwordx4 v[130:131], v[120:123], off offset:128
	global_load_dwordx2 v[120:121], v[124:125], off offset:96
	s_waitcnt vmcnt(0)
;   __device__ __forceinline__ u16* XB() const { return (u16*)(ws + O_XB); }
; DI float bflo(u32 v) { return __uint_as_float(v << 16); }
; DI float bfhi(u32 v) { return __uint_as_float(v & 0xffff0000u); }
; #define EPI_LOOP(MT_, NT_)                                                \
;   const int l_ = ltid() & 63, w_ = ltid() >> 6;                           \
;   const int wm_ = w_ >> 1, wn_ = w_ & 1, fr_ = l_ & 15, fq_ = l_ >> 4;    \
;   _Pragma("unroll") for (int mi = 0; mi < MT_; ++mi)                      \
;   _Pragma("unroll") for (int ni = 0; ni < NT_; ++ni)
; DI void phase_resgemm(const Params& p, const u16* A, int lda, const u16* W, int ldw, int K, char* smem) {
;     ...
;     EPI_LOOP(4, 8) {
;       const int row = r0 + wm_ * 64 + mi * 16 + fr_, col = c0 + wn_ * 128 + ni * 16 + fq_ * 4;
;       const uint2 xb = *(const uint2*)(p.XB() + (size_t)row * LDX + col);
;       float4 o;
;       o.x = DN_ALPHA * bflo(xb.x) + acc[mi][ni][0]; o.y = DN_ALPHA * bfhi(xb.x) + acc[mi][ni][1];
;       o.z = DN_ALPHA * bflo(xb.y) + acc[mi][ni][2]; o.w = DN_ALPHA * bfhi(xb.y) + acc[mi][ni][3];
;       *(float4*)(p.out + (size_t)row * 1024 + col) = o;
;     }
	v_lshlrev_b32_e32 v132, 16, v121
	v_lshlrev_b32_e32 v122, 16, v120
	v_and_b32_e32 v123, 0xffff0000, v120
	v_and_b32_e32 v133, 0xffff0000, v121
	v_pk_fma_f32 v[120:121], v[122:123], s[74:75], v[126:127] op_sel_hi:[1,0,1]
	v_pk_fma_f32 v[122:123], v[132:133], s[74:75], v[128:129] op_sel_hi:[1,0,1]
	global_store_dwordx4 v[130:131], v[120:123], off offset:192
	global_load_dwordx2 v[120:121], v[124:125], off offset:128
	s_waitcnt vmcnt(0)
	v_lshlrev_b32_e32 v122, 16, v120
	v_and_b32_e32 v123, 0xffff0000, v120
	v_lshlrev_b32_e32 v120, 16, v121
	v_and_b32_e32 v121, 0xffff0000, v121
	v_pk_fma_f32 v[110:111], v[122:123], s[74:75], v[110:111] op_sel_hi:[1,0,1]
	v_pk_fma_f32 v[112:113], v[120:121], s[74:75], v[112:113] op_sel_hi:[1,0,1]
	global_store_dwordx4 v[130:131], v[110:113], off offset:256
	global_load_dwordx2 v[110:111], v[124:125], off offset:160
	s_waitcnt vmcnt(0)
	v_lshlrev_b32_e32 v112, 16, v110
	v_and_b32_e32 v113, 0xffff0000, v110
	v_lshlrev_b32_e32 v110, 16, v111
	v_and_b32_e32 v111, 0xffff0000, v111
	v_pk_fma_f32 v[106:107], v[112:113], s[74:75], v[106:107] op_sel_hi:[1,0,1]
	v_pk_fma_f32 v[108:109], v[110:111], s[74:75], v[108:109] op_sel_hi:[1,0,1]
	global_store_dwordx4 v[130:131], v[106:109], off offset:320
	global_load_dwordx2 v[106:107], v[124:125], off offset:192
	s_waitcnt vmcnt(0)
	v_lshlrev_b32_e32 v108, 16, v106
	v_and_b32_e32 v109, 0xffff0000, v106
	v_lshlrev_b32_e32 v106, 16, v107
	v_and_b32_e32 v107, 0xffff0000, v107
	v_pk_fma_f32 v[102:103], v[108:109], s[74:75], v[102:103] op_sel_hi:[1,0,1]
	v_pk_fma_f32 v[104:105], v[106:107], s[74:75], v[104:105] op_sel_hi:[1,0,1]
	global_store_dwordx4 v[130:131], v[102:105], off offset:384
	global_load_dwordx2 v[102:103], v[124:125], off offset:224
	s_waitcnt vmcnt(0)
	v_lshlrev_b32_e32 v108, 16, v102
	v_or_b32_e32 v104, 16, v114
	v_and_b32_e32 v109, 0xffff0000, v102
	v_lshlrev_b32_e32 v102, 16, v103
	v_and_b32_e32 v103, 0xffff0000, v103
	v_mad_i64_i32 v[106:107], s[0:1], v104, s59, v[118:119]
	v_pk_fma_f32 v[98:99], v[108:109], s[74:75], v[98:99] op_sel_hi:[1,0,1]
	v_pk_fma_f32 v[100:101], v[102:103], s[74:75], v[100:101] op_sel_hi:[1,0,1]
	v_lshl_add_u64 v[106:107], v[106:107], 0, v[0:1]
	global_store_dwordx4 v[130:131], v[98:101], off offset:448
	global_load_dwordx2 v[98:99], v[106:107], off
	v_ashrrev_i32_e32 v105, 31, v104
	v_lshlrev_b64 v[100:101], 12, v[104:105]
	v_lshl_add_u64 v[100:101], s[86:87], 0, v[100:101]
	v_lshl_add_u64 v[100:101], v[100:101], 0, v[116:117]
	s_waitcnt vmcnt(0)
	v_lshlrev_b32_e32 v102, 16, v98
	v_and_b32_e32 v103, 0xffff0000, v98
	v_lshlrev_b32_e32 v98, 16, v99
	v_and_b32_e32 v99, 0xffff0000, v99
	v_pk_fma_f32 v[94:95], v[102:103], s[74:75], v[94:95] op_sel_hi:[1,0,1]
	v_pk_fma_f32 v[96:97], v[98:99], s[74:75], v[96:97] op_sel_hi:[1,0,1]
	global_store_dwordx4 v[100:101], v[94:97], off
	global_load_dwordx2 v[94:95], v[106:107], off offset:32
	s_waitcnt vmcnt(0)
	v_lshlrev_b32_e32 v96, 16, v94
	v_and_b32_e32 v97, 0xffff0000, v94
	v_lshlrev_b32_e32 v94, 16, v95
	v_and_b32_e32 v95, 0xffff0000, v95
	v_pk_fma_f32 v[90:91], v[96:97], s[74:75], v[90:91] op_sel_hi:[1,0,1]
	v_pk_fma_f32 v[92:93], v[94:95], s[74:75], v[92:93] op_sel_hi:[1,0,1]
	global_store_dwordx4 v[100:101], v[90:93], off offset:64
	global_load_dwordx2 v[90:91], v[106:107], off offset:64
	s_waitcnt vmcnt(0)
	v_lshlrev_b32_e32 v92, 16, v90
	v_and_b32_e32 v93, 0xffff0000, v90
	v_lshlrev_b32_e32 v90, 16, v91
	v_and_b32_e32 v91, 0xffff0000, v91
	v_pk_fma_f32 v[86:87], v[92:93], s[74:75], v[86:87] op_sel_hi:[1,0,1]
	v_pk_fma_f32 v[88:89], v[90:91], s[74:75], v[88:89] op_sel_hi:[1,0,1]
	global_store_dwordx4 v[100:101], v[86:89], off offset:128
	global_load_dwordx2 v[86:87], v[106:107], off offset:96
	s_waitcnt vmcnt(0)
	v_lshlrev_b32_e32 v88, 16, v86
	v_and_b32_e32 v89, 0xffff0000, v86
	v_lshlrev_b32_e32 v86, 16, v87
	v_and_b32_e32 v87, 0xffff0000, v87
	v_pk_fma_f32 v[82:83], v[88:89], s[74:75], v[82:83] op_sel_hi:[1,0,1]
	v_pk_fma_f32 v[84:85], v[86:87], s[74:75], v[84:85] op_sel_hi:[1,0,1]
	global_store_dwordx4 v[100:101], v[82:85], off offset:192
	global_load_dwordx2 v[82:83], v[106:107], off offset:128
	s_waitcnt vmcnt(0)
	v_lshlrev_b32_e32 v84, 16, v82
	v_and_b32_e32 v85, 0xffff0000, v82
	v_lshlrev_b32_e32 v82, 16, v83
	v_and_b32_e32 v83, 0xffff0000, v83
	v_pk_fma_f32 v[78:79], v[84:85], s[74:75], v[78:79] op_sel_hi:[1,0,1]
	v_pk_fma_f32 v[80:81], v[82:83], s[74:75], v[80:81] op_sel_hi:[1,0,1]
	global_store_dwordx4 v[100:101], v[78:81], off offset:256
	global_load_dwordx2 v[78:79], v[106:107], off offset:160
	s_waitcnt vmcnt(0)
	v_lshlrev_b32_e32 v80, 16, v78
	v_and_b32_e32 v81, 0xffff0000, v78
	v_lshlrev_b32_e32 v78, 16, v79
	v_and_b32_e32 v79, 0xffff0000, v79
	v_pk_fma_f32 v[74:75], v[80:81], s[74:75], v[74:75] op_sel_hi:[1,0,1]
	v_pk_fma_f32 v[76:77], v[78:79], s[74:75], v[76:77] op_sel_hi:[1,0,1]
	global_store_dwordx4 v[100:101], v[74:77], off offset:320
	global_load_dwordx2 v[74:75], v[106:107], off offset:192
	s_waitcnt vmcnt(0)
	v_lshlrev_b32_e32 v76, 16, v74
	v_and_b32_e32 v77, 0xffff0000, v74
	v_lshlrev_b32_e32 v74, 16, v75
	v_and_b32_e32 v75, 0xffff0000, v75
	v_pk_fma_f32 v[70:71], v[76:77], s[74:75], v[70:71] op_sel_hi:[1,0,1]
	v_pk_fma_f32 v[72:73], v[74:75], s[74:75], v[72:73] op_sel_hi:[1,0,1]
	global_store_dwordx4 v[100:101], v[70:73], off offset:384
	global_load_dwordx2 v[70:71], v[106:107], off offset:224
	s_waitcnt vmcnt(0)
;   __device__ __forceinline__ u16* XB() const { return (u16*)(ws + O_XB); }
; DI float bflo(u32 v) { return __uint_as_float(v << 16); }
; DI float bfhi(u32 v) { return __uint_as_float(v & 0xffff0000u); }
; #define EPI_LOOP(MT_, NT_)                                                \
;   const int l_ = ltid() & 63, w_ = ltid() >> 6;                           \
;   const int wm_ = w_ >> 1, wn_ = w_ & 1, fr_ = l_ & 15, fq_ = l_ >> 4;    \
;   _Pragma("unroll") for (int mi = 0; mi < MT_; ++mi)                      \
;   _Pragma("unroll") for (int ni = 0; ni < NT_; ++ni)
; DI void phase_resgemm(const Params& p, const u16* A, int lda, const u16* W, int ldw, int K, char* smem) {
;     ...
;     EPI_LOOP(4, 8) {
;       const int row = r0 + wm_ * 64 + mi * 16 + fr_, col = c0 + wn_ * 128 + ni * 16 + fq_ * 4;
;       const uint2 xb = *(const uint2*)(p.XB() + (size_t)row * LDX + col);
;       float4 o;
;       o.x = DN_ALPHA * bflo(xb.x) + acc[mi][ni][0]; o.y = DN_ALPHA * bfhi(xb.x) + acc[mi][ni][1];
;       o.z = DN_ALPHA * bflo(xb.y) + acc[mi][ni][2]; o.w = DN_ALPHA * bfhi(xb.y) + acc[mi][ni][3];
;       *(float4*)(p.out + (size_t)row * 1024 + col) = o;
;     }
	v_lshlrev_b32_e32 v76, 16, v70
	v_or_b32_e32 v72, 32, v114
	v_and_b32_e32 v77, 0xffff0000, v70
	v_lshlrev_b32_e32 v70, 16, v71
	v_and_b32_e32 v71, 0xffff0000, v71
	v_mad_i64_i32 v[74:75], s[0:1], v72, s59, v[118:119]
	v_pk_fma_f32 v[66:67], v[76:77], s[74:75], v[66:67] op_sel_hi:[1,0,1]
	v_pk_fma_f32 v[68:69], v[70:71], s[74:75], v[68:69] op_sel_hi:[1,0,1]
	v_lshl_add_u64 v[74:75], v[74:75], 0, v[0:1]
	global_store_dwordx4 v[100:101], v[66:69], off offset:448
	global_load_dwordx2 v[66:67], v[74:75], off
	v_ashrrev_i32_e32 v73, 31, v72
	v_lshlrev_b64 v[68:69], 12, v[72:73]
	v_lshl_add_u64 v[68:69], s[86:87], 0, v[68:69]
	v_lshl_add_u64 v[68:69], v[68:69], 0, v[116:117]
	s_waitcnt vmcnt(0)
	v_lshlrev_b32_e32 v70, 16, v66
	v_and_b32_e32 v71, 0xffff0000, v66
	v_lshlrev_b32_e32 v66, 16, v67
	v_and_b32_e32 v67, 0xffff0000, v67
	v_pk_fma_f32 v[62:63], v[70:71], s[74:75], v[62:63] op_sel_hi:[1,0,1]
	v_pk_fma_f32 v[64:65], v[66:67], s[74:75], v[64:65] op_sel_hi:[1,0,1]
	global_store_dwordx4 v[68:69], v[62:65], off
	global_load_dwordx2 v[62:63], v[74:75], off offset:32
	s_waitcnt vmcnt(0)
	v_lshlrev_b32_e32 v64, 16, v62
	v_and_b32_e32 v65, 0xffff0000, v62
	v_lshlrev_b32_e32 v62, 16, v63
	v_and_b32_e32 v63, 0xffff0000, v63
	v_pk_fma_f32 v[58:59], v[64:65], s[74:75], v[58:59] op_sel_hi:[1,0,1]
	v_pk_fma_f32 v[60:61], v[62:63], s[74:75], v[60:61] op_sel_hi:[1,0,1]
	global_store_dwordx4 v[68:69], v[58:61], off offset:64
	global_load_dwordx2 v[58:59], v[74:75], off offset:64
	s_waitcnt vmcnt(0)
	v_lshlrev_b32_e32 v60, 16, v58
	v_and_b32_e32 v61, 0xffff0000, v58
	v_lshlrev_b32_e32 v58, 16, v59
	v_and_b32_e32 v59, 0xffff0000, v59
	v_pk_fma_f32 v[54:55], v[60:61], s[74:75], v[54:55] op_sel_hi:[1,0,1]
	v_pk_fma_f32 v[56:57], v[58:59], s[74:75], v[56:57] op_sel_hi:[1,0,1]
	global_store_dwordx4 v[68:69], v[54:57], off offset:128
	global_load_dwordx2 v[54:55], v[74:75], off offset:96
	s_waitcnt vmcnt(0)
	v_lshlrev_b32_e32 v56, 16, v54
	v_and_b32_e32 v57, 0xffff0000, v54
	v_lshlrev_b32_e32 v54, 16, v55
	v_and_b32_e32 v55, 0xffff0000, v55
	v_pk_fma_f32 v[50:51], v[56:57], s[74:75], v[50:51] op_sel_hi:[1,0,1]
	v_pk_fma_f32 v[52:53], v[54:55], s[74:75], v[52:53] op_sel_hi:[1,0,1]
	global_store_dwordx4 v[68:69], v[50:53], off offset:192
	global_load_dwordx2 v[50:51], v[74:75], off offset:128
	s_waitcnt vmcnt(0)
	v_lshlrev_b32_e32 v52, 16, v50
	v_and_b32_e32 v53, 0xffff0000, v50
	v_lshlrev_b32_e32 v50, 16, v51
	v_and_b32_e32 v51, 0xffff0000, v51
	v_pk_fma_f32 v[46:47], v[52:53], s[74:75], v[46:47] op_sel_hi:[1,0,1]
	v_pk_fma_f32 v[48:49], v[50:51], s[74:75], v[48:49] op_sel_hi:[1,0,1]
	global_store_dwordx4 v[68:69], v[46:49], off offset:256
	global_load_dwordx2 v[46:47], v[74:75], off offset:160
	s_waitcnt vmcnt(0)
	v_lshlrev_b32_e32 v48, 16, v46
	v_and_b32_e32 v49, 0xffff0000, v46
	v_lshlrev_b32_e32 v46, 16, v47
	v_and_b32_e32 v47, 0xffff0000, v47
	v_pk_fma_f32 v[42:43], v[48:49], s[74:75], v[42:43] op_sel_hi:[1,0,1]
	v_pk_fma_f32 v[44:45], v[46:47], s[74:75], v[44:45] op_sel_hi:[1,0,1]
	global_store_dwordx4 v[68:69], v[42:45], off offset:320
	global_load_dwordx2 v[42:43], v[74:75], off offset:192
	s_waitcnt vmcnt(0)
	v_lshlrev_b32_e32 v44, 16, v42
	v_and_b32_e32 v45, 0xffff0000, v42
	v_lshlrev_b32_e32 v42, 16, v43
	v_and_b32_e32 v43, 0xffff0000, v43
	v_pk_fma_f32 v[38:39], v[44:45], s[74:75], v[38:39] op_sel_hi:[1,0,1]
	v_pk_fma_f32 v[40:41], v[42:43], s[74:75], v[40:41] op_sel_hi:[1,0,1]
	global_store_dwordx4 v[68:69], v[38:41], off offset:384
	global_load_dwordx2 v[38:39], v[74:75], off offset:224
	s_waitcnt vmcnt(0)
;   __device__ __forceinline__ u16* XB() const { return (u16*)(ws + O_XB); }
; DI float bflo(u32 v) { return __uint_as_float(v << 16); }
; DI float bfhi(u32 v) { return __uint_as_float(v & 0xffff0000u); }
; #define EPI_LOOP(MT_, NT_)                                                \
;   const int l_ = ltid() & 63, w_ = ltid() >> 6;                           \
;   const int wm_ = w_ >> 1, wn_ = w_ & 1, fr_ = l_ & 15, fq_ = l_ >> 4;    \
;   _Pragma("unroll") for (int mi = 0; mi < MT_; ++mi)                      \
;   _Pragma("unroll") for (int ni = 0; ni < NT_; ++ni)
; DI void phase_resgemm(const Params& p, const u16* A, int lda, const u16* W, int ldw, int K, char* smem) {
;     ...
;     EPI_LOOP(4, 8) {
;       const int row = r0 + wm_ * 64 + mi * 16 + fr_, col = c0 + wn_ * 128 + ni * 16 + fq_ * 4;
;       const uint2 xb = *(const uint2*)(p.XB() + (size_t)row * LDX + col);
;       float4 o;
;       o.x = DN_ALPHA * bflo(xb.x) + acc[mi][ni][0]; o.y = DN_ALPHA * bfhi(xb.x) + acc[mi][ni][1];
;       o.z = DN_ALPHA * bflo(xb.y) + acc[mi][ni][2]; o.w = DN_ALPHA * bfhi(xb.y) + acc[mi][ni][3];
;       *(float4*)(p.out + (size_t)row * 1024 + col) = o;
;     }
	v_lshlrev_b32_e32 v44, 16, v38
	v_or_b32_e32 v40, 48, v114
	v_and_b32_e32 v45, 0xffff0000, v38
	v_lshlrev_b32_e32 v38, 16, v39
	v_and_b32_e32 v39, 0xffff0000, v39
	v_mad_i64_i32 v[42:43], s[0:1], v40, s59, v[118:119]
	v_pk_fma_f32 v[34:35], v[44:45], s[74:75], v[34:35] op_sel_hi:[1,0,1]
	v_pk_fma_f32 v[36:37], v[38:39], s[74:75], v[36:37] op_sel_hi:[1,0,1]
	v_lshl_add_u64 v[42:43], v[42:43], 0, v[0:1]
	global_store_dwordx4 v[68:69], v[34:37], off offset:448
	global_load_dwordx2 v[34:35], v[42:43], off
	v_ashrrev_i32_e32 v41, 31, v40
	v_lshlrev_b64 v[36:37], 12, v[40:41]
	v_lshl_add_u64 v[36:37], s[86:87], 0, v[36:37]
	v_lshl_add_u64 v[36:37], v[36:37], 0, v[116:117]
	s_mov_b64 s[0:1], 0
	s_waitcnt vmcnt(0)
	v_lshlrev_b32_e32 v38, 16, v34
	v_and_b32_e32 v39, 0xffff0000, v34
	v_lshlrev_b32_e32 v34, 16, v35
	v_and_b32_e32 v35, 0xffff0000, v35
	v_pk_fma_f32 v[30:31], v[38:39], s[74:75], v[30:31] op_sel_hi:[1,0,1]
	v_pk_fma_f32 v[32:33], v[34:35], s[74:75], v[32:33] op_sel_hi:[1,0,1]
	global_store_dwordx4 v[36:37], v[30:33], off
	global_load_dwordx2 v[30:31], v[42:43], off offset:32
	s_waitcnt vmcnt(0)
	v_lshlrev_b32_e32 v32, 16, v30
	v_and_b32_e32 v33, 0xffff0000, v30
	v_lshlrev_b32_e32 v30, 16, v31
	v_and_b32_e32 v31, 0xffff0000, v31
	v_pk_fma_f32 v[26:27], v[32:33], s[74:75], v[26:27] op_sel_hi:[1,0,1]
	v_pk_fma_f32 v[28:29], v[30:31], s[74:75], v[28:29] op_sel_hi:[1,0,1]
	global_store_dwordx4 v[36:37], v[26:29], off offset:64
	global_load_dwordx2 v[26:27], v[42:43], off offset:64
	s_waitcnt vmcnt(0)
	v_lshlrev_b32_e32 v28, 16, v26
	v_and_b32_e32 v29, 0xffff0000, v26
	v_lshlrev_b32_e32 v26, 16, v27
	v_and_b32_e32 v27, 0xffff0000, v27
	v_pk_fma_f32 v[22:23], v[28:29], s[74:75], v[22:23] op_sel_hi:[1,0,1]
	v_pk_fma_f32 v[24:25], v[26:27], s[74:75], v[24:25] op_sel_hi:[1,0,1]
	global_store_dwordx4 v[36:37], v[22:25], off offset:128
	global_load_dwordx2 v[22:23], v[42:43], off offset:96
	s_waitcnt vmcnt(0)
	v_lshlrev_b32_e32 v24, 16, v22
	v_and_b32_e32 v25, 0xffff0000, v22
	v_lshlrev_b32_e32 v22, 16, v23
	v_and_b32_e32 v23, 0xffff0000, v23
	v_pk_fma_f32 v[18:19], v[24:25], s[74:75], v[18:19] op_sel_hi:[1,0,1]
	v_pk_fma_f32 v[20:21], v[22:23], s[74:75], v[20:21] op_sel_hi:[1,0,1]
	global_store_dwordx4 v[36:37], v[18:21], off offset:192
	global_load_dwordx2 v[18:19], v[42:43], off offset:128
	s_waitcnt vmcnt(0)
	v_lshlrev_b32_e32 v20, 16, v18
	v_and_b32_e32 v21, 0xffff0000, v18
	v_lshlrev_b32_e32 v18, 16, v19
	v_and_b32_e32 v19, 0xffff0000, v19
	v_pk_fma_f32 v[14:15], v[20:21], s[74:75], v[14:15] op_sel_hi:[1,0,1]
	v_pk_fma_f32 v[16:17], v[18:19], s[74:75], v[16:17] op_sel_hi:[1,0,1]
	global_store_dwordx4 v[36:37], v[14:17], off offset:256
	global_load_dwordx2 v[14:15], v[42:43], off offset:160
	s_waitcnt vmcnt(0)
	v_lshlrev_b32_e32 v16, 16, v14
	v_and_b32_e32 v17, 0xffff0000, v14
	v_lshlrev_b32_e32 v14, 16, v15
	v_and_b32_e32 v15, 0xffff0000, v15
	v_pk_fma_f32 v[10:11], v[16:17], s[74:75], v[10:11] op_sel_hi:[1,0,1]
	v_pk_fma_f32 v[12:13], v[14:15], s[74:75], v[12:13] op_sel_hi:[1,0,1]
	global_store_dwordx4 v[36:37], v[10:13], off offset:320
	global_load_dwordx2 v[10:11], v[42:43], off offset:192
	s_waitcnt vmcnt(0)
	v_lshlrev_b32_e32 v12, 16, v10
	v_and_b32_e32 v13, 0xffff0000, v10
	v_lshlrev_b32_e32 v10, 16, v11
	v_and_b32_e32 v11, 0xffff0000, v11
	v_pk_fma_f32 v[6:7], v[12:13], s[74:75], v[6:7] op_sel_hi:[1,0,1]
	v_pk_fma_f32 v[8:9], v[10:11], s[74:75], v[8:9] op_sel_hi:[1,0,1]
	global_store_dwordx4 v[36:37], v[6:9], off offset:384
	global_load_dwordx2 v[6:7], v[42:43], off offset:224
	s_waitcnt vmcnt(0)
	v_lshlrev_b32_e32 v8, 16, v6
	v_and_b32_e32 v9, 0xffff0000, v6
	v_lshlrev_b32_e32 v6, 16, v7
	v_and_b32_e32 v7, 0xffff0000, v7
	v_pk_fma_f32 v[2:3], v[8:9], s[74:75], v[2:3] op_sel_hi:[1,0,1]
	v_pk_fma_f32 v[4:5], v[6:7], s[74:75], v[4:5] op_sel_hi:[1,0,1]
	global_store_dwordx4 v[36:37], v[2:5], off offset:448
	s_branch .LBB0_794
